# software-pipelined gemm<4,8> K-loops (LDS fragment prefetch, one barrier per K tile) + diff-attention kt-loop: K/V fragments prefetched, exp/pack in place
# speedup vs baseline: 1.0139x; 1.0139x over previous
; DI int lbid() { int b = blockIdx.x; asm volatile("" : "+s"(b)); return b; }
; DI int lgdim() { int b = gridDim.x; asm volatile("" : "+s"(b)); return b; }
; DI int ltid() { int t = threadIdx.x; asm volatile("" : "+v"(t)); return t; }
; #define GLOAD(kt) { GL1(0, kt) GL1(1, kt) GL1(2, kt) GL1(3, kt) }
; #define SSTORE(buf)                              \
;   {                                              \
;     char* as_ = smem + (buf) * BUF;              \
;     char* bs_ = as_ + ASZ;                       \
;     SS1(0) SS1(1) SS1(2) SS1(3)                  \
;   }
; template <int MT, int NT>
; DI void gemm_core(const u16* __restrict__ A, int lda, const u16* __restrict__ B, int ldb, int K,
;                   f32x4 (&acc)[MT][NT], char* smem) {
;   constexpr int BM = 64 * MT, BN = 32 * NT;
;   constexpr int ASZ = BM * 128, BSZ = BN * 128, BUF = ASZ + BSZ;
;   constexpr int NA = BM / 64, NB = BN / 64;
;   const int tid = ltid(), l = tid & 63, w = tid >> 6, wm = w >> 1, wn = w & 1;
;   const int fr = l & 15, fq = l >> 4;
;   uint4 ra0, ra1, ra2, ra3, rb0, rb1, rb2, rb3;
;   const int nk = K >> 6;
;   const int srow = tid >> 3, sch = tid & 7;
;   const int ssw = sch ^ ((srow >> 1) & 7);
;   const int fsw = (fr >> 1) & 7;
;     ...
;   GLOAD(0);
;   SSTORE(0);
;   GLOAD(((1 < nk) ? 1 : 0));
; DI bool next_tile(int it, int RT, int CT, int PR, int PCc, int& rt, int& ct) {
;   const int bid = lbid(), x = bid & 7, j = bid >> 3, J = lgdim() >> 3;
;   const int u = j + it * J;
;   const int pcols = CT / PCc, npatch = (RT / PR) * pcols;
;   const int pid = (u >> 6) * 8 + x;
;   if (pid >= npatch) return false;
;   const int w = u & 63, pr = pid / pcols, pc = pid - pr * pcols;
;   rt = pr * PR + w / PCc;
;   ct = pc * PCc + w % PCc;
;   return true;
; }
.LBB0_129:
	s_mov_b32 s0, s56
	s_load_dword s1, s[36:37], 0x0
	s_waitcnt lgkmcnt(0)
	s_ashr_i32 s1, s1, 3
	s_and_b32 s3, s0, 7
	s_ashr_i32 s0, s0, 3
	s_mul_i32 s2, s1, s18
	s_add_i32 s2, s2, s0
	s_ashr_i32 s0, s2, 3
	s_and_b32 s0, s0, -8
	s_or_b32 s3, s0, s3
	s_cmp_gt_i32 s3, 31
	s_mov_b64 s[0:1], -1
	s_cbranch_scc1 .LBB0_128
	s_lshr_b32 s0, s3, 31
	s_add_i32 s0, s3, s0
	s_ashr_i32 s0, s0, 1
	s_lshl_b32 s1, s0, 4
	s_lshl_b32 s3, s3, 3
	s_sub_i32 s1, s3, s1
	s_and_b32 s3, s2, 7
	s_lshl_b32 s2, s2, 5
	s_lshl_b32 s0, s0, 11
	s_and_b32 s2, s2, 0x700
	s_or_b32 s1, s1, s3
	s_or_b32 s0, s0, s2
	s_lshl_b32 s19, s1, 8
	s_mul_i32 s2, s0, 0x880
	s_mul_hi_i32 s3, s0, 0x880
	s_add_u32 s2, s60, s2
	s_addc_u32 s3, s61, s3
	s_mul_i32 s1, s1, 0x88000
	s_mul_hi_i32 s5, s19, 0x880
	s_add_u32 s4, s52, s1
	v_mov_b32_e32 v34, v171
	s_addc_u32 s5, s33, s5
	v_mov_b64_e32 v[26:27], s[2:3]
	v_ashrrev_i32_e32 v35, 3, v34
	v_lshlrev_b32_e32 v36, 4, v34
	v_mov_b64_e32 v[30:31], s[4:5]
	v_add_u32_e32 v37, 64, v35
	v_add_u32_e32 v38, 0x80, v35
	v_add_u32_e32 v39, 0xc0, v35
	v_mad_i64_i32 v[2:3], s[2:3], v35, s59, v[26:27]
	v_and_b32_e32 v0, 0x70, v36
	v_mad_i64_i32 v[6:7], s[2:3], v35, s59, v[30:31]
	v_mad_i64_i32 v[10:11], s[2:3], v37, s59, v[26:27]
	v_mad_i64_i32 v[14:15], s[2:3], v37, s59, v[30:31]
	v_mad_i64_i32 v[18:19], s[2:3], v38, s59, v[26:27]
	v_mad_i64_i32 v[22:23], s[2:3], v38, s59, v[30:31]
	v_mad_i64_i32 v[26:27], s[2:3], v39, s59, v[26:27]
	v_mad_i64_i32 v[30:31], s[2:3], v39, s59, v[30:31]
	s_waitcnt vmcnt(16)
	v_lshl_add_u64 v[162:163], v[2:3], 0, v[0:1]
	v_lshl_add_u64 v[164:165], v[6:7], 0, v[0:1]
	v_lshl_add_u64 v[166:167], v[10:11], 0, v[0:1]
	v_lshl_add_u64 v[168:169], v[14:15], 0, v[0:1]
	v_lshl_add_u64 v[176:177], v[18:19], 0, v[0:1]
	v_lshl_add_u64 v[178:179], v[22:23], 0, v[0:1]
	v_lshl_add_u64 v[180:181], v[26:27], 0, v[0:1]
	s_waitcnt vmcnt(0)
	v_lshl_add_u64 v[182:183], v[30:31], 0, v[0:1]
	global_load_dwordx4 v[2:5], v[162:163], off
	global_load_dwordx4 v[6:9], v[164:165], off
	global_load_dwordx4 v[10:13], v[166:167], off
	global_load_dwordx4 v[14:17], v[168:169], off
	global_load_dwordx4 v[18:21], v[176:177], off
	global_load_dwordx4 v[22:25], v[178:179], off
	global_load_dwordx4 v[26:29], v[180:181], off
	global_load_dwordx4 v[30:33], v[182:183], off
	global_load_dwordx4 v[134:137], v[180:181], off offset:128
	global_load_dwordx4 v[126:129], v[176:177], off offset:128
	global_load_dwordx4 v[114:117], v[166:167], off offset:128
	global_load_dwordx4 v[110:113], v[162:163], off offset:128
	global_load_dwordx4 v[150:153], v[182:183], off offset:128
	global_load_dwordx4 v[138:141], v[178:179], off offset:128
	global_load_dwordx4 v[130:133], v[168:169], off offset:128
	global_load_dwordx4 v[118:121], v[164:165], off offset:128
	v_lshlrev_b32_e32 v0, 7, v35
	v_bitop3_b32 v173, v36, s75, v34 bitop3:0x48
	v_and_b32_e32 v44, 15, v34
	v_lshlrev_b32_e32 v45, 1, v34
	v_or_b32_e32 v35, v0, v173
	v_lshlrev_b32_e32 v175, 7, v37
	v_lshlrev_b32_e32 v184, 7, v38
	v_lshlrev_b32_e32 v185, 7, v39
	v_bfe_u32 v41, v34, 4, 2
	v_bfe_u32 v43, v34, 1, 3
	v_or_b32_e32 v36, v175, v173
	v_or_b32_e32 v37, v184, v173
	v_or_b32_e32 v38, v185, v173
	v_lshrrev_b32_e32 v40, 4, v34
	v_lshrrev_b32_e32 v42, 1, v34
	v_and_or_b32 v34, v42, s90, v44
	v_lshlrev_b32_e32 v187, 7, v34
	s_mov_b32 s1, 0
	s_mov_b32 s2, 0
	s_waitcnt vmcnt(15)
	ds_write_b128 v35, v[2:5]
	s_waitcnt vmcnt(13)
	ds_write_b128 v36, v[10:13]
	s_waitcnt vmcnt(11)
	ds_write_b128 v37, v[18:21]
	s_waitcnt vmcnt(9)
	ds_write_b128 v38, v[26:29]
	ds_write_b128 v35, v[6:9] offset:32768
	ds_write_b128 v36, v[14:17] offset:32768
	ds_write_b128 v37, v[22:25] offset:32768
	s_waitcnt vmcnt(8)
	ds_write_b128 v38, v[30:33] offset:32768
	v_and_or_b32 v2, v45, s57, v44
	v_lshlrev_b32_e32 v188, 7, v2
	v_bitop3_b32 v2, v41, v43, 4 bitop3:0x36
	v_bitop3_b32 v3, v40, v43, 3 bitop3:0x6c
	v_lshlrev_b32_e32 v189, 4, v2
	v_mov_b32_e32 v2, 0
	v_lshlrev_b32_e32 v186, 4, v3
	v_mov_b32_e32 v3, v2
	v_mov_b32_e32 v4, v2
	v_mov_b32_e32 v5, v2
	v_mov_b32_e32 v6, v2
	v_mov_b32_e32 v7, v2
	v_mov_b32_e32 v8, v2
	v_mov_b32_e32 v9, v2
	v_mov_b32_e32 v10, v2
	v_mov_b32_e32 v11, v2
	v_mov_b32_e32 v12, v2
	v_mov_b32_e32 v13, v2
	v_mov_b32_e32 v14, v2
	v_mov_b32_e32 v15, v2
	v_mov_b32_e32 v16, v2
	v_mov_b32_e32 v17, v2
	v_mov_b32_e32 v18, v2
	v_mov_b32_e32 v19, v2
	v_mov_b32_e32 v20, v2
	v_mov_b32_e32 v21, v2
	v_mov_b32_e32 v22, v2
	v_mov_b32_e32 v23, v2
	v_mov_b32_e32 v24, v2
	v_mov_b32_e32 v25, v2
	v_mov_b32_e32 v26, v2
	v_mov_b32_e32 v27, v2
	v_mov_b32_e32 v28, v2
	v_mov_b32_e32 v29, v2
	v_mov_b32_e32 v30, v2
	v_mov_b32_e32 v31, v2
	v_mov_b32_e32 v32, v2
	v_mov_b32_e32 v33, v2
	v_mov_b32_e32 v34, v2
	v_mov_b32_e32 v35, v2
	v_mov_b32_e32 v36, v2
	v_mov_b32_e32 v37, v2
	v_mov_b32_e32 v38, v2
	v_mov_b32_e32 v39, v2
	v_mov_b32_e32 v40, v2
	v_mov_b32_e32 v41, v2
	v_mov_b32_e32 v42, v2
	v_mov_b32_e32 v43, v2
	v_mov_b32_e32 v44, v2
	v_mov_b32_e32 v45, v2
	v_mov_b32_e32 v46, v2
	v_mov_b32_e32 v47, v2
	v_mov_b32_e32 v48, v2
	v_mov_b32_e32 v49, v2
	v_mov_b32_e32 v50, v2
	v_mov_b32_e32 v51, v2
	v_mov_b32_e32 v52, v2
	v_mov_b32_e32 v53, v2
	v_mov_b32_e32 v54, v2
	v_mov_b32_e32 v55, v2
	v_mov_b32_e32 v56, v2
	v_mov_b32_e32 v57, v2
	v_mov_b32_e32 v58, v2
	v_mov_b32_e32 v59, v2
	v_mov_b32_e32 v60, v2
	v_mov_b32_e32 v61, v2
	v_mov_b32_e32 v62, v2
	v_mov_b32_e32 v63, v2
	v_mov_b32_e32 v64, v2
	v_mov_b32_e32 v65, v2
	v_mov_b32_e32 v66, v2
	v_mov_b32_e32 v67, v2
	v_mov_b32_e32 v68, v2
	v_mov_b32_e32 v69, v2
	v_mov_b32_e32 v70, v2
	v_mov_b32_e32 v71, v2
	v_mov_b32_e32 v72, v2
	v_mov_b32_e32 v73, v2
	v_mov_b32_e32 v74, v2
	v_mov_b32_e32 v75, v2
	v_mov_b32_e32 v76, v2
	v_mov_b32_e32 v77, v2
	v_mov_b32_e32 v78, v2
	v_mov_b32_e32 v79, v2
	v_mov_b32_e32 v80, v2
	v_mov_b32_e32 v81, v2
	v_mov_b32_e32 v82, v2
	v_mov_b32_e32 v83, v2
	v_mov_b32_e32 v84, v2
	v_mov_b32_e32 v85, v2
	v_mov_b32_e32 v86, v2
	v_mov_b32_e32 v87, v2
	v_mov_b32_e32 v88, v2
	v_mov_b32_e32 v89, v2
	v_mov_b32_e32 v90, v2
	v_mov_b32_e32 v91, v2
	v_mov_b32_e32 v92, v2
	v_mov_b32_e32 v93, v2
	v_mov_b32_e32 v94, v2
	v_mov_b32_e32 v95, v2
	v_mov_b32_e32 v96, v2
	v_mov_b32_e32 v97, v2
	v_mov_b32_e32 v98, v2
	v_mov_b32_e32 v99, v2
	v_mov_b32_e32 v100, v2
	v_mov_b32_e32 v101, v2
	v_mov_b32_e32 v102, v2
	v_mov_b32_e32 v103, v2
	v_mov_b32_e32 v104, v2
	v_mov_b32_e32 v105, v2
	v_mov_b32_e32 v106, v2
	v_mov_b32_e32 v107, v2
	v_mov_b32_e32 v108, v2
	v_mov_b32_e32 v109, v2
	v_mov_b32_e32 v122, v2
	v_mov_b32_e32 v123, v2
	v_mov_b32_e32 v124, v2
	v_mov_b32_e32 v125, v2
	v_mov_b32_e32 v142, v2
	v_mov_b32_e32 v143, v2
	v_mov_b32_e32 v144, v2
	v_mov_b32_e32 v145, v2
	v_mov_b32_e32 v146, v2
	v_mov_b32_e32 v147, v2
	v_mov_b32_e32 v148, v2
	v_mov_b32_e32 v149, v2
	v_mov_b32_e32 v154, v2
	v_mov_b32_e32 v155, v2
	v_mov_b32_e32 v156, v2
	v_mov_b32_e32 v157, v2
	v_mov_b32_e32 v158, v2
	v_mov_b32_e32 v159, v2
	v_mov_b32_e32 v160, v2
	v_mov_b32_e32 v161, v2
	s_waitcnt lgkmcnt(0)
	s_barrier
; DI f32x4 mfma16(bf16x8 a, bf16x8 b, f32x4 c) { return __builtin_amdgcn_mfma_f32_16x16x32_bf16(a, b, c, 0, 0, 0); }
; #define GLOAD(kt) { GL1(0, kt) GL1(1, kt) GL1(2, kt) GL1(3, kt) }
; #define SSTORE(buf)                              \
;   {                                              \
;     char* as_ = smem + (buf) * BUF;              \
;     char* bs_ = as_ + ASZ;                       \
;     SS1(0) SS1(1) SS1(2) SS1(3)                  \
;   }
; template <int MT, int NT>
; DI void gemm_core(const u16* __restrict__ A, int lda, const u16* __restrict__ B, int ldb, int K,
;                   f32x4 (&acc)[MT][NT], char* smem) {
;     ...
;   for (int kt = 0; kt < nk; ++kt) {
;     __syncthreads();
;     SSTORE((kt + 1) & 1);
;     { const int kn_ = (kt + 2 < nk) ? kt + 2 : nk - 1; GLOAD(kn_); }
;     const char* as = smem + (kt & 1) * BUF;
;     const char* bs = as + ASZ;
; #pragma unroll
;     for (int kk = 0; kk < 2; ++kk) {
;       bf16x8 xf[MT], wf[NT];
; #pragma unroll
;       for (int mi = 0; mi < MT; ++mi)
;         xf[mi] = *(const bf16x8*)(as + (wm * (MT * 16) + mi * 16 + fr) * 128 + (((kk * 4 + fq) ^ fsw) * 16));
; #pragma unroll
;       for (int ni = 0; ni < NT; ++ni)
;         wf[ni] = *(const bf16x8*)(bs + (wn * (NT * 16) + ni * 16 + fr) * 128 + (((kk * 4 + fq) ^ fsw) * 16));
;       __builtin_amdgcn_s_setprio(1);
; #pragma unroll
;       for (int mi = 0; mi < MT; ++mi)
; #pragma unroll
;         for (int ni = 0; ni < NT; ++ni) acc[mi][ni] = mfma16(wf[ni], xf[mi], acc[mi][ni]);
;       __builtin_amdgcn_s_setprio(0);
;     }
;   }
	v_add_u32_e32 v207, v186, v188
	v_add_u32_e32 v206, v186, v187
	ds_read_b128 v[190:193], v206
	ds_read_b128 v[208:211], v206 offset:2048
	ds_read_b128 v[212:215], v206 offset:4096
	ds_read_b128 v[216:219], v206 offset:6144
	ds_read_b128 v[220:223], v207 offset:32768
	ds_read_b128 v[224:227], v207 offset:34816
	ds_read_b128 v[228:231], v207 offset:36864
	ds_read_b128 v[232:235], v207 offset:38912
	ds_read_b128 v[236:239], v207 offset:40960
	ds_read_b128 v[240:243], v207 offset:43008
	ds_read_b128 v[244:247], v207 offset:45056
	ds_read_b128 v[248:251], v207 offset:47104
	s_waitcnt lgkmcnt(0)
.LBB0_131:
	s_add_i32 s4, s1, 0x10000
	s_and_b32 s5, s4, 0x10000
	s_add_i32 s3, s2, 1
	s_min_u32 s2, s2, 13
	s_lshl_b32 s54, s2, 7
	s_and_b32 s1, s1, 0x10000
	v_or_b32_e32 v206, s1, v189
	v_add_u32_e32 v207, v206, v188
	v_add_u32_e32 v206, v206, v187
	v_add3_u32 v170, s5, v0, v173
	s_waitcnt lgkmcnt(10)
	v_mfma_f32_16x16x32_bf16 v[158:161], v[220:223], v[190:193], v[158:161]
	s_waitcnt vmcnt(0)
	ds_write_b128 v170, v[110:113]
	s_waitcnt lgkmcnt(10)
	v_mfma_f32_16x16x32_bf16 v[94:97], v[220:223], v[208:211], v[94:97]
	v_lshl_add_u64 v[110:111], v[162:163], 0, s[54:55]
	global_load_dwordx4 v[110:113], v[110:111], off offset:256
	s_waitcnt lgkmcnt(8)
	v_mfma_f32_16x16x32_bf16 v[62:65], v[220:223], v[212:215], v[62:65]
	ds_write_b128 v170, v[118:121] offset:32768
	s_waitcnt lgkmcnt(3)
	v_mfma_f32_16x16x32_bf16 v[30:33], v[220:223], v[216:219], v[30:33]
	v_lshl_add_u64 v[118:119], v[164:165], 0, s[54:55]
	global_load_dwordx4 v[118:121], v[118:119], off offset:256
	ds_read_b128 v[194:197], v206
	v_mfma_f32_16x16x32_bf16 v[154:157], v[224:227], v[190:193], v[154:157]
	ds_read_b128 v[220:223], v207 offset:32768
	ds_write_b128 v170, v[114:117] offset:8192
	v_mfma_f32_16x16x32_bf16 v[90:93], v[224:227], v[208:211], v[90:93]
	v_lshl_add_u64 v[114:115], v[166:167], 0, s[54:55]
	global_load_dwordx4 v[114:117], v[114:115], off offset:256
	v_mfma_f32_16x16x32_bf16 v[58:61], v[224:227], v[212:215], v[58:61]
	ds_write_b128 v170, v[130:133] offset:40960
	v_mfma_f32_16x16x32_bf16 v[26:29], v[224:227], v[216:219], v[26:29]
	v_lshl_add_u64 v[130:131], v[168:169], 0, s[54:55]
	global_load_dwordx4 v[130:133], v[130:131], off offset:256
	ds_read_b128 v[198:201], v206 offset:2048
	v_mfma_f32_16x16x32_bf16 v[146:149], v[228:231], v[190:193], v[146:149]
	ds_read_b128 v[224:227], v207 offset:34816
	ds_write_b128 v170, v[126:129] offset:16384
	v_mfma_f32_16x16x32_bf16 v[86:89], v[228:231], v[208:211], v[86:89]
	v_lshl_add_u64 v[126:127], v[176:177], 0, s[54:55]
	global_load_dwordx4 v[126:129], v[126:127], off offset:256
	v_mfma_f32_16x16x32_bf16 v[54:57], v[228:231], v[212:215], v[54:57]
	ds_write_b128 v170, v[138:141] offset:49152
	v_mfma_f32_16x16x32_bf16 v[22:25], v[228:231], v[216:219], v[22:25]
	v_lshl_add_u64 v[138:139], v[178:179], 0, s[54:55]
	global_load_dwordx4 v[138:141], v[138:139], off offset:256
	ds_read_b128 v[202:205], v206 offset:4096
	v_mfma_f32_16x16x32_bf16 v[142:145], v[232:235], v[190:193], v[142:145]
	ds_read_b128 v[228:231], v207 offset:36864
	ds_write_b128 v170, v[134:137] offset:24576
	v_mfma_f32_16x16x32_bf16 v[82:85], v[232:235], v[208:211], v[82:85]
	v_lshl_add_u64 v[134:135], v[180:181], 0, s[54:55]
	global_load_dwordx4 v[134:137], v[134:135], off offset:256
	v_mfma_f32_16x16x32_bf16 v[50:53], v[232:235], v[212:215], v[50:53]
	ds_write_b128 v170, v[150:153] offset:57344
	v_mfma_f32_16x16x32_bf16 v[18:21], v[232:235], v[216:219], v[18:21]
	v_lshl_add_u64 v[150:151], v[182:183], 0, s[54:55]
	global_load_dwordx4 v[150:153], v[150:151], off offset:256
	v_mfma_f32_16x16x32_bf16 v[122:125], v[236:239], v[190:193], v[122:125]
	ds_read_b128 v[232:235], v207 offset:38912
	v_mfma_f32_16x16x32_bf16 v[78:81], v[236:239], v[208:211], v[78:81]
	v_mfma_f32_16x16x32_bf16 v[46:49], v[236:239], v[212:215], v[46:49]
	v_mfma_f32_16x16x32_bf16 v[14:17], v[236:239], v[216:219], v[14:17]
	v_mfma_f32_16x16x32_bf16 v[106:109], v[240:243], v[190:193], v[106:109]
	ds_read_b128 v[236:239], v207 offset:40960
	v_mfma_f32_16x16x32_bf16 v[74:77], v[240:243], v[208:211], v[74:77]
	v_mfma_f32_16x16x32_bf16 v[42:45], v[240:243], v[212:215], v[42:45]
	v_mfma_f32_16x16x32_bf16 v[10:13], v[240:243], v[216:219], v[10:13]
	v_mfma_f32_16x16x32_bf16 v[102:105], v[244:247], v[190:193], v[102:105]
	ds_read_b128 v[240:243], v207 offset:43008
	v_mfma_f32_16x16x32_bf16 v[70:73], v[244:247], v[208:211], v[70:73]
	v_mfma_f32_16x16x32_bf16 v[38:41], v[244:247], v[212:215], v[38:41]
	v_mfma_f32_16x16x32_bf16 v[6:9], v[244:247], v[216:219], v[6:9]
	s_waitcnt lgkmcnt(15)
	v_mfma_f32_16x16x32_bf16 v[2:5], v[248:251], v[216:219], v[2:5]
	ds_read_b128 v[244:247], v207 offset:45056
	ds_read_b128 v[216:219], v206 offset:6144
	v_mfma_f32_16x16x32_bf16 v[98:101], v[248:251], v[190:193], v[98:101]
	v_mfma_f32_16x16x32_bf16 v[66:69], v[248:251], v[208:211], v[66:69]
	v_mfma_f32_16x16x32_bf16 v[34:37], v[248:251], v[212:215], v[34:37]
	ds_read_b128 v[248:251], v207 offset:47104
	s_waitcnt lgkmcnt(6)
	s_barrier
;   __device__ __forceinline__ u16* P() const { return (u16*)(ws + O_P); }
;   __device__ __forceinline__ u16* HALO() const { return (u16*)(ws + O_HALO); }
; DI f32x4 mfma16(bf16x8 a, bf16x8 b, f32x4 c) { return __builtin_amdgcn_mfma_f32_16x16x32_bf16(a, b, c, 0, 0, 0); }
; #define GLOAD(kt) { GL1(0, kt) GL1(1, kt) GL1(2, kt) GL1(3, kt) }
; #define SSTORE(buf)                              \
;   {                                              \
;     char* as_ = smem + (buf) * BUF;              \
;     char* bs_ = as_ + ASZ;                       \
;     SS1(0) SS1(1) SS1(2) SS1(3)                  \
;   }
; template <int MT, int NT>
; DI void gemm_core(const u16* __restrict__ A, int lda, const u16* __restrict__ B, int ldb, int K,
;                   f32x4 (&acc)[MT][NT], char* smem) {
;     ...
;   for (int kt = 0; kt < nk; ++kt) {
;     __syncthreads();
;     SSTORE((kt + 1) & 1);
;     { const int kn_ = (kt + 2 < nk) ? kt + 2 : nk - 1; GLOAD(kn_); }
;     const char* as = smem + (kt & 1) * BUF;
;     const char* bs = as + ASZ;
; #pragma unroll
;     for (int kk = 0; kk < 2; ++kk) {
;       bf16x8 xf[MT], wf[NT];
; #pragma unroll
;       for (int mi = 0; mi < MT; ++mi)
;         xf[mi] = *(const bf16x8*)(as + (wm * (MT * 16) + mi * 16 + fr) * 128 + (((kk * 4 + fq) ^ fsw) * 16));
; #pragma unroll
;       for (int ni = 0; ni < NT; ++ni)
;         wf[ni] = *(const bf16x8*)(bs + (wn * (NT * 16) + ni * 16 + fr) * 128 + (((kk * 4 + fq) ^ fsw) * 16));
;       __builtin_amdgcn_s_setprio(1);
; #pragma unroll
;       for (int mi = 0; mi < MT; ++mi)
; #pragma unroll
;         for (int ni = 0; ni < NT; ++ni) acc[mi][ni] = mfma16(wf[ni], xf[mi], acc[mi][ni]);
;       __builtin_amdgcn_s_setprio(0);
;     }
;   }
; DI void phase_inproj(const Params& p, int l, char* smem) {
;     ...
;     EPI_LOOP(4, 8) {
;       const int row = r0 + wm_ * 64 + mi * 16 + fr_, col = c0 + wn_ * 128 + ni * 16 + fq_ * 4;
;       if (col < PC) {
;         uint2 o;
;         o.x = pack2(acc[mi][ni][0], acc[mi][ni][1]); o.y = pack2(acc[mi][ni][2], acc[mi][ni][3]);
;         *(uint2*)(p.P() + (size_t)row * PC + col) = o;
;         if (col >= BQ && col < BZ && (row & 63) >= 61)
;           *(uint2*)(p.HALO() + ((size_t)(row >> 6) * 3 + ((row & 63) - 61)) * 1536 + (col - BQ)) = o;
;       }
	v_or_b32_e32 v206, s5, v186
	v_add_u32_e32 v207, v206, v188
	v_add_u32_e32 v206, v206, v187
	v_mfma_f32_16x16x32_bf16 v[158:161], v[220:223], v[194:197], v[158:161]
	v_mfma_f32_16x16x32_bf16 v[94:97], v[220:223], v[198:201], v[94:97]
	v_mfma_f32_16x16x32_bf16 v[62:65], v[220:223], v[202:205], v[62:65]
	s_waitcnt lgkmcnt(1)
	v_mfma_f32_16x16x32_bf16 v[30:33], v[220:223], v[216:219], v[30:33]
	ds_read_b128 v[190:193], v206
	v_mfma_f32_16x16x32_bf16 v[154:157], v[224:227], v[194:197], v[154:157]
	ds_read_b128 v[220:223], v207 offset:32768
	v_mfma_f32_16x16x32_bf16 v[90:93], v[224:227], v[198:201], v[90:93]
	v_mfma_f32_16x16x32_bf16 v[58:61], v[224:227], v[202:205], v[58:61]
	v_mfma_f32_16x16x32_bf16 v[26:29], v[224:227], v[216:219], v[26:29]
	ds_read_b128 v[208:211], v206 offset:2048
	v_mfma_f32_16x16x32_bf16 v[146:149], v[228:231], v[194:197], v[146:149]
	ds_read_b128 v[224:227], v207 offset:34816
	v_mfma_f32_16x16x32_bf16 v[86:89], v[228:231], v[198:201], v[86:89]
	v_mfma_f32_16x16x32_bf16 v[54:57], v[228:231], v[202:205], v[54:57]
	v_mfma_f32_16x16x32_bf16 v[22:25], v[228:231], v[216:219], v[22:25]
	ds_read_b128 v[212:215], v206 offset:4096
	v_mfma_f32_16x16x32_bf16 v[142:145], v[232:235], v[194:197], v[142:145]
	ds_read_b128 v[228:231], v207 offset:36864
	v_mfma_f32_16x16x32_bf16 v[82:85], v[232:235], v[198:201], v[82:85]
	v_mfma_f32_16x16x32_bf16 v[50:53], v[232:235], v[202:205], v[50:53]
	v_mfma_f32_16x16x32_bf16 v[18:21], v[232:235], v[216:219], v[18:21]
	v_mfma_f32_16x16x32_bf16 v[122:125], v[236:239], v[194:197], v[122:125]
	ds_read_b128 v[232:235], v207 offset:38912
	v_mfma_f32_16x16x32_bf16 v[78:81], v[236:239], v[198:201], v[78:81]
	v_mfma_f32_16x16x32_bf16 v[46:49], v[236:239], v[202:205], v[46:49]
	v_mfma_f32_16x16x32_bf16 v[14:17], v[236:239], v[216:219], v[14:17]
	v_mfma_f32_16x16x32_bf16 v[106:109], v[240:243], v[194:197], v[106:109]
	ds_read_b128 v[236:239], v207 offset:40960
	v_mfma_f32_16x16x32_bf16 v[74:77], v[240:243], v[198:201], v[74:77]
	v_mfma_f32_16x16x32_bf16 v[42:45], v[240:243], v[202:205], v[42:45]
	v_mfma_f32_16x16x32_bf16 v[10:13], v[240:243], v[216:219], v[10:13]
	v_mfma_f32_16x16x32_bf16 v[102:105], v[244:247], v[194:197], v[102:105]
	ds_read_b128 v[240:243], v207 offset:43008
	v_mfma_f32_16x16x32_bf16 v[70:73], v[244:247], v[198:201], v[70:73]
	v_mfma_f32_16x16x32_bf16 v[38:41], v[244:247], v[202:205], v[38:41]
	v_mfma_f32_16x16x32_bf16 v[6:9], v[244:247], v[216:219], v[6:9]
	s_waitcnt lgkmcnt(9)
	v_mfma_f32_16x16x32_bf16 v[2:5], v[248:251], v[216:219], v[2:5]
	ds_read_b128 v[244:247], v207 offset:45056
	ds_read_b128 v[216:219], v206 offset:6144
	v_mfma_f32_16x16x32_bf16 v[98:101], v[248:251], v[194:197], v[98:101]
	v_mfma_f32_16x16x32_bf16 v[66:69], v[248:251], v[198:201], v[66:69]
	v_mfma_f32_16x16x32_bf16 v[34:37], v[248:251], v[202:205], v[34:37]
	ds_read_b128 v[248:251], v207 offset:47104
	s_cmp_lg_u32 s3, 16
	s_mov_b32 s1, s4
	s_mov_b32 s2, s3
	s_cbranch_scc1 .LBB0_131
	s_waitcnt vmcnt(0) lgkmcnt(0)
	v_mov_b32_e32 v170, 0x358637bd
	v_mov_b32_e32 v194, 0x25a08
	v_mbcnt_lo_u32_b32 v195, -1, 0
	v_mbcnt_hi_u32_b32 v196, -1, v195
	v_mov_b32_e32 v197, 0x24000
	v_mov_b32_e32 v198, 0x1fa0
	v_mov_b32_e32 v199, 0x41b17218
	v_mov_b32_e32 v200, 0x7e800
	v_mov_b32_e32 v201, 0xfd0
	v_mov_b32_e32 v202, 0x100
	v_mov_b32_e32 v203, 0x200
	v_mov_b32_e32 v204, 0x7f61b1e6
	v_mov_b32_e32 v205, 0xff800000
	v_mov_b32_e32 v206, 0x3f80
	v_mov_b32_e32 v207, 0x1d400
	s_waitcnt vmcnt(7)
	v_mov_b32_e32 v110, v171
	v_mov_b32_e32 v111, v171
	s_barrier
	s_nop 0
	v_ashrrev_i32_e32 v112, 1, v111
	v_and_b32_e32 v112, 0xffffffc0, v112
	v_and_b32_e32 v0, 15, v110
	s_waitcnt vmcnt(5)
	v_add_u32_e32 v114, s0, v112
	v_lshlrev_b32_e32 v111, 1, v111
	v_lshrrev_b32_e32 v110, 2, v110
	v_and_b32_e32 v111, 0x80, v111
	v_and_b32_e32 v110, 12, v110
	v_or_b32_e32 v115, v114, v0
	v_or3_b32 v110, v110, v111, s19
	v_mad_i64_i32 v[112:113], s[0:1], v115, s91, 0
	v_cmp_gt_i32_e64 s[12:13], s69, v110
	v_lshl_add_u64 v[112:113], s[78:79], 0, v[112:113]
	v_ashrrev_i32_e32 v111, 31, v110
	s_and_saveexec_b64 s[0:1], s[12:13]
	s_cbranch_execz .LBB0_134
	v_lshl_add_u64 v[116:117], v[110:111], 1, v[112:113]
	v_cvt_pk_bf16_f32 v119, v160, v161
	v_cvt_pk_bf16_f32 v118, v158, v159
	global_store_dwordx2 v[116:117], v[118:119], off

; DI int ltid() { int t = threadIdx.x; asm volatile("" : "+v"(t)); return t; }
; #define GLOAD(kt) { GL1(0, kt) GL1(1, kt) GL1(2, kt) GL1(3, kt) }
; #define SSTORE(buf)                              \
;   {                                              \
;     char* as_ = smem + (buf) * BUF;              \
;     char* bs_ = as_ + ASZ;                       \
;     SS1(0) SS1(1) SS1(2) SS1(3)                  \
;   }
; template <int MT, int NT>
; DI void gemm_core(const u16* __restrict__ A, int lda, const u16* __restrict__ B, int ldb, int K,
;                   f32x4 (&acc)[MT][NT], char* smem) {
;   constexpr int BM = 64 * MT, BN = 32 * NT;
;   constexpr int ASZ = BM * 128, BSZ = BN * 128, BUF = ASZ + BSZ;
;   constexpr int NA = BM / 64, NB = BN / 64;
;   const int tid = ltid(), l = tid & 63, w = tid >> 6, wm = w >> 1, wn = w & 1;
;   const int fr = l & 15, fq = l >> 4;
;   uint4 ra0, ra1, ra2, ra3, rb0, rb1, rb2, rb3;
;   const int nk = K >> 6;
;   const int srow = tid >> 3, sch = tid & 7;
;   const int ssw = sch ^ ((srow >> 1) & 7);
;   const int fsw = (fr >> 1) & 7;
;     ...
;   GLOAD(0);
;   SSTORE(0);
;   GLOAD(((1 < nk) ? 1 : 0));
.LBB0_234:
	s_or_b64 exec, exec, s[0:1]
	s_mul_i32 s0, s8, 0x7ffffd
	s_add_i32 s0, s0, s7
	s_lshl_b32 s1, s6, 8
	s_lshl_b32 s0, s0, 9
	s_and_b32 s1, s1, 0x100
	s_or_b32 s0, s0, s1
	s_mul_i32 s6, s5, 0x1fa0
	s_mul_hi_i32 s1, s5, 0x1fa0
	s_add_u32 s6, s78, s6
	s_addc_u32 s1, s79, s1
	s_add_u32 s6, s6, 0x1c10
	s_addc_u32 s7, s1, 0
	s_mul_i32 s8, s0, 0x280
	s_mul_hi_i32 s1, s0, 0x280
	s_add_u32 s8, s2, s8
	v_mov_b32_e32 v34, v171
	s_addc_u32 s9, s3, s1
	v_mov_b64_e32 v[26:27], s[6:7]
	v_ashrrev_i32_e32 v35, 3, v34
	v_lshlrev_b32_e32 v36, 4, v34
	v_mov_b64_e32 v[30:31], s[8:9]
	v_add_u32_e32 v37, 64, v35
	v_add_u32_e32 v38, 0x80, v35
	v_add_u32_e32 v39, 0xc0, v35
	s_waitcnt lgkmcnt(0)
	v_mad_i64_i32 v[2:3], s[6:7], v35, s91, v[26:27]
	v_and_b32_e32 v0, 0x70, v36
	v_mad_i64_i32 v[6:7], s[6:7], v35, s12, v[30:31]
	v_mad_i64_i32 v[10:11], s[6:7], v37, s91, v[26:27]
	v_mad_i64_i32 v[14:15], s[6:7], v37, s12, v[30:31]
	v_mad_i64_i32 v[18:19], s[6:7], v38, s91, v[26:27]
	v_mad_i64_i32 v[22:23], s[6:7], v38, s12, v[30:31]
	v_mad_i64_i32 v[26:27], s[6:7], v39, s91, v[26:27]
	v_mad_i64_i32 v[30:31], s[6:7], v39, s12, v[30:31]
	v_lshl_add_u64 v[162:163], v[2:3], 0, v[0:1]
	v_lshl_add_u64 v[164:165], v[6:7], 0, v[0:1]
	v_lshl_add_u64 v[166:167], v[10:11], 0, v[0:1]
	v_lshl_add_u64 v[168:169], v[14:15], 0, v[0:1]
	v_lshl_add_u64 v[176:177], v[18:19], 0, v[0:1]
	v_lshl_add_u64 v[178:179], v[22:23], 0, v[0:1]
	v_lshl_add_u64 v[180:181], v[26:27], 0, v[0:1]
	v_lshl_add_u64 v[182:183], v[30:31], 0, v[0:1]
	global_load_dwordx4 v[2:5], v[162:163], off
	global_load_dwordx4 v[6:9], v[164:165], off
	global_load_dwordx4 v[10:13], v[166:167], off
	global_load_dwordx4 v[14:17], v[168:169], off
	global_load_dwordx4 v[18:21], v[176:177], off
	global_load_dwordx4 v[22:25], v[178:179], off
	global_load_dwordx4 v[26:29], v[180:181], off
	global_load_dwordx4 v[30:33], v[182:183], off
	global_load_dwordx4 v[98:101], v[180:181], off offset:128
	global_load_dwordx4 v[102:105], v[176:177], off offset:128
	global_load_dwordx4 v[106:109], v[166:167], off offset:128
	global_load_dwordx4 v[110:113], v[162:163], off offset:128
	global_load_dwordx4 v[114:117], v[182:183], off offset:128
	global_load_dwordx4 v[118:121], v[178:179], off offset:128
	global_load_dwordx4 v[122:125], v[168:169], off offset:128
	global_load_dwordx4 v[126:129], v[164:165], off offset:128
	v_lshrrev_b32_e32 v40, 4, v34
	v_lshrrev_b32_e32 v42, 1, v34
	v_bfe_u32 v43, v34, 1, 3
	v_and_b32_e32 v44, 15, v34
	v_lshlrev_b32_e32 v0, 7, v35
	v_bitop3_b32 v173, v36, s75, v34 bitop3:0x48
	v_bfe_u32 v41, v34, 4, 2
	v_lshlrev_b32_e32 v45, 1, v34
	v_and_or_b32 v34, v42, s90, v44
	v_bitop3_b32 v36, v40, v43, 3 bitop3:0x6c
	v_or_b32_e32 v40, v0, v173
	v_lshlrev_b32_e32 v175, 7, v37
	v_lshlrev_b32_e32 v184, 7, v38
	v_lshlrev_b32_e32 v185, 7, v39
	v_lshlrev_b32_e32 v186, 4, v36
	v_lshlrev_b32_e32 v187, 7, v34
	v_or_b32_e32 v34, v175, v173
	v_or_b32_e32 v36, v184, v173
	v_or_b32_e32 v37, v185, v173
	v_and_or_b32 v35, v45, s57, v44
	v_lshlrev_b32_e32 v188, 7, v35
	s_mov_b32 s1, 0
	s_waitcnt vmcnt(15)
	ds_write_b128 v40, v[2:5]
	s_waitcnt vmcnt(13)
	ds_write_b128 v34, v[10:13]
	s_waitcnt vmcnt(11)
	ds_write_b128 v36, v[18:21]
	s_waitcnt vmcnt(9)
	ds_write_b128 v37, v[26:29]
	ds_write_b128 v40, v[6:9] offset:32768
	ds_write_b128 v34, v[14:17] offset:32768
	ds_write_b128 v36, v[22:25] offset:32768
	s_waitcnt vmcnt(8)
	ds_write_b128 v37, v[30:33] offset:32768
	v_bitop3_b32 v2, v41, v43, 4 bitop3:0x36
	v_lshlrev_b32_e32 v189, 4, v2
	v_mov_b32_e32 v2, 0
	v_mov_b32_e32 v3, v2
	v_mov_b32_e32 v4, v2
	v_mov_b32_e32 v5, v2
	v_mov_b32_e32 v6, v2
	v_mov_b32_e32 v7, v2
	v_mov_b32_e32 v8, v2
	v_mov_b32_e32 v9, v2
	v_mov_b32_e32 v10, v2
	v_mov_b32_e32 v11, v2
	v_mov_b32_e32 v12, v2
	v_mov_b32_e32 v13, v2
	v_mov_b32_e32 v14, v2
	v_mov_b32_e32 v15, v2
	v_mov_b32_e32 v16, v2
	v_mov_b32_e32 v17, v2
	v_mov_b32_e32 v18, v2
	v_mov_b32_e32 v19, v2
	v_mov_b32_e32 v20, v2
	v_mov_b32_e32 v21, v2
	v_mov_b32_e32 v22, v2
	v_mov_b32_e32 v23, v2
	v_mov_b32_e32 v24, v2
	v_mov_b32_e32 v25, v2
	v_mov_b32_e32 v26, v2
	v_mov_b32_e32 v27, v2
	v_mov_b32_e32 v28, v2
	v_mov_b32_e32 v29, v2
	v_mov_b32_e32 v30, v2
	v_mov_b32_e32 v31, v2
	v_mov_b32_e32 v32, v2
	v_mov_b32_e32 v33, v2
	v_mov_b32_e32 v34, v2
	v_mov_b32_e32 v35, v2
	v_mov_b32_e32 v36, v2
	v_mov_b32_e32 v37, v2
	v_mov_b32_e32 v38, v2
	v_mov_b32_e32 v39, v2
	v_mov_b32_e32 v40, v2
	v_mov_b32_e32 v41, v2
	v_mov_b32_e32 v42, v2
	v_mov_b32_e32 v43, v2
	v_mov_b32_e32 v44, v2
	v_mov_b32_e32 v45, v2
	v_mov_b32_e32 v46, v2
	v_mov_b32_e32 v47, v2
	v_mov_b32_e32 v48, v2
	v_mov_b32_e32 v49, v2
	v_mov_b32_e32 v50, v2
	v_mov_b32_e32 v51, v2
	v_mov_b32_e32 v52, v2
	v_mov_b32_e32 v53, v2
	v_mov_b32_e32 v54, v2
	v_mov_b32_e32 v55, v2
	v_mov_b32_e32 v56, v2
	v_mov_b32_e32 v57, v2
	v_mov_b32_e32 v58, v2
	v_mov_b32_e32 v59, v2
	v_mov_b32_e32 v60, v2
	v_mov_b32_e32 v61, v2
	v_mov_b32_e32 v62, v2
	v_mov_b32_e32 v63, v2
	v_mov_b32_e32 v64, v2
	v_mov_b32_e32 v65, v2
	v_mov_b32_e32 v66, v2
	v_mov_b32_e32 v67, v2
	v_mov_b32_e32 v68, v2
	v_mov_b32_e32 v69, v2
	v_mov_b32_e32 v70, v2
	v_mov_b32_e32 v71, v2
	v_mov_b32_e32 v72, v2
	v_mov_b32_e32 v73, v2
	v_mov_b32_e32 v74, v2
	v_mov_b32_e32 v75, v2
	v_mov_b32_e32 v76, v2
	v_mov_b32_e32 v77, v2
	v_mov_b32_e32 v78, v2
	v_mov_b32_e32 v79, v2
	v_mov_b32_e32 v80, v2
	v_mov_b32_e32 v81, v2
	v_mov_b32_e32 v82, v2
	v_mov_b32_e32 v83, v2
	v_mov_b32_e32 v84, v2
	v_mov_b32_e32 v85, v2
	v_mov_b32_e32 v86, v2
	v_mov_b32_e32 v87, v2
	v_mov_b32_e32 v88, v2
	v_mov_b32_e32 v89, v2
	v_mov_b32_e32 v90, v2
	v_mov_b32_e32 v91, v2
	v_mov_b32_e32 v92, v2
	v_mov_b32_e32 v93, v2
	v_mov_b32_e32 v94, v2
	v_mov_b32_e32 v95, v2
	v_mov_b32_e32 v96, v2
	v_mov_b32_e32 v97, v2
	v_mov_b32_e32 v130, v2
	v_mov_b32_e32 v131, v2
	v_mov_b32_e32 v132, v2
	v_mov_b32_e32 v133, v2
	v_mov_b32_e32 v134, v2
	v_mov_b32_e32 v135, v2
	v_mov_b32_e32 v136, v2
	v_mov_b32_e32 v137, v2
	v_mov_b32_e32 v138, v2
	v_mov_b32_e32 v139, v2
	v_mov_b32_e32 v140, v2
	v_mov_b32_e32 v141, v2
	v_mov_b32_e32 v142, v2
	v_mov_b32_e32 v143, v2
	v_mov_b32_e32 v144, v2
	v_mov_b32_e32 v145, v2
	v_mov_b32_e32 v146, v2
	v_mov_b32_e32 v147, v2
	v_mov_b32_e32 v148, v2
	v_mov_b32_e32 v149, v2
	v_mov_b32_e32 v150, v2
	v_mov_b32_e32 v151, v2
	v_mov_b32_e32 v152, v2
	v_mov_b32_e32 v153, v2
	v_mov_b32_e32 v154, v2
	v_mov_b32_e32 v155, v2
	v_mov_b32_e32 v156, v2
	v_mov_b32_e32 v157, v2
	v_mov_b32_e32 v158, v2
	v_mov_b32_e32 v159, v2
	v_mov_b32_e32 v160, v2
	v_mov_b32_e32 v161, v2
	s_waitcnt lgkmcnt(0)
	s_barrier
; DI f32x4 mfma16(bf16x8 a, bf16x8 b, f32x4 c) { return __builtin_amdgcn_mfma_f32_16x16x32_bf16(a, b, c, 0, 0, 0); }
; #define GLOAD(kt) { GL1(0, kt) GL1(1, kt) GL1(2, kt) GL1(3, kt) }
; #define SSTORE(buf)                              \
;   {                                              \
;     char* as_ = smem + (buf) * BUF;              \
;     char* bs_ = as_ + ASZ;                       \
;     SS1(0) SS1(1) SS1(2) SS1(3)                  \
;   }
; template <int MT, int NT>
; DI void gemm_core(const u16* __restrict__ A, int lda, const u16* __restrict__ B, int ldb, int K,
;                   f32x4 (&acc)[MT][NT], char* smem) {
;     ...
;   for (int kt = 0; kt < nk; ++kt) {
;     __syncthreads();
;     SSTORE((kt + 1) & 1);
;     { const int kn_ = (kt + 2 < nk) ? kt + 2 : nk - 1; GLOAD(kn_); }
;     const char* as = smem + (kt & 1) * BUF;
;     const char* bs = as + ASZ;
; #pragma unroll
;     for (int kk = 0; kk < 2; ++kk) {
;       bf16x8 xf[MT], wf[NT];
; #pragma unroll
;       for (int mi = 0; mi < MT; ++mi)
;         xf[mi] = *(const bf16x8*)(as + (wm * (MT * 16) + mi * 16 + fr) * 128 + (((kk * 4 + fq) ^ fsw) * 16));
; #pragma unroll
;       for (int ni = 0; ni < NT; ++ni)
;         wf[ni] = *(const bf16x8*)(bs + (wn * (NT * 16) + ni * 16 + fr) * 128 + (((kk * 4 + fq) ^ fsw) * 16));
;       __builtin_amdgcn_s_setprio(1);
; #pragma unroll
;       for (int mi = 0; mi < MT; ++mi)
; #pragma unroll
;         for (int ni = 0; ni < NT; ++ni) acc[mi][ni] = mfma16(wf[ni], xf[mi], acc[mi][ni]);
;       __builtin_amdgcn_s_setprio(0);
;     }
;   }
	v_add_u32_e32 v207, v186, v188
	v_add_u32_e32 v206, v186, v187
	ds_read_b128 v[190:193], v206
	ds_read_b128 v[208:211], v206 offset:2048
	ds_read_b128 v[212:215], v206 offset:4096
	ds_read_b128 v[216:219], v206 offset:6144
	ds_read_b128 v[220:223], v207 offset:32768
	ds_read_b128 v[224:227], v207 offset:34816
	ds_read_b128 v[228:231], v207 offset:36864
	ds_read_b128 v[232:235], v207 offset:38912
	ds_read_b128 v[236:239], v207 offset:40960
	ds_read_b128 v[240:243], v207 offset:43008
	ds_read_b128 v[244:247], v207 offset:45056
	ds_read_b128 v[248:251], v207 offset:47104
	s_waitcnt lgkmcnt(0)
.LBB0_235:
	s_add_i32 s6, s1, 0x10000
	s_and_b32 s7, s6, 0x10000
	s_cmp_eq_u32 s1, 0
	s_cselect_b32 s54, 0x100, s63
	s_and_b32 s1, s1, 0x10000
	v_or_b32_e32 v206, s1, v189
	v_add_u32_e32 v207, v206, v188
	v_add_u32_e32 v206, v206, v187
	v_add3_u32 v170, s7, v0, v173
	s_waitcnt lgkmcnt(10)
	v_mfma_f32_16x16x32_bf16 v[158:161], v[220:223], v[190:193], v[158:161]
	s_waitcnt vmcnt(0)
	ds_write_b128 v170, v[110:113]
	s_waitcnt lgkmcnt(10)
	v_mfma_f32_16x16x32_bf16 v[94:97], v[220:223], v[208:211], v[94:97]
	v_lshl_add_u64 v[110:111], v[162:163], 0, s[54:55]
	global_load_dwordx4 v[110:113], v[110:111], off
	s_waitcnt lgkmcnt(8)
	v_mfma_f32_16x16x32_bf16 v[62:65], v[220:223], v[212:215], v[62:65]
	ds_write_b128 v170, v[126:129] offset:32768
	s_waitcnt lgkmcnt(3)
	v_mfma_f32_16x16x32_bf16 v[30:33], v[220:223], v[216:219], v[30:33]
	v_lshl_add_u64 v[126:127], v[164:165], 0, s[54:55]
	global_load_dwordx4 v[126:129], v[126:127], off
	ds_read_b128 v[194:197], v206
	v_mfma_f32_16x16x32_bf16 v[154:157], v[224:227], v[190:193], v[154:157]
	ds_read_b128 v[220:223], v207 offset:32768
	ds_write_b128 v170, v[106:109] offset:8192
	v_mfma_f32_16x16x32_bf16 v[90:93], v[224:227], v[208:211], v[90:93]
	v_lshl_add_u64 v[106:107], v[166:167], 0, s[54:55]
	global_load_dwordx4 v[106:109], v[106:107], off
	v_mfma_f32_16x16x32_bf16 v[58:61], v[224:227], v[212:215], v[58:61]
	ds_write_b128 v170, v[122:125] offset:40960
	v_mfma_f32_16x16x32_bf16 v[26:29], v[224:227], v[216:219], v[26:29]
	v_lshl_add_u64 v[122:123], v[168:169], 0, s[54:55]
	global_load_dwordx4 v[122:125], v[122:123], off
	ds_read_b128 v[198:201], v206 offset:2048
	v_mfma_f32_16x16x32_bf16 v[150:153], v[228:231], v[190:193], v[150:153]
	ds_read_b128 v[224:227], v207 offset:34816
	ds_write_b128 v170, v[102:105] offset:16384
	v_mfma_f32_16x16x32_bf16 v[86:89], v[228:231], v[208:211], v[86:89]
	v_lshl_add_u64 v[102:103], v[176:177], 0, s[54:55]
	global_load_dwordx4 v[102:105], v[102:103], off
	v_mfma_f32_16x16x32_bf16 v[54:57], v[228:231], v[212:215], v[54:57]
	ds_write_b128 v170, v[118:121] offset:49152
	v_mfma_f32_16x16x32_bf16 v[22:25], v[228:231], v[216:219], v[22:25]
	v_lshl_add_u64 v[118:119], v[178:179], 0, s[54:55]
	global_load_dwordx4 v[118:121], v[118:119], off
	ds_read_b128 v[202:205], v206 offset:4096
	v_mfma_f32_16x16x32_bf16 v[146:149], v[232:235], v[190:193], v[146:149]
	ds_read_b128 v[228:231], v207 offset:36864
	ds_write_b128 v170, v[98:101] offset:24576
	v_mfma_f32_16x16x32_bf16 v[82:85], v[232:235], v[208:211], v[82:85]
	v_lshl_add_u64 v[98:99], v[180:181], 0, s[54:55]
	global_load_dwordx4 v[98:101], v[98:99], off
	v_mfma_f32_16x16x32_bf16 v[50:53], v[232:235], v[212:215], v[50:53]
	ds_write_b128 v170, v[114:117] offset:57344
	v_mfma_f32_16x16x32_bf16 v[18:21], v[232:235], v[216:219], v[18:21]
	v_lshl_add_u64 v[114:115], v[182:183], 0, s[54:55]
	global_load_dwordx4 v[114:117], v[114:115], off
	v_mfma_f32_16x16x32_bf16 v[142:145], v[236:239], v[190:193], v[142:145]
	ds_read_b128 v[232:235], v207 offset:38912
	v_mfma_f32_16x16x32_bf16 v[78:81], v[236:239], v[208:211], v[78:81]
	v_mfma_f32_16x16x32_bf16 v[46:49], v[236:239], v[212:215], v[46:49]
	v_mfma_f32_16x16x32_bf16 v[14:17], v[236:239], v[216:219], v[14:17]
	v_mfma_f32_16x16x32_bf16 v[138:141], v[240:243], v[190:193], v[138:141]
	ds_read_b128 v[236:239], v207 offset:40960
	v_mfma_f32_16x16x32_bf16 v[74:77], v[240:243], v[208:211], v[74:77]
	v_mfma_f32_16x16x32_bf16 v[42:45], v[240:243], v[212:215], v[42:45]
	v_mfma_f32_16x16x32_bf16 v[10:13], v[240:243], v[216:219], v[10:13]
	v_mfma_f32_16x16x32_bf16 v[134:137], v[244:247], v[190:193], v[134:137]
	ds_read_b128 v[240:243], v207 offset:43008
	v_mfma_f32_16x16x32_bf16 v[70:73], v[244:247], v[208:211], v[70:73]
	v_mfma_f32_16x16x32_bf16 v[38:41], v[244:247], v[212:215], v[38:41]
	v_mfma_f32_16x16x32_bf16 v[6:9], v[244:247], v[216:219], v[6:9]
	s_waitcnt lgkmcnt(15)
	v_mfma_f32_16x16x32_bf16 v[2:5], v[248:251], v[216:219], v[2:5]
	ds_read_b128 v[244:247], v207 offset:45056
	ds_read_b128 v[216:219], v206 offset:6144
	v_mfma_f32_16x16x32_bf16 v[130:133], v[248:251], v[190:193], v[130:133]
	v_mfma_f32_16x16x32_bf16 v[66:69], v[248:251], v[208:211], v[66:69]
	v_mfma_f32_16x16x32_bf16 v[34:37], v[248:251], v[212:215], v[34:37]
	ds_read_b128 v[248:251], v207 offset:47104
	s_waitcnt lgkmcnt(6)
	s_barrier
; DI f32x4 mfma16(bf16x8 a, bf16x8 b, f32x4 c) { return __builtin_amdgcn_mfma_f32_16x16x32_bf16(a, b, c, 0, 0, 0); }
; #define GLOAD(kt) { GL1(0, kt) GL1(1, kt) GL1(2, kt) GL1(3, kt) }
; #define SSTORE(buf)                              \
;   {                                              \
;     char* as_ = smem + (buf) * BUF;              \
;     char* bs_ = as_ + ASZ;                       \
;     SS1(0) SS1(1) SS1(2) SS1(3)                  \
;   }
; #define EPI_LOOP(MT_, NT_)                                                \
;   const int l_ = ltid() & 63, w_ = ltid() >> 6;                           \
;   const int wm_ = w_ >> 1, wn_ = w_ & 1, fr_ = l_ & 15, fq_ = l_ >> 4;    \
;   _Pragma("unroll") for (int mi = 0; mi < MT_; ++mi)                      \
;   _Pragma("unroll") for (int ni = 0; ni < NT_; ++ni)
; template <int MT, int NT>
; DI void gemm_core(const u16* __restrict__ A, int lda, const u16* __restrict__ B, int ldb, int K,
;                   f32x4 (&acc)[MT][NT], char* smem) {
;     ...
;   for (int kt = 0; kt < nk; ++kt) {
;     __syncthreads();
;     SSTORE((kt + 1) & 1);
;     { const int kn_ = (kt + 2 < nk) ? kt + 2 : nk - 1; GLOAD(kn_); }
;     const char* as = smem + (kt & 1) * BUF;
;     const char* bs = as + ASZ;
; #pragma unroll
;     for (int kk = 0; kk < 2; ++kk) {
;       bf16x8 xf[MT], wf[NT];
; #pragma unroll
;       for (int mi = 0; mi < MT; ++mi)
;         xf[mi] = *(const bf16x8*)(as + (wm * (MT * 16) + mi * 16 + fr) * 128 + (((kk * 4 + fq) ^ fsw) * 16));
; #pragma unroll
;       for (int ni = 0; ni < NT; ++ni)
;         wf[ni] = *(const bf16x8*)(bs + (wn * (NT * 16) + ni * 16 + fr) * 128 + (((kk * 4 + fq) ^ fsw) * 16));
;       __builtin_amdgcn_s_setprio(1);
; #pragma unroll
;       for (int mi = 0; mi < MT; ++mi)
; #pragma unroll
;         for (int ni = 0; ni < NT; ++ni) acc[mi][ni] = mfma16(wf[ni], xf[mi], acc[mi][ni]);
;       __builtin_amdgcn_s_setprio(0);
;     }
;   }
; DI void qx_tile(const Params& p, int l, int rt, int ct, char* smem) {
;     ...
;   u16* QX = (u16*)p.out;
;   EPI_LOOP(4, 8) {
;     const int rl = wm_ * 64 + mi * 16 + fr_, col = c0 + wn_ * 128 + ni * 16 + fq_ * 4;
;     const float rs = rsv[rl];
;     uint2 o;
;     o.x = pack2(acc[mi][ni][0] * rs, acc[mi][ni][1] * rs); o.y = pack2(acc[mi][ni][2] * rs, acc[mi][ni][3] * rs);
;     *(uint2*)(QX + (size_t)(r0 + rl) * LDQ + col) = o;
;   }
	v_or_b32_e32 v206, s7, v186
	v_add_u32_e32 v207, v206, v188
	v_add_u32_e32 v206, v206, v187
	v_mfma_f32_16x16x32_bf16 v[158:161], v[220:223], v[194:197], v[158:161]
	v_mfma_f32_16x16x32_bf16 v[94:97], v[220:223], v[198:201], v[94:97]
	v_mfma_f32_16x16x32_bf16 v[62:65], v[220:223], v[202:205], v[62:65]
	s_waitcnt lgkmcnt(1)
	v_mfma_f32_16x16x32_bf16 v[30:33], v[220:223], v[216:219], v[30:33]
	ds_read_b128 v[190:193], v206
	v_mfma_f32_16x16x32_bf16 v[154:157], v[224:227], v[194:197], v[154:157]
	ds_read_b128 v[220:223], v207 offset:32768
	v_mfma_f32_16x16x32_bf16 v[90:93], v[224:227], v[198:201], v[90:93]
	v_mfma_f32_16x16x32_bf16 v[58:61], v[224:227], v[202:205], v[58:61]
	v_mfma_f32_16x16x32_bf16 v[26:29], v[224:227], v[216:219], v[26:29]
	ds_read_b128 v[208:211], v206 offset:2048
	v_mfma_f32_16x16x32_bf16 v[150:153], v[228:231], v[194:197], v[150:153]
	ds_read_b128 v[224:227], v207 offset:34816
	v_mfma_f32_16x16x32_bf16 v[86:89], v[228:231], v[198:201], v[86:89]
	v_mfma_f32_16x16x32_bf16 v[54:57], v[228:231], v[202:205], v[54:57]
	v_mfma_f32_16x16x32_bf16 v[22:25], v[228:231], v[216:219], v[22:25]
	ds_read_b128 v[212:215], v206 offset:4096
	v_mfma_f32_16x16x32_bf16 v[146:149], v[232:235], v[194:197], v[146:149]
	ds_read_b128 v[228:231], v207 offset:36864
	v_mfma_f32_16x16x32_bf16 v[82:85], v[232:235], v[198:201], v[82:85]
	v_mfma_f32_16x16x32_bf16 v[50:53], v[232:235], v[202:205], v[50:53]
	v_mfma_f32_16x16x32_bf16 v[18:21], v[232:235], v[216:219], v[18:21]
	v_mfma_f32_16x16x32_bf16 v[142:145], v[236:239], v[194:197], v[142:145]
	ds_read_b128 v[232:235], v207 offset:38912
	v_mfma_f32_16x16x32_bf16 v[78:81], v[236:239], v[198:201], v[78:81]
	v_mfma_f32_16x16x32_bf16 v[46:49], v[236:239], v[202:205], v[46:49]
	v_mfma_f32_16x16x32_bf16 v[14:17], v[236:239], v[216:219], v[14:17]
	v_mfma_f32_16x16x32_bf16 v[138:141], v[240:243], v[194:197], v[138:141]
	ds_read_b128 v[236:239], v207 offset:40960
	v_mfma_f32_16x16x32_bf16 v[74:77], v[240:243], v[198:201], v[74:77]
	v_mfma_f32_16x16x32_bf16 v[42:45], v[240:243], v[202:205], v[42:45]
	v_mfma_f32_16x16x32_bf16 v[10:13], v[240:243], v[216:219], v[10:13]
	v_mfma_f32_16x16x32_bf16 v[134:137], v[244:247], v[194:197], v[134:137]
	ds_read_b128 v[240:243], v207 offset:43008
	v_mfma_f32_16x16x32_bf16 v[70:73], v[244:247], v[198:201], v[70:73]
	v_mfma_f32_16x16x32_bf16 v[38:41], v[244:247], v[202:205], v[38:41]
	v_mfma_f32_16x16x32_bf16 v[6:9], v[244:247], v[216:219], v[6:9]
	s_waitcnt lgkmcnt(9)
	v_mfma_f32_16x16x32_bf16 v[2:5], v[248:251], v[216:219], v[2:5]
	ds_read_b128 v[244:247], v207 offset:45056
	ds_read_b128 v[216:219], v206 offset:6144
	v_mfma_f32_16x16x32_bf16 v[130:133], v[248:251], v[194:197], v[130:133]
	v_mfma_f32_16x16x32_bf16 v[66:69], v[248:251], v[198:201], v[66:69]
	v_mfma_f32_16x16x32_bf16 v[34:37], v[248:251], v[202:205], v[34:37]
	ds_read_b128 v[248:251], v207 offset:47104
	s_cmp_lg_u32 s6, 0x40000
	s_mov_b32 s1, s6
	s_cbranch_scc1 .LBB0_235
	s_waitcnt vmcnt(0) lgkmcnt(0)
	v_mov_b32_e32 v170, 0x358637bd
	v_mov_b32_e32 v194, 0x25a08
	v_mbcnt_lo_u32_b32 v195, -1, 0
	v_mbcnt_hi_u32_b32 v196, -1, v195
	v_mov_b32_e32 v197, 0x24000
	v_mov_b32_e32 v198, 0x1fa0
	v_mov_b32_e32 v199, 0x41b17218
	v_mov_b32_e32 v200, 0x7e800
	v_mov_b32_e32 v201, 0xfd0
	v_mov_b32_e32 v202, 0x100
	v_mov_b32_e32 v203, 0x200
	v_mov_b32_e32 v204, 0x7f61b1e6
	v_mov_b32_e32 v205, 0xff800000
	v_mov_b32_e32 v206, 0x3f80
	v_mov_b32_e32 v207, 0x1d400
	s_waitcnt vmcnt(1)
	v_mov_b32_e32 v98, v171
	v_mov_b32_e32 v99, v171
	s_barrier
	s_movk_i32 s1, 0xffc0
	v_and_b32_e32 v0, 15, v98
	v_ashrrev_i32_e32 v100, 1, v99
	v_lshlrev_b32_e32 v99, 1, v99
	v_lshrrev_b32_e32 v98, 2, v98
	v_and_or_b32 v0, v100, s1, v0
	v_and_b32_e32 v99, 0x80, v99
	v_and_b32_e32 v98, 12, v98
	v_or3_b32 v98, v98, v99, s0
	v_lshl_add_u32 v99, v0, 2, v197
	ds_read_b32 v106, v99
	v_add_u32_e32 v102, s5, v0
	v_mov_b64_e32 v[100:101], s[86:87]
	s_movk_i32 s6, 0xc80
	v_ashrrev_i32_e32 v99, 31, v98
	v_mad_i64_i32 v[102:103], s[0:1], v102, s6, v[100:101]
	s_waitcnt lgkmcnt(0)
	v_mul_f32_e32 v104, v158, v106
	v_mul_f32_e32 v107, v159, v106
	v_mul_f32_e32 v105, v160, v106
	v_mul_f32_e32 v108, v161, v106
	v_lshlrev_b64 v[98:99], 1, v[98:99]
	v_lshl_add_u64 v[102:103], v[102:103], 0, v[98:99]
	v_cvt_pk_bf16_f32 v105, v105, v108
	v_cvt_pk_bf16_f32 v104, v104, v107
	global_store_dwordx2 v[102:103], v[104:105], off
	v_mul_f32_e32 v104, v154, v106
	v_mul_f32_e32 v107, v155, v106
	v_mul_f32_e32 v105, v156, v106
	v_mul_f32_e32 v108, v157, v106
	v_cvt_pk_bf16_f32 v105, v105, v108
	v_cvt_pk_bf16_f32 v104, v104, v107
	global_store_dwordx2 v[102:103], v[104:105], off offset:32
	v_mul_f32_e32 v104, v150, v106
	v_mul_f32_e32 v107, v151, v106
	v_mul_f32_e32 v105, v152, v106
	v_mul_f32_e32 v108, v153, v106
	v_cvt_pk_bf16_f32 v105, v105, v108
	v_cvt_pk_bf16_f32 v104, v104, v107
	global_store_dwordx2 v[102:103], v[104:105], off offset:64
	v_mul_f32_e32 v104, v146, v106
	v_mul_f32_e32 v107, v147, v106
	v_mul_f32_e32 v105, v148, v106
	v_mul_f32_e32 v108, v149, v106
	v_cvt_pk_bf16_f32 v105, v105, v108
	v_cvt_pk_bf16_f32 v104, v104, v107
	global_store_dwordx2 v[102:103], v[104:105], off offset:96
	v_mul_f32_e32 v104, v142, v106
	v_mul_f32_e32 v107, v143, v106
	v_mul_f32_e32 v105, v144, v106
	v_mul_f32_e32 v108, v145, v106
	v_cvt_pk_bf16_f32 v105, v105, v108
	v_cvt_pk_bf16_f32 v104, v104, v107
	global_store_dwordx2 v[102:103], v[104:105], off offset:128
	v_mul_f32_e32 v104, v138, v106
	v_mul_f32_e32 v107, v139, v106
	v_mul_f32_e32 v105, v140, v106
	v_mul_f32_e32 v108, v141, v106
	v_cvt_pk_bf16_f32 v105, v105, v108
	v_cvt_pk_bf16_f32 v104, v104, v107
	global_store_dwordx2 v[102:103], v[104:105], off offset:160
	v_mul_f32_e32 v104, v134, v106
	v_mul_f32_e32 v107, v135, v106
	v_mul_f32_e32 v105, v136, v106
	v_mul_f32_e32 v108, v137, v106
	v_cvt_pk_bf16_f32 v105, v105, v108
	v_cvt_pk_bf16_f32 v104, v104, v107
	global_store_dwordx2 v[102:103], v[104:105], off offset:192
	v_mul_f32_e32 v104, v130, v106
	v_mul_f32_e32 v107, v131, v106
	v_mul_f32_e32 v105, v132, v106
	v_mul_f32_e32 v106, v133, v106
	v_cvt_pk_bf16_f32 v105, v105, v106
	v_cvt_pk_bf16_f32 v104, v104, v107
	global_store_dwordx2 v[102:103], v[104:105], off offset:224
	v_or_b32_e32 v102, 16, v0
	v_lshl_add_u32 v104, v102, 2, v197
	ds_read_b32 v104, v104
	v_add_u32_e32 v102, s5, v102
	v_mad_i64_i32 v[102:103], s[0:1], v102, s6, v[100:101]
	s_add_i32 s4, s4, 1
	s_waitcnt lgkmcnt(0)
; #define EPI_LOOP(MT_, NT_)                                                \
;   const int l_ = ltid() & 63, w_ = ltid() >> 6;                           \
;   const int wm_ = w_ >> 1, wn_ = w_ & 1, fr_ = l_ & 15, fq_ = l_ >> 4;    \
;   _Pragma("unroll") for (int mi = 0; mi < MT_; ++mi)                      \
;   _Pragma("unroll") for (int ni = 0; ni < NT_; ++ni)
; DI void qx_tile(const Params& p, int l, int rt, int ct, char* smem) {
;     ...
;   EPI_LOOP(4, 8) {
;     const int rl = wm_ * 64 + mi * 16 + fr_, col = c0 + wn_ * 128 + ni * 16 + fq_ * 4;
;     const float rs = rsv[rl];
;     uint2 o;
;     o.x = pack2(acc[mi][ni][0] * rs, acc[mi][ni][1] * rs); o.y = pack2(acc[mi][ni][2] * rs, acc[mi][ni][3] * rs);
;     *(uint2*)(QX + (size_t)(r0 + rl) * LDQ + col) = o;
;   }
;   __syncthreads();
	v_mul_f32_e32 v105, v94, v104
	v_mul_f32_e32 v106, v95, v104
	v_mul_f32_e32 v96, v96, v104
	v_mul_f32_e32 v97, v97, v104
	v_lshl_add_u64 v[94:95], v[102:103], 0, v[98:99]
	v_cvt_pk_bf16_f32 v97, v96, v97
	v_cvt_pk_bf16_f32 v96, v105, v106
	global_store_dwordx2 v[94:95], v[96:97], off
	v_mul_f32_e32 v90, v90, v104
	v_mul_f32_e32 v96, v91, v104
	v_mul_f32_e32 v91, v92, v104
	v_mul_f32_e32 v92, v93, v104
	v_cvt_pk_bf16_f32 v91, v91, v92
	v_cvt_pk_bf16_f32 v90, v90, v96
	global_store_dwordx2 v[94:95], v[90:91], off offset:32
	v_mul_f32_e32 v86, v86, v104
	v_mul_f32_e32 v90, v87, v104
	v_mul_f32_e32 v87, v88, v104
	v_mul_f32_e32 v88, v89, v104
	v_cvt_pk_bf16_f32 v87, v87, v88
	v_cvt_pk_bf16_f32 v86, v86, v90
	global_store_dwordx2 v[94:95], v[86:87], off offset:64
	v_mul_f32_e32 v82, v82, v104
	v_mul_f32_e32 v86, v83, v104
	v_mul_f32_e32 v83, v84, v104
	v_mul_f32_e32 v84, v85, v104
	v_cvt_pk_bf16_f32 v83, v83, v84
	v_cvt_pk_bf16_f32 v82, v82, v86
	global_store_dwordx2 v[94:95], v[82:83], off offset:96
	v_mul_f32_e32 v78, v78, v104
	v_mul_f32_e32 v82, v79, v104
	v_mul_f32_e32 v79, v80, v104
	v_mul_f32_e32 v80, v81, v104
	v_cvt_pk_bf16_f32 v79, v79, v80
	v_cvt_pk_bf16_f32 v78, v78, v82
	global_store_dwordx2 v[94:95], v[78:79], off offset:128
	v_mul_f32_e32 v74, v74, v104
	v_mul_f32_e32 v78, v75, v104
	v_mul_f32_e32 v75, v76, v104
	v_mul_f32_e32 v76, v77, v104
	v_cvt_pk_bf16_f32 v75, v75, v76
	v_cvt_pk_bf16_f32 v74, v74, v78
	global_store_dwordx2 v[94:95], v[74:75], off offset:160
	v_mul_f32_e32 v70, v70, v104
	v_mul_f32_e32 v74, v71, v104
	v_mul_f32_e32 v71, v72, v104
	v_mul_f32_e32 v72, v73, v104
	v_cvt_pk_bf16_f32 v71, v71, v72
	v_cvt_pk_bf16_f32 v70, v70, v74
	global_store_dwordx2 v[94:95], v[70:71], off offset:192
	v_mul_f32_e32 v66, v66, v104
	v_mul_f32_e32 v70, v67, v104
	v_mul_f32_e32 v67, v68, v104
	v_mul_f32_e32 v68, v69, v104
	v_cvt_pk_bf16_f32 v67, v67, v68
	v_cvt_pk_bf16_f32 v66, v66, v70
	global_store_dwordx2 v[94:95], v[66:67], off offset:224
	v_or_b32_e32 v66, 32, v0
	v_lshl_add_u32 v68, v66, 2, v197
	ds_read_b32 v68, v68
	v_add_u32_e32 v66, s5, v66
	v_mad_i64_i32 v[66:67], s[0:1], v66, s6, v[100:101]
	v_or_b32_e32 v0, 48, v0
	s_waitcnt lgkmcnt(0)
	v_mul_f32_e32 v69, v62, v68
	v_mul_f32_e32 v70, v63, v68
	v_mul_f32_e32 v64, v64, v68
	v_mul_f32_e32 v65, v65, v68
	v_lshl_add_u64 v[62:63], v[66:67], 0, v[98:99]
	v_cvt_pk_bf16_f32 v65, v64, v65
	v_cvt_pk_bf16_f32 v64, v69, v70
	global_store_dwordx2 v[62:63], v[64:65], off
	v_mul_f32_e32 v58, v58, v68
	v_mul_f32_e32 v64, v59, v68
	v_mul_f32_e32 v59, v60, v68
	v_mul_f32_e32 v60, v61, v68
	v_cvt_pk_bf16_f32 v59, v59, v60
	v_cvt_pk_bf16_f32 v58, v58, v64
	global_store_dwordx2 v[62:63], v[58:59], off offset:32
	v_mul_f32_e32 v54, v54, v68
	v_mul_f32_e32 v58, v55, v68
	v_mul_f32_e32 v55, v56, v68
	v_mul_f32_e32 v56, v57, v68
	v_cvt_pk_bf16_f32 v55, v55, v56
	v_cvt_pk_bf16_f32 v54, v54, v58
	global_store_dwordx2 v[62:63], v[54:55], off offset:64
	v_mul_f32_e32 v50, v50, v68
	v_mul_f32_e32 v54, v51, v68
	v_mul_f32_e32 v51, v52, v68
	v_mul_f32_e32 v52, v53, v68
	v_cvt_pk_bf16_f32 v51, v51, v52
	v_cvt_pk_bf16_f32 v50, v50, v54
	global_store_dwordx2 v[62:63], v[50:51], off offset:96
	v_mul_f32_e32 v46, v46, v68
	v_mul_f32_e32 v50, v47, v68
	v_mul_f32_e32 v47, v48, v68
	v_mul_f32_e32 v48, v49, v68
	v_cvt_pk_bf16_f32 v47, v47, v48
	v_cvt_pk_bf16_f32 v46, v46, v50
	global_store_dwordx2 v[62:63], v[46:47], off offset:128
	v_mul_f32_e32 v42, v42, v68
	v_mul_f32_e32 v46, v43, v68
	v_mul_f32_e32 v43, v44, v68
	v_mul_f32_e32 v44, v45, v68
	v_cvt_pk_bf16_f32 v43, v43, v44
	v_cvt_pk_bf16_f32 v42, v42, v46
	global_store_dwordx2 v[62:63], v[42:43], off offset:160
	v_mul_f32_e32 v38, v38, v68
	v_mul_f32_e32 v42, v39, v68
	v_mul_f32_e32 v39, v40, v68
	v_mul_f32_e32 v40, v41, v68
	v_cvt_pk_bf16_f32 v39, v39, v40
	v_cvt_pk_bf16_f32 v38, v38, v42
	global_store_dwordx2 v[62:63], v[38:39], off offset:192
	v_mul_f32_e32 v34, v34, v68
	v_mul_f32_e32 v38, v35, v68
	v_mul_f32_e32 v35, v36, v68
	v_mul_f32_e32 v36, v37, v68
	v_cvt_pk_bf16_f32 v35, v35, v36
	v_cvt_pk_bf16_f32 v34, v34, v38
	v_lshl_add_u32 v36, v0, 2, v197
	v_add_u32_e32 v0, s5, v0
	global_store_dwordx2 v[62:63], v[34:35], off offset:224
	v_mad_i64_i32 v[34:35], s[0:1], v0, s6, v[100:101]
	ds_read_b32 v0, v36
	s_mov_b64 s[0:1], 0
	s_waitcnt lgkmcnt(0)
	v_mul_f32_e32 v36, v30, v0
	v_mul_f32_e32 v37, v31, v0
	v_mul_f32_e32 v32, v32, v0
	v_mul_f32_e32 v33, v33, v0
	v_lshl_add_u64 v[30:31], v[34:35], 0, v[98:99]
	v_cvt_pk_bf16_f32 v33, v32, v33
	v_cvt_pk_bf16_f32 v32, v36, v37
	global_store_dwordx2 v[30:31], v[32:33], off
	v_mul_f32_e32 v26, v26, v0
	v_mul_f32_e32 v32, v27, v0
	v_mul_f32_e32 v27, v28, v0
	v_mul_f32_e32 v28, v29, v0
	v_cvt_pk_bf16_f32 v27, v27, v28
	v_cvt_pk_bf16_f32 v26, v26, v32
	global_store_dwordx2 v[30:31], v[26:27], off offset:32
	v_mul_f32_e32 v22, v22, v0
	v_mul_f32_e32 v26, v23, v0
	v_mul_f32_e32 v23, v24, v0
	v_mul_f32_e32 v24, v25, v0
	v_cvt_pk_bf16_f32 v23, v23, v24
	v_cvt_pk_bf16_f32 v22, v22, v26
	global_store_dwordx2 v[30:31], v[22:23], off offset:64
	v_mul_f32_e32 v18, v18, v0
	v_mul_f32_e32 v22, v19, v0
	v_mul_f32_e32 v19, v20, v0
	v_mul_f32_e32 v20, v21, v0
	v_cvt_pk_bf16_f32 v19, v19, v20
	v_cvt_pk_bf16_f32 v18, v18, v22
	global_store_dwordx2 v[30:31], v[18:19], off offset:96
	v_mul_f32_e32 v14, v14, v0
	v_mul_f32_e32 v18, v15, v0
	v_mul_f32_e32 v15, v16, v0
	v_mul_f32_e32 v16, v17, v0
	v_cvt_pk_bf16_f32 v15, v15, v16
	v_cvt_pk_bf16_f32 v14, v14, v18
	global_store_dwordx2 v[30:31], v[14:15], off offset:128
	v_mul_f32_e32 v10, v10, v0
	v_mul_f32_e32 v14, v11, v0
	v_mul_f32_e32 v11, v12, v0
	v_mul_f32_e32 v12, v13, v0
	v_cvt_pk_bf16_f32 v11, v11, v12
	v_cvt_pk_bf16_f32 v10, v10, v14
	global_store_dwordx2 v[30:31], v[10:11], off offset:160
	v_mul_f32_e32 v6, v6, v0
	v_mul_f32_e32 v10, v7, v0
	v_mul_f32_e32 v7, v8, v0
	v_mul_f32_e32 v8, v9, v0
	v_cvt_pk_bf16_f32 v7, v7, v8
	v_cvt_pk_bf16_f32 v6, v6, v10
	global_store_dwordx2 v[30:31], v[6:7], off offset:192
	v_mul_f32_e32 v2, v2, v0
	v_mul_f32_e32 v6, v3, v0
	v_mul_f32_e32 v3, v4, v0
	v_mul_f32_e32 v0, v5, v0
	v_cvt_pk_bf16_f32 v3, v3, v0
	v_cvt_pk_bf16_f32 v2, v2, v6
	global_store_dwordx2 v[30:31], v[2:3], off offset:224
	s_barrier
	s_branch .LBB0_228

; DI f32x16 mfma32(bf16x8 a, bf16x8 b, f32x16 c) { return __builtin_amdgcn_mfma_f32_32x32x16_bf16(a, b, c, 0, 0, 0); }
; DI void diff_item(const Params& p, int l, int qt, int bh, char* smem) {
;     ...
; #pragma unroll
;     for (int k2 = 0; k2 < 2; ++k2)
; #pragma unroll
;       for (int j = 0; j < 16; ++j) sa[k2][j] = __builtin_amdgcn_exp2f(sa[k2][j]);
; #pragma unroll
;     for (int k2 = 0; k2 < 2; ++k2)
; #pragma unroll
;       for (int s2 = 0; s2 < 2; ++s2) {
;         const bf16x8 pp = pack8(sa[k2], s2);
;         bf16x8 vf[4];
;         trfrag4<320>(Vs, 32 * k2 + 16 * s2, ln, vf);
; #pragma unroll
;         for (int mt = 0; mt < 4; ++mt) O[mt] = mfma32(vf[mt], pp, O[mt]);
;         Lacc = mfma32(onesf, pp, Lacc);
;       }
.LBB0_577:
	v_add_u32_e32 v182, v168, v169
	s_waitcnt lgkmcnt(1)
	ds_read_b64_tr_b16 v[226:227], v182 offset:22528
	ds_read_b64_tr_b16 v[228:229], v182 offset:25088
	ds_read_b64_tr_b16 v[230:231], v182 offset:22592
	ds_read_b64_tr_b16 v[232:233], v182 offset:25152
	ds_read_b64_tr_b16 v[234:235], v182 offset:22656
	ds_read_b64_tr_b16 v[236:237], v182 offset:25216
	ds_read_b64_tr_b16 v[238:239], v182 offset:22720
	ds_read_b64_tr_b16 v[240:241], v182 offset:25280
	v_exp_f32_e32 v84, v84
	v_exp_f32_e32 v85, v85
	v_exp_f32_e32 v86, v86
	v_exp_f32_e32 v87, v87
	v_exp_f32_e32 v88, v88
	v_exp_f32_e32 v89, v89
	v_exp_f32_e32 v90, v90
	v_exp_f32_e32 v91, v91
	v_exp_f32_e32 v92, v92
	v_exp_f32_e32 v93, v93
	v_cvt_pk_bf16_f32 v84, v84, v85
	v_cvt_pk_bf16_f32 v85, v86, v87
	v_cvt_pk_bf16_f32 v86, v88, v89
	v_cvt_pk_bf16_f32 v87, v90, v91
	s_nop 0
	s_waitcnt lgkmcnt(8)
	v_mfma_f32_32x32x16_bf16 v[52:67], v[210:213], v[84:87], v[52:67]
	v_exp_f32_e32 v94, v94
	v_exp_f32_e32 v95, v95
	v_mfma_f32_32x32x16_bf16 v[36:51], v[214:217], v[84:87], v[36:51]
	v_exp_f32_e32 v96, v96
	v_exp_f32_e32 v97, v97
	v_mfma_f32_32x32x16_bf16 v[20:35], v[218:221], v[84:87], v[20:35]
	v_exp_f32_e32 v98, v98
	v_exp_f32_e32 v99, v99
	v_mfma_f32_32x32x16_bf16 v[4:19], v[222:225], v[84:87], v[4:19]
	v_exp_f32_e32 v100, v100
	v_exp_f32_e32 v101, v101
	ds_read_b64_tr_b16 v[210:211], v182 offset:27648
	ds_read_b64_tr_b16 v[212:213], v182 offset:30208
	ds_read_b64_tr_b16 v[214:215], v182 offset:27712
	ds_read_b64_tr_b16 v[216:217], v182 offset:30272
	ds_read_b64_tr_b16 v[218:219], v182 offset:27776
	ds_read_b64_tr_b16 v[220:221], v182 offset:30336
	ds_read_b64_tr_b16 v[222:223], v182 offset:27840
	ds_read_b64_tr_b16 v[224:225], v182 offset:30400
	v_mfma_f32_32x32x16_bf16 v[68:83], v[116:119], v[84:87], v[68:83]
	v_cvt_pk_bf16_f32 v92, v92, v93
	v_cvt_pk_bf16_f32 v93, v94, v95
	v_cvt_pk_bf16_f32 v94, v96, v97
	v_cvt_pk_bf16_f32 v95, v98, v99
	s_nop 0
	s_waitcnt lgkmcnt(8)
	v_mfma_f32_32x32x16_bf16 v[52:67], v[226:229], v[92:95], v[52:67]
	v_exp_f32_e32 v102, v102
	v_exp_f32_e32 v103, v103
	v_mfma_f32_32x32x16_bf16 v[36:51], v[230:233], v[92:95], v[36:51]
	v_exp_f32_e32 v104, v104
	v_exp_f32_e32 v105, v105
	v_mfma_f32_32x32x16_bf16 v[20:35], v[234:237], v[92:95], v[20:35]
	v_exp_f32_e32 v106, v106
	v_exp_f32_e32 v107, v107
	v_mfma_f32_32x32x16_bf16 v[4:19], v[238:241], v[92:95], v[4:19]
	v_exp_f32_e32 v108, v108
	v_exp_f32_e32 v109, v109
	ds_read_b64_tr_b16 v[226:227], v182 offset:32768
	ds_read_b64_tr_b16 v[228:229], v182 offset:35328
	ds_read_b64_tr_b16 v[230:231], v182 offset:32832
	ds_read_b64_tr_b16 v[232:233], v182 offset:35392
	ds_read_b64_tr_b16 v[234:235], v182 offset:32896
	ds_read_b64_tr_b16 v[236:237], v182 offset:35456
	ds_read_b64_tr_b16 v[238:239], v182 offset:32960
	ds_read_b64_tr_b16 v[240:241], v182 offset:35520
	v_mfma_f32_32x32x16_bf16 v[68:83], v[116:119], v[92:95], v[68:83]
	v_cvt_pk_bf16_f32 v100, v100, v101
	v_cvt_pk_bf16_f32 v101, v102, v103
	v_cvt_pk_bf16_f32 v102, v104, v105
	v_cvt_pk_bf16_f32 v103, v106, v107
	s_nop 0
	s_waitcnt lgkmcnt(8)
	v_mfma_f32_32x32x16_bf16 v[52:67], v[210:213], v[100:103], v[52:67]
	v_exp_f32_e32 v110, v110
	v_exp_f32_e32 v111, v111
	v_mfma_f32_32x32x16_bf16 v[36:51], v[214:217], v[100:103], v[36:51]
	v_exp_f32_e32 v112, v112
	v_exp_f32_e32 v113, v113
	v_mfma_f32_32x32x16_bf16 v[20:35], v[218:221], v[100:103], v[20:35]
	v_exp_f32_e32 v114, v114
	v_exp_f32_e32 v115, v115
	v_mfma_f32_32x32x16_bf16 v[4:19], v[222:225], v[100:103], v[4:19]
	v_mfma_f32_32x32x16_bf16 v[68:83], v[116:119], v[100:103], v[68:83]
	v_cvt_pk_bf16_f32 v108, v108, v109
	v_cvt_pk_bf16_f32 v109, v110, v111
	v_cvt_pk_bf16_f32 v110, v112, v113
	v_cvt_pk_bf16_f32 v111, v114, v115
	s_nop 0
	s_waitcnt lgkmcnt(0)
	v_mfma_f32_32x32x16_bf16 v[52:67], v[226:229], v[108:111], v[52:67]
	v_mfma_f32_32x32x16_bf16 v[36:51], v[230:233], v[108:111], v[36:51]
	v_mfma_f32_32x32x16_bf16 v[20:35], v[234:237], v[108:111], v[20:35]
	v_mfma_f32_32x32x16_bf16 v[4:19], v[238:241], v[108:111], v[4:19]
	v_mfma_f32_32x32x16_bf16 v[68:83], v[116:119], v[108:111], v[68:83]

; DI f32x16 mfma32(bf16x8 a, bf16x8 b, f32x16 c) { return __builtin_amdgcn_mfma_f32_32x32x16_bf16(a, b, c, 0, 0, 0); }
; DI int crow(int i, int hh) { return (i & 3) + 8 * (i >> 2) + 4 * hh; }
; #define DLOAD(kt) { DLOAD1(0, kt) DLOAD1(1, kt) }
; DI void diff_item(const Params& p, int l, int qt, int bh, char* smem) {
;     ...
;   for (int kt = 0; kt < nkt; ++kt) {
;     __syncthreads();
;     DSTORE1(0) DSTORE1(1)
;     __syncthreads();
;     if (kt + 1 < nkt) { DLOAD(kt + 1); }
;     if (kt * 64 > qt * 128 + 32 * st + 31) continue;
;     f32x16 sa[2];
; #pragma unroll
;     for (int k2 = 0; k2 < 2; ++k2) {
; #pragma unroll
;       for (int j = 0; j < 16; ++j) sa[k2][j] = 0.f;
; #pragma unroll
;       for (int s = 0; s < 4; ++s)
;         sa[k2] = mfma32(*(const bf16x8*)(Ks + (32 * k2 + c31) * 272 + (c * 64 + 16 * s + 8 * hh) * 2), qf[s], sa[k2]);
;       sa[k2] = mfma32(onesK, mfrag, sa[k2]);
;     }
;     if (kt >= 2 * qt) {
; #pragma unroll
;       for (int k2 = 0; k2 < 2; ++k2)
; #pragma unroll
;         for (int j = 0; j < 16; ++j)
;           if (kt * 64 + 32 * k2 + crow(j, hh) > qb) sa[k2][j] = -INFINITY;
;     }
.LBB0_579:
	v_add_co_u32_e32 v84, vcc, 0x3f000, v164
	v_add_u32_e32 v180, v162, v160
	v_add_u32_e32 v181, v177, v160
	v_addc_co_u32_e32 v85, vcc, 0, v165, vcc
	s_barrier
	s_waitcnt vmcnt(3)
	ds_write_b128 v179, v[140:143]
	s_waitcnt vmcnt(2)
	ds_write_b128 v180, v[136:139] offset:17408
	s_waitcnt vmcnt(1)
	ds_write_b128 v181, v[144:147]
	s_waitcnt vmcnt(0)
	ds_write_b128 v178, v[148:151] offset:17408
	s_waitcnt lgkmcnt(0)
	s_barrier
	global_load_dwordx4 v[140:143], v[164:165], off
	global_load_dwordx4 v[136:139], v[164:165], off offset:1024
	global_load_dwordx4 v[144:147], v[84:85], off offset:1024
	global_load_dwordx4 v[148:151], v[84:85], off offset:2048
	v_cmp_le_u32_e32 vcc, s5, v173
	s_and_saveexec_b64 s[2:3], vcc
	s_cbranch_execz .LBB0_578
	v_add_u32_e32 v186, v176, v175
	ds_read_b128 v[210:213], v186
	ds_read_b128 v[214:217], v186 offset:32
	ds_read_b128 v[218:221], v186 offset:64
	ds_read_b128 v[222:225], v186 offset:96
	ds_read_b128 v[226:229], v186 offset:8704
	ds_read_b128 v[230:233], v186 offset:8736
	ds_read_b128 v[234:237], v186 offset:8768
	ds_read_b128 v[238:241], v186 offset:8800
	s_cmp_lt_u32 s8, s6
	s_waitcnt lgkmcnt(7)
	v_mfma_f32_32x32x16_bf16 v[84:99], v[210:213], v[132:135], 0
	s_waitcnt lgkmcnt(6)
	v_mfma_f32_32x32x16_bf16 v[84:99], v[214:217], v[128:131], v[84:99]
	s_waitcnt lgkmcnt(5)
	v_mfma_f32_32x32x16_bf16 v[84:99], v[218:221], v[124:127], v[84:99]
	s_waitcnt lgkmcnt(4)
	v_mfma_f32_32x32x16_bf16 v[84:99], v[222:225], v[120:123], v[84:99]
	s_waitcnt lgkmcnt(3)
	v_mfma_f32_32x32x16_bf16 v[100:115], v[226:229], v[132:135], 0
	s_waitcnt lgkmcnt(2)
	v_mfma_f32_32x32x16_bf16 v[100:115], v[230:233], v[128:131], v[100:115]
	s_waitcnt lgkmcnt(1)
	v_mfma_f32_32x32x16_bf16 v[100:115], v[234:237], v[124:127], v[100:115]
	s_waitcnt lgkmcnt(0)
	v_mfma_f32_32x32x16_bf16 v[100:115], v[238:241], v[120:123], v[100:115]
	v_mfma_f32_32x32x16_bf16 v[84:99], v[0:3], v[152:155], v[84:99]
	v_mfma_f32_32x32x16_bf16 v[100:115], v[0:3], v[152:155], v[100:115]
	v_add_u32_e32 v182, v168, v169
	ds_read_b64_tr_b16 v[210:211], v182 offset:17408
	ds_read_b64_tr_b16 v[212:213], v182 offset:19968
	ds_read_b64_tr_b16 v[214:215], v182 offset:17472
	ds_read_b64_tr_b16 v[216:217], v182 offset:20032
	ds_read_b64_tr_b16 v[218:219], v182 offset:17536
	ds_read_b64_tr_b16 v[220:221], v182 offset:20096
	ds_read_b64_tr_b16 v[222:223], v182 offset:17600
	ds_read_b64_tr_b16 v[224:225], v182 offset:20160
	s_cbranch_scc1 .LBB0_582
	v_add_u32_e32 v182, s5, v159
	v_cmp_gt_u32_e32 vcc, v182, v156
	s_nop 1
	v_cndmask_b32_e32 v183, v84, v205, vcc
	v_cmp_lt_u32_e32 vcc, v182, v156
	s_nop 1
	v_cndmask_b32_e32 v84, v183, v84, vcc
	v_add_u32_e32 v183, 2, v182
	v_cndmask_b32_e32 v85, v205, v85, vcc
	v_cmp_le_u32_e32 vcc, v183, v156
	v_add_u32_e32 v183, 3, v182
	s_nop 0
	v_cndmask_b32_e32 v86, v205, v86, vcc
	v_cmp_le_u32_e32 vcc, v183, v156
	v_add_u32_e32 v183, 8, v182
	s_nop 0
	v_cndmask_b32_e32 v87, v205, v87, vcc
	v_cmp_le_u32_e32 vcc, v183, v156
	v_add_u32_e32 v183, 9, v182
	s_nop 0
	v_cndmask_b32_e32 v88, v205, v88, vcc
	v_cmp_le_u32_e32 vcc, v183, v156
	v_add_u32_e32 v183, 10, v182
	s_nop 0
	v_cndmask_b32_e32 v89, v205, v89, vcc
	v_cmp_le_u32_e32 vcc, v183, v156
	v_add_u32_e32 v183, 11, v182
	s_nop 0
	v_cndmask_b32_e32 v90, v205, v90, vcc
	v_cmp_le_u32_e32 vcc, v183, v156
	v_add_u32_e32 v183, 16, v182
	s_nop 0
	v_cndmask_b32_e32 v91, v205, v91, vcc
	v_cmp_le_u32_e32 vcc, v183, v156
	v_add_u32_e32 v183, 17, v182
	s_nop 0
	v_cndmask_b32_e32 v92, v205, v92, vcc
	v_cmp_le_u32_e32 vcc, v183, v156
	v_add_u32_e32 v183, 18, v182
	s_nop 0
	v_cndmask_b32_e32 v93, v205, v93, vcc
	v_cmp_le_u32_e32 vcc, v183, v156
	v_add_u32_e32 v183, 19, v182
	s_nop 0
	v_cndmask_b32_e32 v94, v205, v94, vcc
	v_cmp_le_u32_e32 vcc, v183, v156
	v_add_u32_e32 v183, 24, v182
	s_nop 0
	v_cndmask_b32_e32 v95, v205, v95, vcc
	v_cmp_le_u32_e32 vcc, v183, v156
	v_add_u32_e32 v183, 25, v182
	s_nop 0
	v_cndmask_b32_e32 v96, v205, v96, vcc
	v_cmp_le_u32_e32 vcc, v183, v156
	v_add_u32_e32 v183, 26, v182
	s_nop 0
	v_cndmask_b32_e32 v97, v205, v97, vcc
	v_cmp_le_u32_e32 vcc, v183, v156
	v_add_u32_e32 v183, 27, v182
	s_nop 0
	v_cndmask_b32_e32 v98, v205, v98, vcc
	v_cmp_le_u32_e32 vcc, v183, v156
	v_add_u32_e32 v183, 32, v182
	s_nop 0
	v_cndmask_b32_e32 v99, v205, v99, vcc
	v_cmp_le_u32_e32 vcc, v183, v156
	v_add_u32_e32 v183, 33, v182
	s_nop 0
	v_cndmask_b32_e32 v100, v205, v100, vcc
	v_cmp_le_u32_e32 vcc, v183, v156
	v_add_u32_e32 v183, 34, v182
	s_nop 0
	v_cndmask_b32_e32 v101, v205, v101, vcc
	v_cmp_le_u32_e32 vcc, v183, v156
	v_add_u32_e32 v183, 35, v182
	s_nop 0
	v_cndmask_b32_e32 v102, v205, v102, vcc
	v_cmp_le_u32_e32 vcc, v183, v156
	v_add_u32_e32 v183, 40, v182
	s_nop 0
	v_cndmask_b32_e32 v103, v205, v103, vcc
	v_cmp_le_u32_e32 vcc, v183, v156
	v_add_u32_e32 v183, 41, v182
	s_nop 0
	v_cndmask_b32_e32 v104, v205, v104, vcc
	v_cmp_le_u32_e32 vcc, v183, v156
	v_add_u32_e32 v183, 42, v182
	s_nop 0
	v_cndmask_b32_e32 v105, v205, v105, vcc
	v_cmp_le_u32_e32 vcc, v183, v156
	v_add_u32_e32 v183, 43, v182
	s_nop 0
	v_cndmask_b32_e32 v106, v205, v106, vcc
	v_cmp_le_u32_e32 vcc, v183, v156
	v_add_u32_e32 v183, 48, v182
	s_nop 0
	v_cndmask_b32_e32 v107, v205, v107, vcc
	v_cmp_le_u32_e32 vcc, v183, v156
	v_add_u32_e32 v183, 49, v182
	s_nop 0
	v_cndmask_b32_e32 v108, v205, v108, vcc
	v_cmp_le_u32_e32 vcc, v183, v156
	v_add_u32_e32 v183, 50, v182
	s_nop 0
	v_cndmask_b32_e32 v109, v205, v109, vcc
	v_cmp_le_u32_e32 vcc, v183, v156
	v_add_u32_e32 v183, 51, v182
	s_nop 0
	v_cndmask_b32_e32 v110, v205, v110, vcc
	v_cmp_le_u32_e32 vcc, v183, v156
	v_add_u32_e32 v183, 56, v182
	s_nop 0
	v_cndmask_b32_e32 v111, v205, v111, vcc
	v_cmp_le_u32_e32 vcc, v183, v156
	v_add_u32_e32 v183, 57, v182
	s_nop 0
	v_cndmask_b32_e32 v112, v205, v112, vcc
	v_cmp_le_u32_e32 vcc, v183, v156
	v_add_u32_e32 v183, 58, v182
	v_add_u32_e32 v182, 59, v182
	v_cndmask_b32_e32 v113, v205, v113, vcc
	v_cmp_le_u32_e32 vcc, v183, v156
	s_nop 1
	v_cndmask_b32_e32 v114, v205, v114, vcc
	v_cmp_le_u32_e32 vcc, v182, v156
	s_nop 1
	v_cndmask_b32_e32 v115, v205, v115, vcc
; DI float bf2f(u16 h) { return __uint_as_float(((u32)h) << 16); }
; DI void diff_item(const Params& p, int l, int qt, int bh, char* smem) {
;     ...
;     float tmax = sa[0][0];
; #pragma unroll
;     for (int k2 = 0; k2 < 2; ++k2)
; #pragma unroll
;       for (int j = 0; j < 16; ++j) tmax = fmaxf(tmax, sa[k2][j]);
;     tmax = xhalf_max(tmax);
;     if (__any(tmax > 8.f)) {
;       const float mnew = bf2f(f2bf(mrun + fmaxf(tmax, 0.f)));
;       const float delta = mnew - mrun;
;       const float alpha = __builtin_amdgcn_exp2f(-delta);
;       mrun = mnew;
;       {
;         const short mb = (hh == 0) ? (short)f2bf(-mnew) : (short)0;
;         mfrag = bf16x8{mb, 0, 0, 0, 0, 0, 0, 0};
;       }
; #pragma unroll
;       for (int k2 = 0; k2 < 2; ++k2)
; #pragma unroll
;         for (int j = 0; j < 16; ++j) sa[k2][j] -= delta;
; #pragma unroll
;       for (int j = 0; j < 16; ++j) Lacc[j] *= alpha;
; #pragma unroll
;       for (int i = 0; i < 4; ++i)
; #pragma unroll
;         for (int j = 0; j < 16; ++j) O[i][j] *= alpha;
;     }
.LBB0_582:
	s_nop 1
	v_max_f32_e32 v182, v85, v85
	v_max_f32_e32 v183, v84, v84
	v_max_f32_e32 v182, v183, v182
	v_max3_f32 v182, v182, v86, v87
	v_max3_f32 v182, v182, v88, v89
	v_max3_f32 v182, v182, v90, v91
	v_max3_f32 v182, v182, v92, v93
	v_max3_f32 v182, v182, v94, v95
	v_max3_f32 v182, v182, v96, v97
	v_max3_f32 v182, v182, v98, v99
	v_max3_f32 v182, v182, v100, v101
	v_max3_f32 v182, v182, v102, v103
	v_max3_f32 v182, v182, v104, v105
	v_max3_f32 v182, v182, v106, v107
	v_max3_f32 v182, v182, v108, v109
	v_max3_f32 v182, v182, v110, v111
	v_max3_f32 v182, v182, v112, v113
	v_max3_f32 v182, v182, v114, v115
	v_mov_b32_e32 v183, v182
	s_nop 1
	v_permlane32_swap_b32_e32 v182, v183
	v_max_f32_e32 v183, v183, v183
	v_max_f32_e32 v182, v182, v182
	v_max_f32_e32 v182, v182, v183
	v_cmp_lt_f32_e32 vcc, s9, v182
	s_cbranch_vccz .LBB0_577
	v_max_f32_e32 v152, v182, v182
	v_max_f32_e32 v152, 0, v152
	v_add_f32_e32 v152, v161, v152
	v_cvt_pk_bf16_f32 v152, v152, s0
	v_lshlrev_b32_e32 v182, 16, v152
	v_sub_f32_e32 v152, v182, v161
	v_exp_f32_e64 v154, -v152
	v_cvt_pk_bf16_f32 v153, -v182, s0
	v_cndmask_b32_e64 v153, 0, v153, s[0:1]
	v_pk_add_f32 v[84:85], v[84:85], v[152:153] op_sel_hi:[1,0] neg_lo:[0,1] neg_hi:[0,1]
	v_pk_add_f32 v[86:87], v[86:87], v[152:153] op_sel_hi:[1,0] neg_lo:[0,1] neg_hi:[0,1]
	v_pk_add_f32 v[88:89], v[88:89], v[152:153] op_sel_hi:[1,0] neg_lo:[0,1] neg_hi:[0,1]
	v_pk_add_f32 v[90:91], v[90:91], v[152:153] op_sel_hi:[1,0] neg_lo:[0,1] neg_hi:[0,1]
	v_pk_add_f32 v[92:93], v[92:93], v[152:153] op_sel_hi:[1,0] neg_lo:[0,1] neg_hi:[0,1]
	v_pk_add_f32 v[94:95], v[94:95], v[152:153] op_sel_hi:[1,0] neg_lo:[0,1] neg_hi:[0,1]
	v_pk_add_f32 v[96:97], v[96:97], v[152:153] op_sel_hi:[1,0] neg_lo:[0,1] neg_hi:[0,1]
	v_pk_add_f32 v[98:99], v[98:99], v[152:153] op_sel_hi:[1,0] neg_lo:[0,1] neg_hi:[0,1]
	v_pk_add_f32 v[100:101], v[100:101], v[152:153] op_sel_hi:[1,0] neg_lo:[0,1] neg_hi:[0,1]
	v_pk_add_f32 v[102:103], v[102:103], v[152:153] op_sel_hi:[1,0] neg_lo:[0,1] neg_hi:[0,1]
	v_pk_add_f32 v[104:105], v[104:105], v[152:153] op_sel_hi:[1,0] neg_lo:[0,1] neg_hi:[0,1]
	v_pk_add_f32 v[106:107], v[106:107], v[152:153] op_sel_hi:[1,0] neg_lo:[0,1] neg_hi:[0,1]
	v_pk_add_f32 v[108:109], v[108:109], v[152:153] op_sel_hi:[1,0] neg_lo:[0,1] neg_hi:[0,1]
	v_pk_add_f32 v[110:111], v[110:111], v[152:153] op_sel_hi:[1,0] neg_lo:[0,1] neg_hi:[0,1]
	v_pk_add_f32 v[112:113], v[112:113], v[152:153] op_sel_hi:[1,0] neg_lo:[0,1] neg_hi:[0,1]
	v_pk_add_f32 v[114:115], v[114:115], v[152:153] op_sel_hi:[1,0] neg_lo:[0,1] neg_hi:[0,1]
	v_pk_mul_f32 v[66:67], v[66:67], v[154:155] op_sel_hi:[1,0]
	v_pk_mul_f32 v[64:65], v[64:65], v[154:155] op_sel_hi:[1,0]
	v_pk_mul_f32 v[62:63], v[62:63], v[154:155] op_sel_hi:[1,0]
	v_pk_mul_f32 v[60:61], v[60:61], v[154:155] op_sel_hi:[1,0]
	v_pk_mul_f32 v[58:59], v[58:59], v[154:155] op_sel_hi:[1,0]
	v_pk_mul_f32 v[56:57], v[56:57], v[154:155] op_sel_hi:[1,0]
	v_pk_mul_f32 v[54:55], v[54:55], v[154:155] op_sel_hi:[1,0]
	v_pk_mul_f32 v[52:53], v[52:53], v[154:155] op_sel_hi:[1,0]
	v_pk_mul_f32 v[50:51], v[50:51], v[154:155] op_sel_hi:[1,0]
	v_pk_mul_f32 v[48:49], v[48:49], v[154:155] op_sel_hi:[1,0]
	v_pk_mul_f32 v[46:47], v[46:47], v[154:155] op_sel_hi:[1,0]
	v_pk_mul_f32 v[44:45], v[44:45], v[154:155] op_sel_hi:[1,0]
	v_pk_mul_f32 v[42:43], v[42:43], v[154:155] op_sel_hi:[1,0]
	v_pk_mul_f32 v[40:41], v[40:41], v[154:155] op_sel_hi:[1,0]
	v_pk_mul_f32 v[38:39], v[38:39], v[154:155] op_sel_hi:[1,0]
	v_pk_mul_f32 v[36:37], v[36:37], v[154:155] op_sel_hi:[1,0]
	v_pk_mul_f32 v[34:35], v[34:35], v[154:155] op_sel_hi:[1,0]
	v_pk_mul_f32 v[32:33], v[32:33], v[154:155] op_sel_hi:[1,0]
	v_pk_mul_f32 v[30:31], v[30:31], v[154:155] op_sel_hi:[1,0]
	v_pk_mul_f32 v[28:29], v[28:29], v[154:155] op_sel_hi:[1,0]
	v_pk_mul_f32 v[26:27], v[26:27], v[154:155] op_sel_hi:[1,0]
	v_pk_mul_f32 v[24:25], v[24:25], v[154:155] op_sel_hi:[1,0]
	v_pk_mul_f32 v[22:23], v[22:23], v[154:155] op_sel_hi:[1,0]
	v_pk_mul_f32 v[20:21], v[20:21], v[154:155] op_sel_hi:[1,0]
	v_pk_mul_f32 v[18:19], v[18:19], v[154:155] op_sel_hi:[1,0]
	v_pk_mul_f32 v[16:17], v[16:17], v[154:155] op_sel_hi:[1,0]
	v_pk_mul_f32 v[14:15], v[14:15], v[154:155] op_sel_hi:[1,0]
	v_pk_mul_f32 v[12:13], v[12:13], v[154:155] op_sel_hi:[1,0]
	v_pk_mul_f32 v[10:11], v[10:11], v[154:155] op_sel_hi:[1,0]
	v_pk_mul_f32 v[8:9], v[8:9], v[154:155] op_sel_hi:[1,0]
	v_pk_mul_f32 v[6:7], v[6:7], v[154:155] op_sel_hi:[1,0]
	v_pk_mul_f32 v[4:5], v[4:5], v[154:155] op_sel_hi:[1,0]
	v_pk_mul_f32 v[82:83], v[82:83], v[154:155] op_sel_hi:[1,0]
	v_pk_mul_f32 v[80:81], v[80:81], v[154:155] op_sel_hi:[1,0]
	v_pk_mul_f32 v[78:79], v[78:79], v[154:155] op_sel_hi:[1,0]
	v_pk_mul_f32 v[76:77], v[76:77], v[154:155] op_sel_hi:[1,0]
	v_pk_mul_f32 v[74:75], v[74:75], v[154:155] op_sel_hi:[1,0]
	v_pk_mul_f32 v[72:73], v[72:73], v[154:155] op_sel_hi:[1,0]
	v_pk_mul_f32 v[70:71], v[70:71], v[154:155] op_sel_hi:[1,0]
	v_pk_mul_f32 v[68:69], v[68:69], v[154:155] op_sel_hi:[1,0]
	v_and_b32_e32 v152, 0xffff, v153
	v_mov_b32_e32 v153, 0
	v_mov_b32_e32 v154, 0
	v_mov_b32_e32 v155, 0
	v_mov_b32_e32 v161, v182
	s_branch .LBB0_577

; DI int lbid() { int b = blockIdx.x; asm volatile("" : "+s"(b)); return b; }
; DI int lgdim() { int b = gridDim.x; asm volatile("" : "+s"(b)); return b; }
; DI int ltid() { int t = threadIdx.x; asm volatile("" : "+v"(t)); return t; }
; #define GLOAD(kt) { GL1(0, kt) GL1(1, kt) GL1(2, kt) GL1(3, kt) }
; #define SSTORE(buf)                              \
;   {                                              \
;     char* as_ = smem + (buf) * BUF;              \
;     char* bs_ = as_ + ASZ;                       \
;     SS1(0) SS1(1) SS1(2) SS1(3)                  \
;   }
; template <int MT, int NT>
; DI void gemm_core(const u16* __restrict__ A, int lda, const u16* __restrict__ B, int ldb, int K,
;                   f32x4 (&acc)[MT][NT], char* smem) {
;   constexpr int BM = 64 * MT, BN = 32 * NT;
;   constexpr int ASZ = BM * 128, BSZ = BN * 128, BUF = ASZ + BSZ;
;   constexpr int NA = BM / 64, NB = BN / 64;
;   const int tid = ltid(), l = tid & 63, w = tid >> 6, wm = w >> 1, wn = w & 1;
;   const int fr = l & 15, fq = l >> 4;
;   uint4 ra0, ra1, ra2, ra3, rb0, rb1, rb2, rb3;
;   const int nk = K >> 6;
;   const int srow = tid >> 3, sch = tid & 7;
;   const int ssw = sch ^ ((srow >> 1) & 7);
;   const int fsw = (fr >> 1) & 7;
;     ...
;   GLOAD(0);
;   SSTORE(0);
;   GLOAD(((1 < nk) ? 1 : 0));
; DI bool next_tile(int it, int RT, int CT, int PR, int PCc, int& rt, int& ct) {
;   const int bid = lbid(), x = bid & 7, j = bid >> 3, J = lgdim() >> 3;
;   const int u = j + it * J;
;   const int pcols = CT / PCc, npatch = (RT / PR) * pcols;
;   const int pid = (u >> 6) * 8 + x;
;   if (pid >= npatch) return false;
;   const int w = u & 63, pr = pid / pcols, pc = pid - pr * pcols;
;   rt = pr * PR + w / PCc;
;   ct = pc * PCc + w % PCc;
;   return true;
; }
.LBB0_711:
	s_mov_b32 s0, s56
	v_readlane_b32 s5, v252, 23
	s_ashr_i32 s5, s5, 3
	s_and_b32 s1, s0, 7
	s_ashr_i32 s0, s0, 3
	s_mul_i32 s5, s5, s4
	s_add_i32 s5, s5, s0
	s_ashr_i32 s0, s5, 3
	s_and_b32 s0, s0, -8
	s_or_b32 s6, s0, s1
	s_cmp_gt_i32 s6, 7
	s_mov_b64 s[0:1], -1
	s_cbranch_scc1 .LBB0_710
	s_lshl_b32 s1, s5, 6
	s_lshl_b32 s0, s6, 12
	s_and_b32 s1, s1, 0xf00
	s_or_b32 s1, s0, s1
	s_lshl_b32 s0, s5, 8
	s_and_b32 s0, s0, 0x300
	s_mul_i32 s6, s1, 0x880
	s_mul_hi_i32 s5, s1, 0x880
	s_add_u32 s6, s94, s6
	s_addc_u32 s7, s95, s5
	s_mul_i32 s5, s0, 0x880
	s_add_u32 s8, s2, s5
	v_mov_b32_e32 v34, v171
	s_addc_u32 s9, s3, 0
	v_mov_b64_e32 v[26:27], s[6:7]
	v_ashrrev_i32_e32 v35, 3, v34
	v_lshlrev_b32_e32 v36, 4, v34
	v_mov_b64_e32 v[30:31], s[8:9]
	v_add_u32_e32 v37, 64, v35
	v_add_u32_e32 v38, 0x80, v35
	v_add_u32_e32 v39, 0xc0, v35
	v_mad_i64_i32 v[2:3], s[6:7], v35, s59, v[26:27]
	v_and_b32_e32 v0, 0x70, v36
	v_mad_i64_i32 v[6:7], s[6:7], v35, s59, v[30:31]
	v_mad_i64_i32 v[10:11], s[6:7], v37, s59, v[26:27]
	v_mad_i64_i32 v[14:15], s[6:7], v37, s59, v[30:31]
	v_mad_i64_i32 v[18:19], s[6:7], v38, s59, v[26:27]
	v_mad_i64_i32 v[22:23], s[6:7], v38, s59, v[30:31]
	v_mad_i64_i32 v[26:27], s[6:7], v39, s59, v[26:27]
	v_mad_i64_i32 v[30:31], s[6:7], v39, s59, v[30:31]
	s_waitcnt vmcnt(16)
	v_lshl_add_u64 v[162:163], v[2:3], 0, v[0:1]
	v_lshl_add_u64 v[164:165], v[6:7], 0, v[0:1]
	v_lshl_add_u64 v[166:167], v[10:11], 0, v[0:1]
	v_lshl_add_u64 v[168:169], v[14:15], 0, v[0:1]
	v_lshl_add_u64 v[176:177], v[18:19], 0, v[0:1]
	v_lshl_add_u64 v[178:179], v[22:23], 0, v[0:1]
	v_lshl_add_u64 v[180:181], v[26:27], 0, v[0:1]
	s_waitcnt vmcnt(0)
	v_lshl_add_u64 v[182:183], v[30:31], 0, v[0:1]
	global_load_dwordx4 v[2:5], v[162:163], off
	global_load_dwordx4 v[6:9], v[164:165], off
	global_load_dwordx4 v[10:13], v[166:167], off
	global_load_dwordx4 v[14:17], v[168:169], off
	global_load_dwordx4 v[18:21], v[176:177], off
	global_load_dwordx4 v[22:25], v[178:179], off
	global_load_dwordx4 v[26:29], v[180:181], off
	global_load_dwordx4 v[30:33], v[182:183], off
	global_load_dwordx4 v[138:141], v[180:181], off offset:128
	global_load_dwordx4 v[130:133], v[176:177], off offset:128
	global_load_dwordx4 v[118:121], v[166:167], off offset:128
	global_load_dwordx4 v[114:117], v[162:163], off offset:128
	global_load_dwordx4 v[154:157], v[182:183], off offset:128
	global_load_dwordx4 v[142:145], v[178:179], off offset:128
	global_load_dwordx4 v[134:137], v[168:169], off offset:128
	global_load_dwordx4 v[122:125], v[164:165], off offset:128
	v_lshrrev_b32_e32 v40, 4, v34
	v_lshrrev_b32_e32 v42, 1, v34
	v_bfe_u32 v43, v34, 1, 3
	v_and_b32_e32 v44, 15, v34
	v_lshlrev_b32_e32 v45, 1, v34
	v_lshlrev_b32_e32 v0, 7, v35
	v_bitop3_b32 v173, v36, s75, v34 bitop3:0x48
	v_bfe_u32 v41, v34, 4, 2
	v_and_or_b32 v34, v42, s90, v44
	v_and_or_b32 v35, v45, s57, v44
	v_bitop3_b32 v36, v40, v43, 3 bitop3:0x6c
	v_or_b32_e32 v40, v0, v173
	v_lshlrev_b32_e32 v175, 7, v37
	v_lshlrev_b32_e32 v184, 7, v38
	v_lshlrev_b32_e32 v185, 7, v39
	v_lshlrev_b32_e32 v186, 4, v36
	v_lshlrev_b32_e32 v187, 7, v34
	v_lshlrev_b32_e32 v188, 7, v35
	v_or_b32_e32 v34, v175, v173
	v_or_b32_e32 v35, v184, v173
	v_or_b32_e32 v36, v185, v173
	s_mov_b32 s5, 0
	s_mov_b32 s6, 0
	s_waitcnt vmcnt(15)
	ds_write_b128 v40, v[2:5]
	s_waitcnt vmcnt(13)
	ds_write_b128 v34, v[10:13]
	s_waitcnt vmcnt(11)
	ds_write_b128 v35, v[18:21]
	s_waitcnt vmcnt(9)
	ds_write_b128 v36, v[26:29]
	ds_write_b128 v40, v[6:9] offset:32768
	ds_write_b128 v34, v[14:17] offset:32768
	ds_write_b128 v35, v[22:25] offset:32768
	s_waitcnt vmcnt(8)
	ds_write_b128 v36, v[30:33] offset:32768
	v_bitop3_b32 v2, v41, v43, 4 bitop3:0x36
	v_lshlrev_b32_e32 v189, 4, v2
	v_mov_b32_e32 v2, 0
	v_mov_b32_e32 v3, v2
	v_mov_b32_e32 v4, v2
	v_mov_b32_e32 v5, v2
	v_mov_b32_e32 v6, v2
	v_mov_b32_e32 v7, v2
	v_mov_b32_e32 v8, v2
	v_mov_b32_e32 v9, v2
	v_mov_b32_e32 v10, v2
	v_mov_b32_e32 v11, v2
	v_mov_b32_e32 v12, v2
	v_mov_b32_e32 v13, v2
	v_mov_b32_e32 v14, v2
	v_mov_b32_e32 v15, v2
	v_mov_b32_e32 v16, v2
	v_mov_b32_e32 v17, v2
	v_mov_b32_e32 v18, v2
	v_mov_b32_e32 v19, v2
	v_mov_b32_e32 v20, v2
	v_mov_b32_e32 v21, v2
	v_mov_b32_e32 v22, v2
	v_mov_b32_e32 v23, v2
	v_mov_b32_e32 v24, v2
	v_mov_b32_e32 v25, v2
	v_mov_b32_e32 v26, v2
	v_mov_b32_e32 v27, v2
	v_mov_b32_e32 v28, v2
	v_mov_b32_e32 v29, v2
	v_mov_b32_e32 v30, v2
	v_mov_b32_e32 v31, v2
	v_mov_b32_e32 v32, v2
	v_mov_b32_e32 v33, v2
	v_mov_b32_e32 v34, v2
	v_mov_b32_e32 v35, v2
	v_mov_b32_e32 v36, v2
	v_mov_b32_e32 v37, v2
	v_mov_b32_e32 v38, v2
	v_mov_b32_e32 v39, v2
	v_mov_b32_e32 v40, v2
	v_mov_b32_e32 v41, v2
	v_mov_b32_e32 v42, v2
	v_mov_b32_e32 v43, v2
	v_mov_b32_e32 v44, v2
	v_mov_b32_e32 v45, v2
	v_mov_b32_e32 v46, v2
	v_mov_b32_e32 v47, v2
	v_mov_b32_e32 v48, v2
	v_mov_b32_e32 v49, v2
	v_mov_b32_e32 v50, v2
	v_mov_b32_e32 v51, v2
	v_mov_b32_e32 v52, v2
	v_mov_b32_e32 v53, v2
	v_mov_b32_e32 v54, v2
	v_mov_b32_e32 v55, v2
	v_mov_b32_e32 v56, v2
	v_mov_b32_e32 v57, v2
	v_mov_b32_e32 v58, v2
	v_mov_b32_e32 v59, v2
	v_mov_b32_e32 v60, v2
	v_mov_b32_e32 v61, v2
	v_mov_b32_e32 v62, v2
	v_mov_b32_e32 v63, v2
	v_mov_b32_e32 v64, v2
	v_mov_b32_e32 v65, v2
	v_mov_b32_e32 v66, v2
	v_mov_b32_e32 v67, v2
	v_mov_b32_e32 v68, v2
	v_mov_b32_e32 v69, v2
	v_mov_b32_e32 v70, v2
	v_mov_b32_e32 v71, v2
	v_mov_b32_e32 v72, v2
	v_mov_b32_e32 v73, v2
	v_mov_b32_e32 v74, v2
	v_mov_b32_e32 v75, v2
	v_mov_b32_e32 v76, v2
	v_mov_b32_e32 v77, v2
	v_mov_b32_e32 v78, v2
	v_mov_b32_e32 v79, v2
	v_mov_b32_e32 v80, v2
	v_mov_b32_e32 v81, v2
	v_mov_b32_e32 v82, v2
	v_mov_b32_e32 v83, v2
	v_mov_b32_e32 v84, v2
	v_mov_b32_e32 v85, v2
	v_mov_b32_e32 v86, v2
	v_mov_b32_e32 v87, v2
	v_mov_b32_e32 v88, v2
	v_mov_b32_e32 v89, v2
	v_mov_b32_e32 v90, v2
	v_mov_b32_e32 v91, v2
	v_mov_b32_e32 v92, v2
	v_mov_b32_e32 v93, v2
	v_mov_b32_e32 v94, v2
	v_mov_b32_e32 v95, v2
	v_mov_b32_e32 v96, v2
	v_mov_b32_e32 v97, v2
	v_mov_b32_e32 v98, v2
	v_mov_b32_e32 v99, v2
	v_mov_b32_e32 v100, v2
	v_mov_b32_e32 v101, v2
	v_mov_b32_e32 v102, v2
	v_mov_b32_e32 v103, v2
	v_mov_b32_e32 v104, v2
	v_mov_b32_e32 v105, v2
	v_mov_b32_e32 v106, v2
	v_mov_b32_e32 v107, v2
	v_mov_b32_e32 v108, v2
	v_mov_b32_e32 v109, v2
	v_mov_b32_e32 v110, v2
	v_mov_b32_e32 v111, v2
	v_mov_b32_e32 v112, v2
	v_mov_b32_e32 v113, v2
	v_mov_b32_e32 v126, v2
	v_mov_b32_e32 v127, v2
	v_mov_b32_e32 v128, v2
	v_mov_b32_e32 v129, v2
	v_mov_b32_e32 v146, v2
	v_mov_b32_e32 v147, v2
	v_mov_b32_e32 v148, v2
	v_mov_b32_e32 v149, v2
	v_mov_b32_e32 v150, v2
	v_mov_b32_e32 v151, v2
	v_mov_b32_e32 v152, v2
	v_mov_b32_e32 v153, v2
	v_mov_b32_e32 v158, v2
	v_mov_b32_e32 v159, v2
	v_mov_b32_e32 v160, v2
	v_mov_b32_e32 v161, v2
	s_waitcnt lgkmcnt(0)
	s_barrier
; DI f32x4 mfma16(bf16x8 a, bf16x8 b, f32x4 c) { return __builtin_amdgcn_mfma_f32_16x16x32_bf16(a, b, c, 0, 0, 0); }
; #define GLOAD(kt) { GL1(0, kt) GL1(1, kt) GL1(2, kt) GL1(3, kt) }
; #define SSTORE(buf)                              \
;   {                                              \
;     char* as_ = smem + (buf) * BUF;              \
;     char* bs_ = as_ + ASZ;                       \
;     SS1(0) SS1(1) SS1(2) SS1(3)                  \
;   }
; template <int MT, int NT>
; DI void gemm_core(const u16* __restrict__ A, int lda, const u16* __restrict__ B, int ldb, int K,
;                   f32x4 (&acc)[MT][NT], char* smem) {
;     ...
;   for (int kt = 0; kt < nk; ++kt) {
;     __syncthreads();
;     SSTORE((kt + 1) & 1);
;     { const int kn_ = (kt + 2 < nk) ? kt + 2 : nk - 1; GLOAD(kn_); }
;     const char* as = smem + (kt & 1) * BUF;
;     const char* bs = as + ASZ;
; #pragma unroll
;     for (int kk = 0; kk < 2; ++kk) {
;       bf16x8 xf[MT], wf[NT];
; #pragma unroll
;       for (int mi = 0; mi < MT; ++mi)
;         xf[mi] = *(const bf16x8*)(as + (wm * (MT * 16) + mi * 16 + fr) * 128 + (((kk * 4 + fq) ^ fsw) * 16));
; #pragma unroll
;       for (int ni = 0; ni < NT; ++ni)
;         wf[ni] = *(const bf16x8*)(bs + (wn * (NT * 16) + ni * 16 + fr) * 128 + (((kk * 4 + fq) ^ fsw) * 16));
;       __builtin_amdgcn_s_setprio(1);
; #pragma unroll
;       for (int mi = 0; mi < MT; ++mi)
; #pragma unroll
;         for (int ni = 0; ni < NT; ++ni) acc[mi][ni] = mfma16(wf[ni], xf[mi], acc[mi][ni]);
;       __builtin_amdgcn_s_setprio(0);
;     }
;   }
	v_add_u32_e32 v207, v186, v188
	v_add_u32_e32 v206, v186, v187
	ds_read_b128 v[190:193], v206
	ds_read_b128 v[208:211], v206 offset:2048
	ds_read_b128 v[212:215], v206 offset:4096
	ds_read_b128 v[216:219], v206 offset:6144
	ds_read_b128 v[220:223], v207 offset:32768
	ds_read_b128 v[224:227], v207 offset:34816
	ds_read_b128 v[228:231], v207 offset:36864
	ds_read_b128 v[232:235], v207 offset:38912
	ds_read_b128 v[236:239], v207 offset:40960
	ds_read_b128 v[240:243], v207 offset:43008
	ds_read_b128 v[244:247], v207 offset:45056
	ds_read_b128 v[248:251], v207 offset:47104
	s_waitcnt lgkmcnt(0)
.LBB0_713:
	s_add_i32 s8, s5, 0x10000
	s_and_b32 s9, s8, 0x10000
	s_add_i32 s7, s6, 1
	s_min_u32 s6, s6, 13
	s_lshl_b32 s54, s6, 7
	s_and_b32 s5, s5, 0x10000
	v_or_b32_e32 v206, s5, v189
	v_add_u32_e32 v207, v206, v188
	v_add_u32_e32 v206, v206, v187
	v_add3_u32 v170, s9, v0, v173
	s_waitcnt lgkmcnt(10)
	v_mfma_f32_16x16x32_bf16 v[158:161], v[220:223], v[190:193], v[158:161]
	s_waitcnt vmcnt(0)
	ds_write_b128 v170, v[114:117]
	s_waitcnt lgkmcnt(10)
	v_mfma_f32_16x16x32_bf16 v[94:97], v[220:223], v[208:211], v[94:97]
	v_lshl_add_u64 v[114:115], v[162:163], 0, s[54:55]
	global_load_dwordx4 v[114:117], v[114:115], off offset:256
	s_waitcnt lgkmcnt(8)
	v_mfma_f32_16x16x32_bf16 v[62:65], v[220:223], v[212:215], v[62:65]
	ds_write_b128 v170, v[122:125] offset:32768
	s_waitcnt lgkmcnt(3)
	v_mfma_f32_16x16x32_bf16 v[30:33], v[220:223], v[216:219], v[30:33]
	v_lshl_add_u64 v[122:123], v[164:165], 0, s[54:55]
	global_load_dwordx4 v[122:125], v[122:123], off offset:256
	ds_read_b128 v[194:197], v206
	v_mfma_f32_16x16x32_bf16 v[150:153], v[224:227], v[190:193], v[150:153]
	ds_read_b128 v[220:223], v207 offset:32768
	ds_write_b128 v170, v[118:121] offset:8192
	v_mfma_f32_16x16x32_bf16 v[90:93], v[224:227], v[208:211], v[90:93]
	v_lshl_add_u64 v[118:119], v[166:167], 0, s[54:55]
	global_load_dwordx4 v[118:121], v[118:119], off offset:256
	v_mfma_f32_16x16x32_bf16 v[58:61], v[224:227], v[212:215], v[58:61]
	ds_write_b128 v170, v[134:137] offset:40960
	v_mfma_f32_16x16x32_bf16 v[26:29], v[224:227], v[216:219], v[26:29]
	v_lshl_add_u64 v[134:135], v[168:169], 0, s[54:55]
	global_load_dwordx4 v[134:137], v[134:135], off offset:256
	ds_read_b128 v[198:201], v206 offset:2048
	v_mfma_f32_16x16x32_bf16 v[146:149], v[228:231], v[190:193], v[146:149]
	ds_read_b128 v[224:227], v207 offset:34816
	ds_write_b128 v170, v[130:133] offset:16384
	v_mfma_f32_16x16x32_bf16 v[86:89], v[228:231], v[208:211], v[86:89]
	v_lshl_add_u64 v[130:131], v[176:177], 0, s[54:55]
	global_load_dwordx4 v[130:133], v[130:131], off offset:256
	v_mfma_f32_16x16x32_bf16 v[54:57], v[228:231], v[212:215], v[54:57]
	ds_write_b128 v170, v[142:145] offset:49152
	v_mfma_f32_16x16x32_bf16 v[22:25], v[228:231], v[216:219], v[22:25]
	v_lshl_add_u64 v[142:143], v[178:179], 0, s[54:55]
	global_load_dwordx4 v[142:145], v[142:143], off offset:256
	ds_read_b128 v[202:205], v206 offset:4096
	v_mfma_f32_16x16x32_bf16 v[126:129], v[232:235], v[190:193], v[126:129]
	ds_read_b128 v[228:231], v207 offset:36864
	ds_write_b128 v170, v[138:141] offset:24576
	v_mfma_f32_16x16x32_bf16 v[82:85], v[232:235], v[208:211], v[82:85]
	v_lshl_add_u64 v[138:139], v[180:181], 0, s[54:55]
	global_load_dwordx4 v[138:141], v[138:139], off offset:256
	v_mfma_f32_16x16x32_bf16 v[50:53], v[232:235], v[212:215], v[50:53]
	ds_write_b128 v170, v[154:157] offset:57344
	v_mfma_f32_16x16x32_bf16 v[18:21], v[232:235], v[216:219], v[18:21]
	v_lshl_add_u64 v[154:155], v[182:183], 0, s[54:55]
	global_load_dwordx4 v[154:157], v[154:155], off offset:256
	v_mfma_f32_16x16x32_bf16 v[110:113], v[236:239], v[190:193], v[110:113]
	ds_read_b128 v[232:235], v207 offset:38912
	v_mfma_f32_16x16x32_bf16 v[78:81], v[236:239], v[208:211], v[78:81]
	v_mfma_f32_16x16x32_bf16 v[46:49], v[236:239], v[212:215], v[46:49]
	v_mfma_f32_16x16x32_bf16 v[14:17], v[236:239], v[216:219], v[14:17]
	v_mfma_f32_16x16x32_bf16 v[106:109], v[240:243], v[190:193], v[106:109]
	ds_read_b128 v[236:239], v207 offset:40960
	v_mfma_f32_16x16x32_bf16 v[74:77], v[240:243], v[208:211], v[74:77]
	v_mfma_f32_16x16x32_bf16 v[42:45], v[240:243], v[212:215], v[42:45]
	v_mfma_f32_16x16x32_bf16 v[10:13], v[240:243], v[216:219], v[10:13]
	v_mfma_f32_16x16x32_bf16 v[102:105], v[244:247], v[190:193], v[102:105]
	ds_read_b128 v[240:243], v207 offset:43008
	v_mfma_f32_16x16x32_bf16 v[70:73], v[244:247], v[208:211], v[70:73]
	v_mfma_f32_16x16x32_bf16 v[38:41], v[244:247], v[212:215], v[38:41]
	v_mfma_f32_16x16x32_bf16 v[6:9], v[244:247], v[216:219], v[6:9]
	s_waitcnt lgkmcnt(15)
	v_mfma_f32_16x16x32_bf16 v[2:5], v[248:251], v[216:219], v[2:5]
	ds_read_b128 v[244:247], v207 offset:45056
	ds_read_b128 v[216:219], v206 offset:6144
	v_mfma_f32_16x16x32_bf16 v[98:101], v[248:251], v[190:193], v[98:101]
	v_mfma_f32_16x16x32_bf16 v[66:69], v[248:251], v[208:211], v[66:69]
	v_mfma_f32_16x16x32_bf16 v[34:37], v[248:251], v[212:215], v[34:37]
	ds_read_b128 v[248:251], v207 offset:47104
	s_waitcnt lgkmcnt(6)
	s_barrier
;   __device__ __forceinline__ u16* XB() const { return (u16*)(ws + O_XB); }
; DI float bflo(u32 v) { return __uint_as_float(v << 16); }
; DI float bfhi(u32 v) { return __uint_as_float(v & 0xffff0000u); }
; DI f32x4 mfma16(bf16x8 a, bf16x8 b, f32x4 c) { return __builtin_amdgcn_mfma_f32_16x16x32_bf16(a, b, c, 0, 0, 0); }
; #define GLOAD(kt) { GL1(0, kt) GL1(1, kt) GL1(2, kt) GL1(3, kt) }
; #define SSTORE(buf)                              \
;   {                                              \
;     char* as_ = smem + (buf) * BUF;              \
;     char* bs_ = as_ + ASZ;                       \
;     SS1(0) SS1(1) SS1(2) SS1(3)                  \
;   }
; template <int MT, int NT>
; DI void gemm_core(const u16* __restrict__ A, int lda, const u16* __restrict__ B, int ldb, int K,
;                   f32x4 (&acc)[MT][NT], char* smem) {
;     ...
;   for (int kt = 0; kt < nk; ++kt) {
;     __syncthreads();
;     SSTORE((kt + 1) & 1);
;     { const int kn_ = (kt + 2 < nk) ? kt + 2 : nk - 1; GLOAD(kn_); }
;     const char* as = smem + (kt & 1) * BUF;
;     const char* bs = as + ASZ;
; #pragma unroll
;     for (int kk = 0; kk < 2; ++kk) {
;       bf16x8 xf[MT], wf[NT];
; #pragma unroll
;       for (int mi = 0; mi < MT; ++mi)
;         xf[mi] = *(const bf16x8*)(as + (wm * (MT * 16) + mi * 16 + fr) * 128 + (((kk * 4 + fq) ^ fsw) * 16));
; #pragma unroll
;       for (int ni = 0; ni < NT; ++ni)
;         wf[ni] = *(const bf16x8*)(bs + (wn * (NT * 16) + ni * 16 + fr) * 128 + (((kk * 4 + fq) ^ fsw) * 16));
;       __builtin_amdgcn_s_setprio(1);
; #pragma unroll
;       for (int mi = 0; mi < MT; ++mi)
; #pragma unroll
;         for (int ni = 0; ni < NT; ++ni) acc[mi][ni] = mfma16(wf[ni], xf[mi], acc[mi][ni]);
;       __builtin_amdgcn_s_setprio(0);
;     }
;   }
; DI void phase_resgemm(const Params& p, const u16* A, int lda, const u16* W, int ldw, int K, char* smem) {
;     ...
;     EPI_LOOP(4, 8) {
;       const int row = r0 + wm_ * 64 + mi * 16 + fr_, col = c0 + wn_ * 128 + ni * 16 + fq_ * 4;
;       const uint2 xb = *(const uint2*)(p.XB() + (size_t)row * LDX + col);
;       float4 o;
;       o.x = DN_ALPHA * bflo(xb.x) + acc[mi][ni][0]; o.y = DN_ALPHA * bfhi(xb.x) + acc[mi][ni][1];
;       o.z = DN_ALPHA * bflo(xb.y) + acc[mi][ni][2]; o.w = DN_ALPHA * bfhi(xb.y) + acc[mi][ni][3];
;       *(float4*)(p.out + (size_t)row * 1024 + col) = o;
;     }
	v_or_b32_e32 v206, s9, v186
	v_add_u32_e32 v207, v206, v188
	v_add_u32_e32 v206, v206, v187
	v_mfma_f32_16x16x32_bf16 v[158:161], v[220:223], v[194:197], v[158:161]
	v_mfma_f32_16x16x32_bf16 v[94:97], v[220:223], v[198:201], v[94:97]
	v_mfma_f32_16x16x32_bf16 v[62:65], v[220:223], v[202:205], v[62:65]
	s_waitcnt lgkmcnt(1)
	v_mfma_f32_16x16x32_bf16 v[30:33], v[220:223], v[216:219], v[30:33]
	ds_read_b128 v[190:193], v206
	v_mfma_f32_16x16x32_bf16 v[150:153], v[224:227], v[194:197], v[150:153]
	ds_read_b128 v[220:223], v207 offset:32768
	v_mfma_f32_16x16x32_bf16 v[90:93], v[224:227], v[198:201], v[90:93]
	v_mfma_f32_16x16x32_bf16 v[58:61], v[224:227], v[202:205], v[58:61]
	v_mfma_f32_16x16x32_bf16 v[26:29], v[224:227], v[216:219], v[26:29]
	ds_read_b128 v[208:211], v206 offset:2048
	v_mfma_f32_16x16x32_bf16 v[146:149], v[228:231], v[194:197], v[146:149]
	ds_read_b128 v[224:227], v207 offset:34816
	v_mfma_f32_16x16x32_bf16 v[86:89], v[228:231], v[198:201], v[86:89]
	v_mfma_f32_16x16x32_bf16 v[54:57], v[228:231], v[202:205], v[54:57]
	v_mfma_f32_16x16x32_bf16 v[22:25], v[228:231], v[216:219], v[22:25]
	ds_read_b128 v[212:215], v206 offset:4096
	v_mfma_f32_16x16x32_bf16 v[126:129], v[232:235], v[194:197], v[126:129]
	ds_read_b128 v[228:231], v207 offset:36864
	v_mfma_f32_16x16x32_bf16 v[82:85], v[232:235], v[198:201], v[82:85]
	v_mfma_f32_16x16x32_bf16 v[50:53], v[232:235], v[202:205], v[50:53]
	v_mfma_f32_16x16x32_bf16 v[18:21], v[232:235], v[216:219], v[18:21]
	v_mfma_f32_16x16x32_bf16 v[110:113], v[236:239], v[194:197], v[110:113]
	ds_read_b128 v[232:235], v207 offset:38912
	v_mfma_f32_16x16x32_bf16 v[78:81], v[236:239], v[198:201], v[78:81]
	v_mfma_f32_16x16x32_bf16 v[46:49], v[236:239], v[202:205], v[46:49]
	v_mfma_f32_16x16x32_bf16 v[14:17], v[236:239], v[216:219], v[14:17]
	v_mfma_f32_16x16x32_bf16 v[106:109], v[240:243], v[194:197], v[106:109]
	ds_read_b128 v[236:239], v207 offset:40960
	v_mfma_f32_16x16x32_bf16 v[74:77], v[240:243], v[198:201], v[74:77]
	v_mfma_f32_16x16x32_bf16 v[42:45], v[240:243], v[202:205], v[42:45]
	v_mfma_f32_16x16x32_bf16 v[10:13], v[240:243], v[216:219], v[10:13]
	v_mfma_f32_16x16x32_bf16 v[102:105], v[244:247], v[194:197], v[102:105]
	ds_read_b128 v[240:243], v207 offset:43008
	v_mfma_f32_16x16x32_bf16 v[70:73], v[244:247], v[198:201], v[70:73]
	v_mfma_f32_16x16x32_bf16 v[38:41], v[244:247], v[202:205], v[38:41]
	v_mfma_f32_16x16x32_bf16 v[6:9], v[244:247], v[216:219], v[6:9]
	s_waitcnt lgkmcnt(9)
	v_mfma_f32_16x16x32_bf16 v[2:5], v[248:251], v[216:219], v[2:5]
	ds_read_b128 v[244:247], v207 offset:45056
	ds_read_b128 v[216:219], v206 offset:6144
	v_mfma_f32_16x16x32_bf16 v[98:101], v[248:251], v[194:197], v[98:101]
	v_mfma_f32_16x16x32_bf16 v[66:69], v[248:251], v[198:201], v[66:69]
	v_mfma_f32_16x16x32_bf16 v[34:37], v[248:251], v[202:205], v[34:37]
	ds_read_b128 v[248:251], v207 offset:47104
	s_cmp_lg_u32 s7, 16
	s_mov_b32 s5, s8
	s_mov_b32 s6, s7
	s_cbranch_scc1 .LBB0_713
	s_waitcnt vmcnt(0) lgkmcnt(0)
	v_mov_b32_e32 v170, 0x358637bd
	v_mov_b32_e32 v194, 0x25a08
	v_mbcnt_lo_u32_b32 v195, -1, 0
	v_mbcnt_hi_u32_b32 v196, -1, v195
	v_mov_b32_e32 v197, 0x24000
	v_mov_b32_e32 v198, 0x1fa0
	v_mov_b32_e32 v199, 0x41b17218
	v_mov_b32_e32 v200, 0x7e800
	v_mov_b32_e32 v201, 0xfd0
	v_mov_b32_e32 v202, 0x100
	v_mov_b32_e32 v203, 0x200
	v_mov_b32_e32 v204, 0x7f61b1e6
	v_mov_b32_e32 v205, 0xff800000
	v_mov_b32_e32 v206, 0x3f80
	v_mov_b32_e32 v207, 0x1d400
	v_mov_b32_e32 v0, v171
	s_waitcnt vmcnt(7)
	v_mov_b32_e32 v115, v171
	s_barrier
	s_waitcnt vmcnt(5)
	v_mov_b64_e32 v[118:119], s[60:61]
	v_ashrrev_i32_e32 v114, 1, v115
	v_and_b32_e32 v114, 0xffffffc0, v114
	v_add_u32_e32 v114, s1, v114
	v_and_or_b32 v114, v0, 15, v114
	v_lshlrev_b32_e32 v115, 1, v115
	v_lshrrev_b32_e32 v0, 2, v0
	v_and_b32_e32 v115, 0x80, v115
	v_and_b32_e32 v0, 12, v0
	v_or3_b32 v115, v0, v115, s0
	v_mad_i64_i32 v[116:117], s[0:1], v114, s59, v[118:119]
	v_lshlrev_b32_e32 v0, 1, v115
	v_lshl_add_u64 v[124:125], v[116:117], 0, v[0:1]
	global_load_dwordx2 v[120:121], v[124:125], off
	v_lshlrev_b32_e32 v116, 2, v115
	v_ashrrev_i32_e32 v115, 31, v114
	v_lshlrev_b64 v[122:123], 12, v[114:115]
	v_mov_b32_e32 v117, v1
	v_lshl_add_u64 v[122:123], s[86:87], 0, v[122:123]
	s_waitcnt vmcnt(4)
	v_lshl_add_u64 v[130:131], v[122:123], 0, v[116:117]
	s_add_i32 s4, s4, 1
	s_waitcnt vmcnt(0)
	v_lshlrev_b32_e32 v122, 16, v120
	v_and_b32_e32 v123, 0xffff0000, v120
	v_lshlrev_b32_e32 v132, 16, v121
	v_and_b32_e32 v133, 0xffff0000, v121
	v_pk_fma_f32 v[120:121], v[122:123], s[74:75], v[158:159] op_sel_hi:[1,0,1]
	v_pk_fma_f32 v[122:123], v[132:133], s[74:75], v[160:161] op_sel_hi:[1,0,1]
	global_store_dwordx4 v[130:131], v[120:123], off
	global_load_dwordx2 v[120:121], v[124:125], off offset:32
	s_waitcnt vmcnt(0)
	v_lshlrev_b32_e32 v132, 16, v121
	v_lshlrev_b32_e32 v122, 16, v120
	v_and_b32_e32 v123, 0xffff0000, v120
	v_and_b32_e32 v133, 0xffff0000, v121
	v_pk_fma_f32 v[120:121], v[122:123], s[74:75], v[150:151] op_sel_hi:[1,0,1]
	v_pk_fma_f32 v[122:123], v[132:133], s[74:75], v[152:153] op_sel_hi:[1,0,1]
	global_store_dwordx4 v[130:131], v[120:123], off offset:64
	global_load_dwordx2 v[120:121], v[124:125], off offset:64
	s_waitcnt vmcnt(0)
	v_lshlrev_b32_e32 v132, 16, v121
	v_lshlrev_b32_e32 v122, 16, v120
	v_and_b32_e32 v123, 0xffff0000, v120
	v_and_b32_e32 v133, 0xffff0000, v121
	v_pk_fma_f32 v[120:121], v[122:123], s[74:75], v[146:147] op_sel_hi:[1,0,1]
	v_pk_fma_f32 v[122:123], v[132:133], s[74:75], v[148:149] op_sel_hi:[1,0,1]
	global_store_dwordx4 v[130:131], v[120:123], off offset:128
	global_load_dwordx2 v[120:121], v[124:125], off offset:96
	s_waitcnt vmcnt(0)
;   __device__ __forceinline__ u16* XB() const { return (u16*)(ws + O_XB); }
; DI float bflo(u32 v) { return __uint_as_float(v << 16); }
; DI float bfhi(u32 v) { return __uint_as_float(v & 0xffff0000u); }
; #define EPI_LOOP(MT_, NT_)                                                \
;   const int l_ = ltid() & 63, w_ = ltid() >> 6;                           \
;   const int wm_ = w_ >> 1, wn_ = w_ & 1, fr_ = l_ & 15, fq_ = l_ >> 4;    \
;   _Pragma("unroll") for (int mi = 0; mi < MT_; ++mi)                      \
;   _Pragma("unroll") for (int ni = 0; ni < NT_; ++ni)
; DI void phase_resgemm(const Params& p, const u16* A, int lda, const u16* W, int ldw, int K, char* smem) {
;     ...
;     EPI_LOOP(4, 8) {
;       const int row = r0 + wm_ * 64 + mi * 16 + fr_, col = c0 + wn_ * 128 + ni * 16 + fq_ * 4;
;       const uint2 xb = *(const uint2*)(p.XB() + (size_t)row * LDX + col);
;       float4 o;
;       o.x = DN_ALPHA * bflo(xb.x) + acc[mi][ni][0]; o.y = DN_ALPHA * bfhi(xb.x) + acc[mi][ni][1];
;       o.z = DN_ALPHA * bflo(xb.y) + acc[mi][ni][2]; o.w = DN_ALPHA * bfhi(xb.y) + acc[mi][ni][3];
;       *(float4*)(p.out + (size_t)row * 1024 + col) = o;
;     }
	v_lshlrev_b32_e32 v132, 16, v121
	v_lshlrev_b32_e32 v122, 16, v120
	v_and_b32_e32 v123, 0xffff0000, v120
	v_and_b32_e32 v133, 0xffff0000, v121
	v_pk_fma_f32 v[120:121], v[122:123], s[74:75], v[126:127] op_sel_hi:[1,0,1]
	v_pk_fma_f32 v[122:123], v[132:133], s[74:75], v[128:129] op_sel_hi:[1,0,1]
	global_store_dwordx4 v[130:131], v[120:123], off offset:192
	global_load_dwordx2 v[120:121], v[124:125], off offset:128
	s_waitcnt vmcnt(0)
	v_lshlrev_b32_e32 v122, 16, v120
	v_and_b32_e32 v123, 0xffff0000, v120
	v_lshlrev_b32_e32 v120, 16, v121
	v_and_b32_e32 v121, 0xffff0000, v121
	v_pk_fma_f32 v[110:111], v[122:123], s[74:75], v[110:111] op_sel_hi:[1,0,1]
	v_pk_fma_f32 v[112:113], v[120:121], s[74:75], v[112:113] op_sel_hi:[1,0,1]
	global_store_dwordx4 v[130:131], v[110:113], off offset:256
	global_load_dwordx2 v[110:111], v[124:125], off offset:160
	s_waitcnt vmcnt(0)
	v_lshlrev_b32_e32 v112, 16, v110
	v_and_b32_e32 v113, 0xffff0000, v110
	v_lshlrev_b32_e32 v110, 16, v111
	v_and_b32_e32 v111, 0xffff0000, v111
	v_pk_fma_f32 v[106:107], v[112:113], s[74:75], v[106:107] op_sel_hi:[1,0,1]
	v_pk_fma_f32 v[108:109], v[110:111], s[74:75], v[108:109] op_sel_hi:[1,0,1]
	global_store_dwordx4 v[130:131], v[106:109], off offset:320
	global_load_dwordx2 v[106:107], v[124:125], off offset:192
	s_waitcnt vmcnt(0)
	v_lshlrev_b32_e32 v108, 16, v106
	v_and_b32_e32 v109, 0xffff0000, v106
	v_lshlrev_b32_e32 v106, 16, v107
	v_and_b32_e32 v107, 0xffff0000, v107
	v_pk_fma_f32 v[102:103], v[108:109], s[74:75], v[102:103] op_sel_hi:[1,0,1]
	v_pk_fma_f32 v[104:105], v[106:107], s[74:75], v[104:105] op_sel_hi:[1,0,1]
	global_store_dwordx4 v[130:131], v[102:105], off offset:384
	global_load_dwordx2 v[102:103], v[124:125], off offset:224
	s_waitcnt vmcnt(0)
	v_lshlrev_b32_e32 v108, 16, v102
	v_or_b32_e32 v104, 16, v114
	v_and_b32_e32 v109, 0xffff0000, v102
	v_lshlrev_b32_e32 v102, 16, v103
	v_and_b32_e32 v103, 0xffff0000, v103
	v_mad_i64_i32 v[106:107], s[0:1], v104, s59, v[118:119]
	v_pk_fma_f32 v[98:99], v[108:109], s[74:75], v[98:99] op_sel_hi:[1,0,1]
	v_pk_fma_f32 v[100:101], v[102:103], s[74:75], v[100:101] op_sel_hi:[1,0,1]
	v_lshl_add_u64 v[106:107], v[106:107], 0, v[0:1]
	global_store_dwordx4 v[130:131], v[98:101], off offset:448
	global_load_dwordx2 v[98:99], v[106:107], off
	v_ashrrev_i32_e32 v105, 31, v104
	v_lshlrev_b64 v[100:101], 12, v[104:105]
	v_lshl_add_u64 v[100:101], s[86:87], 0, v[100:101]
	v_lshl_add_u64 v[100:101], v[100:101], 0, v[116:117]
	s_waitcnt vmcnt(0)
	v_lshlrev_b32_e32 v102, 16, v98
	v_and_b32_e32 v103, 0xffff0000, v98
	v_lshlrev_b32_e32 v98, 16, v99
	v_and_b32_e32 v99, 0xffff0000, v99
	v_pk_fma_f32 v[94:95], v[102:103], s[74:75], v[94:95] op_sel_hi:[1,0,1]
	v_pk_fma_f32 v[96:97], v[98:99], s[74:75], v[96:97] op_sel_hi:[1,0,1]
	global_store_dwordx4 v[100:101], v[94:97], off
	global_load_dwordx2 v[94:95], v[106:107], off offset:32
	s_waitcnt vmcnt(0)
	v_lshlrev_b32_e32 v96, 16, v94
	v_and_b32_e32 v97, 0xffff0000, v94
	v_lshlrev_b32_e32 v94, 16, v95
	v_and_b32_e32 v95, 0xffff0000, v95
	v_pk_fma_f32 v[90:91], v[96:97], s[74:75], v[90:91] op_sel_hi:[1,0,1]
	v_pk_fma_f32 v[92:93], v[94:95], s[74:75], v[92:93] op_sel_hi:[1,0,1]
	global_store_dwordx4 v[100:101], v[90:93], off offset:64
	global_load_dwordx2 v[90:91], v[106:107], off offset:64
	s_waitcnt vmcnt(0)
	v_lshlrev_b32_e32 v92, 16, v90
	v_and_b32_e32 v93, 0xffff0000, v90
	v_lshlrev_b32_e32 v90, 16, v91
	v_and_b32_e32 v91, 0xffff0000, v91
	v_pk_fma_f32 v[86:87], v[92:93], s[74:75], v[86:87] op_sel_hi:[1,0,1]
	v_pk_fma_f32 v[88:89], v[90:91], s[74:75], v[88:89] op_sel_hi:[1,0,1]
	global_store_dwordx4 v[100:101], v[86:89], off offset:128
	global_load_dwordx2 v[86:87], v[106:107], off offset:96
	s_waitcnt vmcnt(0)
	v_lshlrev_b32_e32 v88, 16, v86
	v_and_b32_e32 v89, 0xffff0000, v86
	v_lshlrev_b32_e32 v86, 16, v87
	v_and_b32_e32 v87, 0xffff0000, v87
	v_pk_fma_f32 v[82:83], v[88:89], s[74:75], v[82:83] op_sel_hi:[1,0,1]
	v_pk_fma_f32 v[84:85], v[86:87], s[74:75], v[84:85] op_sel_hi:[1,0,1]
	global_store_dwordx4 v[100:101], v[82:85], off offset:192
	global_load_dwordx2 v[82:83], v[106:107], off offset:128
	s_waitcnt vmcnt(0)
	v_lshlrev_b32_e32 v84, 16, v82
	v_and_b32_e32 v85, 0xffff0000, v82
	v_lshlrev_b32_e32 v82, 16, v83
	v_and_b32_e32 v83, 0xffff0000, v83
	v_pk_fma_f32 v[78:79], v[84:85], s[74:75], v[78:79] op_sel_hi:[1,0,1]
	v_pk_fma_f32 v[80:81], v[82:83], s[74:75], v[80:81] op_sel_hi:[1,0,1]
	global_store_dwordx4 v[100:101], v[78:81], off offset:256
	global_load_dwordx2 v[78:79], v[106:107], off offset:160
	s_waitcnt vmcnt(0)
	v_lshlrev_b32_e32 v80, 16, v78
	v_and_b32_e32 v81, 0xffff0000, v78
	v_lshlrev_b32_e32 v78, 16, v79
	v_and_b32_e32 v79, 0xffff0000, v79
	v_pk_fma_f32 v[74:75], v[80:81], s[74:75], v[74:75] op_sel_hi:[1,0,1]
	v_pk_fma_f32 v[76:77], v[78:79], s[74:75], v[76:77] op_sel_hi:[1,0,1]
	global_store_dwordx4 v[100:101], v[74:77], off offset:320
	global_load_dwordx2 v[74:75], v[106:107], off offset:192
	s_waitcnt vmcnt(0)
	v_lshlrev_b32_e32 v76, 16, v74
	v_and_b32_e32 v77, 0xffff0000, v74
	v_lshlrev_b32_e32 v74, 16, v75
	v_and_b32_e32 v75, 0xffff0000, v75
	v_pk_fma_f32 v[70:71], v[76:77], s[74:75], v[70:71] op_sel_hi:[1,0,1]
	v_pk_fma_f32 v[72:73], v[74:75], s[74:75], v[72:73] op_sel_hi:[1,0,1]
	global_store_dwordx4 v[100:101], v[70:73], off offset:384
	global_load_dwordx2 v[70:71], v[106:107], off offset:224
	s_waitcnt vmcnt(0)
;   __device__ __forceinline__ u16* XB() const { return (u16*)(ws + O_XB); }
; DI float bflo(u32 v) { return __uint_as_float(v << 16); }
; DI float bfhi(u32 v) { return __uint_as_float(v & 0xffff0000u); }
; #define EPI_LOOP(MT_, NT_)                                                \
;   const int l_ = ltid() & 63, w_ = ltid() >> 6;                           \
;   const int wm_ = w_ >> 1, wn_ = w_ & 1, fr_ = l_ & 15, fq_ = l_ >> 4;    \
;   _Pragma("unroll") for (int mi = 0; mi < MT_; ++mi)                      \
;   _Pragma("unroll") for (int ni = 0; ni < NT_; ++ni)
; DI void phase_resgemm(const Params& p, const u16* A, int lda, const u16* W, int ldw, int K, char* smem) {
;     ...
;     EPI_LOOP(4, 8) {
;       const int row = r0 + wm_ * 64 + mi * 16 + fr_, col = c0 + wn_ * 128 + ni * 16 + fq_ * 4;
;       const uint2 xb = *(const uint2*)(p.XB() + (size_t)row * LDX + col);
;       float4 o;
;       o.x = DN_ALPHA * bflo(xb.x) + acc[mi][ni][0]; o.y = DN_ALPHA * bfhi(xb.x) + acc[mi][ni][1];
;       o.z = DN_ALPHA * bflo(xb.y) + acc[mi][ni][2]; o.w = DN_ALPHA * bfhi(xb.y) + acc[mi][ni][3];
;       *(float4*)(p.out + (size_t)row * 1024 + col) = o;
;     }
	v_lshlrev_b32_e32 v76, 16, v70
	v_or_b32_e32 v72, 32, v114
	v_and_b32_e32 v77, 0xffff0000, v70
	v_lshlrev_b32_e32 v70, 16, v71
	v_and_b32_e32 v71, 0xffff0000, v71
	v_mad_i64_i32 v[74:75], s[0:1], v72, s59, v[118:119]
	v_pk_fma_f32 v[66:67], v[76:77], s[74:75], v[66:67] op_sel_hi:[1,0,1]
	v_pk_fma_f32 v[68:69], v[70:71], s[74:75], v[68:69] op_sel_hi:[1,0,1]
	v_lshl_add_u64 v[74:75], v[74:75], 0, v[0:1]
	global_store_dwordx4 v[100:101], v[66:69], off offset:448
	global_load_dwordx2 v[66:67], v[74:75], off
	v_ashrrev_i32_e32 v73, 31, v72
	v_lshlrev_b64 v[68:69], 12, v[72:73]
	v_lshl_add_u64 v[68:69], s[86:87], 0, v[68:69]
	v_lshl_add_u64 v[68:69], v[68:69], 0, v[116:117]
	s_waitcnt vmcnt(0)
	v_lshlrev_b32_e32 v70, 16, v66
	v_and_b32_e32 v71, 0xffff0000, v66
	v_lshlrev_b32_e32 v66, 16, v67
	v_and_b32_e32 v67, 0xffff0000, v67
	v_pk_fma_f32 v[62:63], v[70:71], s[74:75], v[62:63] op_sel_hi:[1,0,1]
	v_pk_fma_f32 v[64:65], v[66:67], s[74:75], v[64:65] op_sel_hi:[1,0,1]
	global_store_dwordx4 v[68:69], v[62:65], off
	global_load_dwordx2 v[62:63], v[74:75], off offset:32
	s_waitcnt vmcnt(0)
	v_lshlrev_b32_e32 v64, 16, v62
	v_and_b32_e32 v65, 0xffff0000, v62
	v_lshlrev_b32_e32 v62, 16, v63
	v_and_b32_e32 v63, 0xffff0000, v63
	v_pk_fma_f32 v[58:59], v[64:65], s[74:75], v[58:59] op_sel_hi:[1,0,1]
	v_pk_fma_f32 v[60:61], v[62:63], s[74:75], v[60:61] op_sel_hi:[1,0,1]
	global_store_dwordx4 v[68:69], v[58:61], off offset:64
	global_load_dwordx2 v[58:59], v[74:75], off offset:64
	s_waitcnt vmcnt(0)
	v_lshlrev_b32_e32 v60, 16, v58
	v_and_b32_e32 v61, 0xffff0000, v58
	v_lshlrev_b32_e32 v58, 16, v59
	v_and_b32_e32 v59, 0xffff0000, v59
	v_pk_fma_f32 v[54:55], v[60:61], s[74:75], v[54:55] op_sel_hi:[1,0,1]
	v_pk_fma_f32 v[56:57], v[58:59], s[74:75], v[56:57] op_sel_hi:[1,0,1]
	global_store_dwordx4 v[68:69], v[54:57], off offset:128
	global_load_dwordx2 v[54:55], v[74:75], off offset:96
	s_waitcnt vmcnt(0)
	v_lshlrev_b32_e32 v56, 16, v54
	v_and_b32_e32 v57, 0xffff0000, v54
	v_lshlrev_b32_e32 v54, 16, v55
	v_and_b32_e32 v55, 0xffff0000, v55
	v_pk_fma_f32 v[50:51], v[56:57], s[74:75], v[50:51] op_sel_hi:[1,0,1]
	v_pk_fma_f32 v[52:53], v[54:55], s[74:75], v[52:53] op_sel_hi:[1,0,1]
	global_store_dwordx4 v[68:69], v[50:53], off offset:192
	global_load_dwordx2 v[50:51], v[74:75], off offset:128
	s_waitcnt vmcnt(0)
	v_lshlrev_b32_e32 v52, 16, v50
	v_and_b32_e32 v53, 0xffff0000, v50
	v_lshlrev_b32_e32 v50, 16, v51
	v_and_b32_e32 v51, 0xffff0000, v51
	v_pk_fma_f32 v[46:47], v[52:53], s[74:75], v[46:47] op_sel_hi:[1,0,1]
	v_pk_fma_f32 v[48:49], v[50:51], s[74:75], v[48:49] op_sel_hi:[1,0,1]
	global_store_dwordx4 v[68:69], v[46:49], off offset:256
	global_load_dwordx2 v[46:47], v[74:75], off offset:160
	s_waitcnt vmcnt(0)
	v_lshlrev_b32_e32 v48, 16, v46
	v_and_b32_e32 v49, 0xffff0000, v46
	v_lshlrev_b32_e32 v46, 16, v47
	v_and_b32_e32 v47, 0xffff0000, v47
	v_pk_fma_f32 v[42:43], v[48:49], s[74:75], v[42:43] op_sel_hi:[1,0,1]
	v_pk_fma_f32 v[44:45], v[46:47], s[74:75], v[44:45] op_sel_hi:[1,0,1]
	global_store_dwordx4 v[68:69], v[42:45], off offset:320
	global_load_dwordx2 v[42:43], v[74:75], off offset:192
	s_waitcnt vmcnt(0)
	v_lshlrev_b32_e32 v44, 16, v42
	v_and_b32_e32 v45, 0xffff0000, v42
	v_lshlrev_b32_e32 v42, 16, v43
	v_and_b32_e32 v43, 0xffff0000, v43
	v_pk_fma_f32 v[38:39], v[44:45], s[74:75], v[38:39] op_sel_hi:[1,0,1]
	v_pk_fma_f32 v[40:41], v[42:43], s[74:75], v[40:41] op_sel_hi:[1,0,1]
	global_store_dwordx4 v[68:69], v[38:41], off offset:384
	global_load_dwordx2 v[38:39], v[74:75], off offset:224
	s_waitcnt vmcnt(0)
;   __device__ __forceinline__ u16* XB() const { return (u16*)(ws + O_XB); }
; DI float bflo(u32 v) { return __uint_as_float(v << 16); }
; DI float bfhi(u32 v) { return __uint_as_float(v & 0xffff0000u); }
; #define EPI_LOOP(MT_, NT_)                                                \
;   const int l_ = ltid() & 63, w_ = ltid() >> 6;                           \
;   const int wm_ = w_ >> 1, wn_ = w_ & 1, fr_ = l_ & 15, fq_ = l_ >> 4;    \
;   _Pragma("unroll") for (int mi = 0; mi < MT_; ++mi)                      \
;   _Pragma("unroll") for (int ni = 0; ni < NT_; ++ni)
; DI void phase_resgemm(const Params& p, const u16* A, int lda, const u16* W, int ldw, int K, char* smem) {
;     ...
;     EPI_LOOP(4, 8) {
;       const int row = r0 + wm_ * 64 + mi * 16 + fr_, col = c0 + wn_ * 128 + ni * 16 + fq_ * 4;
;       const uint2 xb = *(const uint2*)(p.XB() + (size_t)row * LDX + col);
;       float4 o;
;       o.x = DN_ALPHA * bflo(xb.x) + acc[mi][ni][0]; o.y = DN_ALPHA * bfhi(xb.x) + acc[mi][ni][1];
;       o.z = DN_ALPHA * bflo(xb.y) + acc[mi][ni][2]; o.w = DN_ALPHA * bfhi(xb.y) + acc[mi][ni][3];
;       *(float4*)(p.out + (size_t)row * 1024 + col) = o;
;     }
	v_lshlrev_b32_e32 v44, 16, v38
	v_or_b32_e32 v40, 48, v114
	v_and_b32_e32 v45, 0xffff0000, v38
	v_lshlrev_b32_e32 v38, 16, v39
	v_and_b32_e32 v39, 0xffff0000, v39
	v_mad_i64_i32 v[42:43], s[0:1], v40, s59, v[118:119]
	v_pk_fma_f32 v[34:35], v[44:45], s[74:75], v[34:35] op_sel_hi:[1,0,1]
	v_pk_fma_f32 v[36:37], v[38:39], s[74:75], v[36:37] op_sel_hi:[1,0,1]
	v_lshl_add_u64 v[42:43], v[42:43], 0, v[0:1]
	global_store_dwordx4 v[68:69], v[34:37], off offset:448
	global_load_dwordx2 v[34:35], v[42:43], off
	v_ashrrev_i32_e32 v41, 31, v40
	v_lshlrev_b64 v[36:37], 12, v[40:41]
	v_lshl_add_u64 v[36:37], s[86:87], 0, v[36:37]
	v_lshl_add_u64 v[36:37], v[36:37], 0, v[116:117]
	s_mov_b64 s[0:1], 0
	s_waitcnt vmcnt(0)
	v_lshlrev_b32_e32 v38, 16, v34
	v_and_b32_e32 v39, 0xffff0000, v34
	v_lshlrev_b32_e32 v34, 16, v35
	v_and_b32_e32 v35, 0xffff0000, v35
	v_pk_fma_f32 v[30:31], v[38:39], s[74:75], v[30:31] op_sel_hi:[1,0,1]
	v_pk_fma_f32 v[32:33], v[34:35], s[74:75], v[32:33] op_sel_hi:[1,0,1]
	global_store_dwordx4 v[36:37], v[30:33], off
	global_load_dwordx2 v[30:31], v[42:43], off offset:32
	s_waitcnt vmcnt(0)
	v_lshlrev_b32_e32 v32, 16, v30
	v_and_b32_e32 v33, 0xffff0000, v30
	v_lshlrev_b32_e32 v30, 16, v31
	v_and_b32_e32 v31, 0xffff0000, v31
	v_pk_fma_f32 v[26:27], v[32:33], s[74:75], v[26:27] op_sel_hi:[1,0,1]
	v_pk_fma_f32 v[28:29], v[30:31], s[74:75], v[28:29] op_sel_hi:[1,0,1]
	global_store_dwordx4 v[36:37], v[26:29], off offset:64
	global_load_dwordx2 v[26:27], v[42:43], off offset:64
	s_waitcnt vmcnt(0)
	v_lshlrev_b32_e32 v28, 16, v26
	v_and_b32_e32 v29, 0xffff0000, v26
	v_lshlrev_b32_e32 v26, 16, v27
	v_and_b32_e32 v27, 0xffff0000, v27
	v_pk_fma_f32 v[22:23], v[28:29], s[74:75], v[22:23] op_sel_hi:[1,0,1]
	v_pk_fma_f32 v[24:25], v[26:27], s[74:75], v[24:25] op_sel_hi:[1,0,1]
	global_store_dwordx4 v[36:37], v[22:25], off offset:128
	global_load_dwordx2 v[22:23], v[42:43], off offset:96
	s_waitcnt vmcnt(0)
	v_lshlrev_b32_e32 v24, 16, v22
	v_and_b32_e32 v25, 0xffff0000, v22
	v_lshlrev_b32_e32 v22, 16, v23
	v_and_b32_e32 v23, 0xffff0000, v23
	v_pk_fma_f32 v[18:19], v[24:25], s[74:75], v[18:19] op_sel_hi:[1,0,1]
	v_pk_fma_f32 v[20:21], v[22:23], s[74:75], v[20:21] op_sel_hi:[1,0,1]
	global_store_dwordx4 v[36:37], v[18:21], off offset:192
	global_load_dwordx2 v[18:19], v[42:43], off offset:128
	s_waitcnt vmcnt(0)
	v_lshlrev_b32_e32 v20, 16, v18
	v_and_b32_e32 v21, 0xffff0000, v18
	v_lshlrev_b32_e32 v18, 16, v19
	v_and_b32_e32 v19, 0xffff0000, v19
	v_pk_fma_f32 v[14:15], v[20:21], s[74:75], v[14:15] op_sel_hi:[1,0,1]
	v_pk_fma_f32 v[16:17], v[18:19], s[74:75], v[16:17] op_sel_hi:[1,0,1]
	global_store_dwordx4 v[36:37], v[14:17], off offset:256
	global_load_dwordx2 v[14:15], v[42:43], off offset:160
	s_waitcnt vmcnt(0)
	v_lshlrev_b32_e32 v16, 16, v14
	v_and_b32_e32 v17, 0xffff0000, v14
	v_lshlrev_b32_e32 v14, 16, v15
	v_and_b32_e32 v15, 0xffff0000, v15
	v_pk_fma_f32 v[10:11], v[16:17], s[74:75], v[10:11] op_sel_hi:[1,0,1]
	v_pk_fma_f32 v[12:13], v[14:15], s[74:75], v[12:13] op_sel_hi:[1,0,1]
	global_store_dwordx4 v[36:37], v[10:13], off offset:320
	global_load_dwordx2 v[10:11], v[42:43], off offset:192
	s_waitcnt vmcnt(0)
	v_lshlrev_b32_e32 v12, 16, v10
	v_and_b32_e32 v13, 0xffff0000, v10
	v_lshlrev_b32_e32 v10, 16, v11
	v_and_b32_e32 v11, 0xffff0000, v11
	v_pk_fma_f32 v[6:7], v[12:13], s[74:75], v[6:7] op_sel_hi:[1,0,1]
	v_pk_fma_f32 v[8:9], v[10:11], s[74:75], v[8:9] op_sel_hi:[1,0,1]
	global_store_dwordx4 v[36:37], v[6:9], off offset:384
	global_load_dwordx2 v[6:7], v[42:43], off offset:224
	s_waitcnt vmcnt(0)
	v_lshlrev_b32_e32 v8, 16, v6
	v_and_b32_e32 v9, 0xffff0000, v6
	v_lshlrev_b32_e32 v6, 16, v7
	v_and_b32_e32 v7, 0xffff0000, v7
	v_pk_fma_f32 v[2:3], v[8:9], s[74:75], v[2:3] op_sel_hi:[1,0,1]
	v_pk_fma_f32 v[4:5], v[6:7], s[74:75], v[4:5] op_sel_hi:[1,0,1]
	global_store_dwordx4 v[36:37], v[2:5], off offset:448
	s_branch .LBB0_710

; DI int lbid() { int b = blockIdx.x; asm volatile("" : "+s"(b)); return b; }
; DI int lgdim() { int b = gridDim.x; asm volatile("" : "+s"(b)); return b; }
; DI int ltid() { int t = threadIdx.x; asm volatile("" : "+v"(t)); return t; }
; #define GLOAD(kt) { GL1(0, kt) GL1(1, kt) GL1(2, kt) GL1(3, kt) }
; #define SSTORE(buf)                              \
;   {                                              \
;     char* as_ = smem + (buf) * BUF;              \
;     char* bs_ = as_ + ASZ;                       \
;     SS1(0) SS1(1) SS1(2) SS1(3)                  \
;   }
; template <int MT, int NT>
; DI void gemm_core(const u16* __restrict__ A, int lda, const u16* __restrict__ B, int ldb, int K,
;                   f32x4 (&acc)[MT][NT], char* smem) {
;   constexpr int BM = 64 * MT, BN = 32 * NT;
;   constexpr int ASZ = BM * 128, BSZ = BN * 128, BUF = ASZ + BSZ;
;   constexpr int NA = BM / 64, NB = BN / 64;
;   const int tid = ltid(), l = tid & 63, w = tid >> 6, wm = w >> 1, wn = w & 1;
;   const int fr = l & 15, fq = l >> 4;
;   uint4 ra0, ra1, ra2, ra3, rb0, rb1, rb2, rb3;
;   const int nk = K >> 6;
;   const int srow = tid >> 3, sch = tid & 7;
;   const int ssw = sch ^ ((srow >> 1) & 7);
;   const int fsw = (fr >> 1) & 7;
;     ...
;   GLOAD(0);
;   SSTORE(0);
;   GLOAD(((1 < nk) ? 1 : 0));
; DI bool next_tile(int it, int RT, int CT, int PR, int PCc, int& rt, int& ct) {
;   const int bid = lbid(), x = bid & 7, j = bid >> 3, J = lgdim() >> 3;
;   const int u = j + it * J;
;   const int pcols = CT / PCc, npatch = (RT / PR) * pcols;
;   const int pid = (u >> 6) * 8 + x;
;   if (pid >= npatch) return false;
;   const int w = u & 63, pr = pid / pcols, pc = pid - pr * pcols;
;   rt = pr * PR + w / PCc;
;   ct = pc * PCc + w % PCc;
;   return true;
; }
.LBB0_766:
	s_mov_b32 s0, s56
	v_readlane_b32 s5, v252, 23
	s_ashr_i32 s5, s5, 3
	s_and_b32 s1, s0, 7
	s_ashr_i32 s0, s0, 3
	s_mul_i32 s5, s5, s4
	s_add_i32 s5, s5, s0
	s_ashr_i32 s0, s5, 3
	s_and_b32 s0, s0, -8
	s_or_b32 s6, s0, s1
	s_cmp_gt_i32 s6, 31
	s_mov_b64 s[0:1], -1
	s_cbranch_scc1 .LBB0_765
	s_lshr_b32 s0, s6, 31
	s_add_i32 s0, s6, s0
	s_ashr_i32 s0, s0, 1
	s_lshl_b32 s1, s0, 4
	s_lshl_b32 s6, s6, 3
	s_sub_i32 s1, s6, s1
	s_and_b32 s6, s5, 7
	s_or_b32 s8, s1, s6
	s_lshl_b32 s1, s5, 5
	s_lshl_b32 s0, s0, 11
	s_and_b32 s1, s1, 0x700
	s_or_b32 s1, s0, s1
	s_lshl_b32 s0, s8, 8
	s_mul_i32 s6, s1, 0x880
	s_mul_hi_i32 s5, s1, 0x880
	s_add_u32 s6, s60, s6
	s_addc_u32 s7, s61, s5
	s_mul_i32 s8, s8, 0x88000
	s_mul_hi_i32 s5, s0, 0x880
	s_add_u32 s8, s2, s8
	v_mov_b32_e32 v34, v171
	s_addc_u32 s9, s3, s5
	v_mov_b64_e32 v[26:27], s[6:7]
	v_ashrrev_i32_e32 v35, 3, v34
	v_lshlrev_b32_e32 v36, 4, v34
	v_mov_b64_e32 v[30:31], s[8:9]
	v_add_u32_e32 v37, 64, v35
	v_add_u32_e32 v38, 0x80, v35
	v_add_u32_e32 v39, 0xc0, v35
	v_mad_i64_i32 v[2:3], s[6:7], v35, s59, v[26:27]
	v_and_b32_e32 v0, 0x70, v36
	v_mad_i64_i32 v[6:7], s[6:7], v35, s59, v[30:31]
	v_mad_i64_i32 v[10:11], s[6:7], v37, s59, v[26:27]
	v_mad_i64_i32 v[14:15], s[6:7], v37, s59, v[30:31]
	v_mad_i64_i32 v[18:19], s[6:7], v38, s59, v[26:27]
	v_mad_i64_i32 v[22:23], s[6:7], v38, s59, v[30:31]
	v_mad_i64_i32 v[26:27], s[6:7], v39, s59, v[26:27]
	v_mad_i64_i32 v[30:31], s[6:7], v39, s59, v[30:31]
	s_waitcnt vmcnt(16)
	v_lshl_add_u64 v[162:163], v[2:3], 0, v[0:1]
	v_lshl_add_u64 v[164:165], v[6:7], 0, v[0:1]
	v_lshl_add_u64 v[166:167], v[10:11], 0, v[0:1]
	v_lshl_add_u64 v[168:169], v[14:15], 0, v[0:1]
	v_lshl_add_u64 v[176:177], v[18:19], 0, v[0:1]
	v_lshl_add_u64 v[178:179], v[22:23], 0, v[0:1]
	v_lshl_add_u64 v[180:181], v[26:27], 0, v[0:1]
	s_waitcnt vmcnt(0)
	v_lshl_add_u64 v[182:183], v[30:31], 0, v[0:1]
	global_load_dwordx4 v[2:5], v[162:163], off
	global_load_dwordx4 v[6:9], v[164:165], off
	global_load_dwordx4 v[10:13], v[166:167], off
	global_load_dwordx4 v[14:17], v[168:169], off
	global_load_dwordx4 v[18:21], v[176:177], off
	global_load_dwordx4 v[22:25], v[178:179], off
	global_load_dwordx4 v[26:29], v[180:181], off
	global_load_dwordx4 v[30:33], v[182:183], off
	global_load_dwordx4 v[130:133], v[180:181], off offset:128
	global_load_dwordx4 v[122:125], v[176:177], off offset:128
	global_load_dwordx4 v[114:117], v[166:167], off offset:128
	global_load_dwordx4 v[110:113], v[162:163], off offset:128
	global_load_dwordx4 v[150:153], v[182:183], off offset:128
	global_load_dwordx4 v[134:137], v[178:179], off offset:128
	global_load_dwordx4 v[126:129], v[168:169], off offset:128
	global_load_dwordx4 v[118:121], v[164:165], off offset:128
	v_lshlrev_b32_e32 v0, 7, v35
	v_bitop3_b32 v173, v36, s75, v34 bitop3:0x48
	v_and_b32_e32 v44, 15, v34
	v_lshlrev_b32_e32 v45, 1, v34
	v_or_b32_e32 v35, v0, v173
	v_lshlrev_b32_e32 v175, 7, v37
	v_lshlrev_b32_e32 v184, 7, v38
	v_lshlrev_b32_e32 v185, 7, v39
	v_bfe_u32 v41, v34, 4, 2
	v_bfe_u32 v43, v34, 1, 3
	v_or_b32_e32 v36, v175, v173
	v_or_b32_e32 v37, v184, v173
	v_or_b32_e32 v38, v185, v173
	v_lshrrev_b32_e32 v40, 4, v34
	v_lshrrev_b32_e32 v42, 1, v34
	v_and_or_b32 v34, v42, s90, v44
	v_lshlrev_b32_e32 v187, 7, v34
	s_mov_b32 s5, 0
	s_mov_b32 s6, 0
	s_waitcnt vmcnt(15)
	ds_write_b128 v35, v[2:5]
	s_waitcnt vmcnt(13)
	ds_write_b128 v36, v[10:13]
	s_waitcnt vmcnt(11)
	ds_write_b128 v37, v[18:21]
	s_waitcnt vmcnt(9)
	ds_write_b128 v38, v[26:29]
	ds_write_b128 v35, v[6:9] offset:32768
	ds_write_b128 v36, v[14:17] offset:32768
	ds_write_b128 v37, v[22:25] offset:32768
	s_waitcnt vmcnt(8)
	ds_write_b128 v38, v[30:33] offset:32768
	v_and_or_b32 v2, v45, s57, v44
	v_lshlrev_b32_e32 v188, 7, v2
	v_bitop3_b32 v2, v41, v43, 4 bitop3:0x36
	v_bitop3_b32 v3, v40, v43, 3 bitop3:0x6c
	v_lshlrev_b32_e32 v189, 4, v2
	v_mov_b32_e32 v2, 0
	v_lshlrev_b32_e32 v186, 4, v3
	v_mov_b32_e32 v3, v2
	v_mov_b32_e32 v4, v2
	v_mov_b32_e32 v5, v2
	v_mov_b32_e32 v6, v2
	v_mov_b32_e32 v7, v2
	v_mov_b32_e32 v8, v2
	v_mov_b32_e32 v9, v2
	v_mov_b32_e32 v10, v2
	v_mov_b32_e32 v11, v2
	v_mov_b32_e32 v12, v2
	v_mov_b32_e32 v13, v2
	v_mov_b32_e32 v14, v2
	v_mov_b32_e32 v15, v2
	v_mov_b32_e32 v16, v2
	v_mov_b32_e32 v17, v2
	v_mov_b32_e32 v18, v2
	v_mov_b32_e32 v19, v2
	v_mov_b32_e32 v20, v2
	v_mov_b32_e32 v21, v2
	v_mov_b32_e32 v22, v2
	v_mov_b32_e32 v23, v2
	v_mov_b32_e32 v24, v2
	v_mov_b32_e32 v25, v2
	v_mov_b32_e32 v26, v2
	v_mov_b32_e32 v27, v2
	v_mov_b32_e32 v28, v2
	v_mov_b32_e32 v29, v2
	v_mov_b32_e32 v30, v2
	v_mov_b32_e32 v31, v2
	v_mov_b32_e32 v32, v2
	v_mov_b32_e32 v33, v2
	v_mov_b32_e32 v34, v2
	v_mov_b32_e32 v35, v2
	v_mov_b32_e32 v36, v2
	v_mov_b32_e32 v37, v2
	v_mov_b32_e32 v38, v2
	v_mov_b32_e32 v39, v2
	v_mov_b32_e32 v40, v2
	v_mov_b32_e32 v41, v2
	v_mov_b32_e32 v42, v2
	v_mov_b32_e32 v43, v2
	v_mov_b32_e32 v44, v2
	v_mov_b32_e32 v45, v2
	v_mov_b32_e32 v46, v2
	v_mov_b32_e32 v47, v2
	v_mov_b32_e32 v48, v2
	v_mov_b32_e32 v49, v2
	v_mov_b32_e32 v50, v2
	v_mov_b32_e32 v51, v2
	v_mov_b32_e32 v52, v2
	v_mov_b32_e32 v53, v2
	v_mov_b32_e32 v54, v2
	v_mov_b32_e32 v55, v2
	v_mov_b32_e32 v56, v2
	v_mov_b32_e32 v57, v2
	v_mov_b32_e32 v58, v2
	v_mov_b32_e32 v59, v2
	v_mov_b32_e32 v60, v2
	v_mov_b32_e32 v61, v2
	v_mov_b32_e32 v62, v2
	v_mov_b32_e32 v63, v2
	v_mov_b32_e32 v64, v2
	v_mov_b32_e32 v65, v2
	v_mov_b32_e32 v66, v2
	v_mov_b32_e32 v67, v2
	v_mov_b32_e32 v68, v2
	v_mov_b32_e32 v69, v2
	v_mov_b32_e32 v70, v2
	v_mov_b32_e32 v71, v2
	v_mov_b32_e32 v72, v2
	v_mov_b32_e32 v73, v2
	v_mov_b32_e32 v74, v2
	v_mov_b32_e32 v75, v2
	v_mov_b32_e32 v76, v2
	v_mov_b32_e32 v77, v2
	v_mov_b32_e32 v78, v2
	v_mov_b32_e32 v79, v2
	v_mov_b32_e32 v80, v2
	v_mov_b32_e32 v81, v2
	v_mov_b32_e32 v82, v2
	v_mov_b32_e32 v83, v2
	v_mov_b32_e32 v84, v2
	v_mov_b32_e32 v85, v2
	v_mov_b32_e32 v86, v2
	v_mov_b32_e32 v87, v2
	v_mov_b32_e32 v88, v2
	v_mov_b32_e32 v89, v2
	v_mov_b32_e32 v90, v2
	v_mov_b32_e32 v91, v2
	v_mov_b32_e32 v92, v2
	v_mov_b32_e32 v93, v2
	v_mov_b32_e32 v94, v2
	v_mov_b32_e32 v95, v2
	v_mov_b32_e32 v96, v2
	v_mov_b32_e32 v97, v2
	v_mov_b32_e32 v98, v2
	v_mov_b32_e32 v99, v2
	v_mov_b32_e32 v100, v2
	v_mov_b32_e32 v101, v2
	v_mov_b32_e32 v102, v2
	v_mov_b32_e32 v103, v2
	v_mov_b32_e32 v104, v2
	v_mov_b32_e32 v105, v2
	v_mov_b32_e32 v106, v2
	v_mov_b32_e32 v107, v2
	v_mov_b32_e32 v108, v2
	v_mov_b32_e32 v109, v2
	v_mov_b32_e32 v138, v2
	v_mov_b32_e32 v139, v2
	v_mov_b32_e32 v140, v2
	v_mov_b32_e32 v141, v2
	v_mov_b32_e32 v142, v2
	v_mov_b32_e32 v143, v2
	v_mov_b32_e32 v144, v2
	v_mov_b32_e32 v145, v2
	v_mov_b32_e32 v146, v2
	v_mov_b32_e32 v147, v2
	v_mov_b32_e32 v148, v2
	v_mov_b32_e32 v149, v2
	v_mov_b32_e32 v154, v2
	v_mov_b32_e32 v155, v2
	v_mov_b32_e32 v156, v2
	v_mov_b32_e32 v157, v2
	v_mov_b32_e32 v158, v2
	v_mov_b32_e32 v159, v2
	v_mov_b32_e32 v160, v2
	v_mov_b32_e32 v161, v2
	s_waitcnt lgkmcnt(0)
	s_barrier
; DI f32x4 mfma16(bf16x8 a, bf16x8 b, f32x4 c) { return __builtin_amdgcn_mfma_f32_16x16x32_bf16(a, b, c, 0, 0, 0); }
; #define GLOAD(kt) { GL1(0, kt) GL1(1, kt) GL1(2, kt) GL1(3, kt) }
; #define SSTORE(buf)                              \
;   {                                              \
;     char* as_ = smem + (buf) * BUF;              \
;     char* bs_ = as_ + ASZ;                       \
;     SS1(0) SS1(1) SS1(2) SS1(3)                  \
;   }
; template <int MT, int NT>
; DI void gemm_core(const u16* __restrict__ A, int lda, const u16* __restrict__ B, int ldb, int K,
;                   f32x4 (&acc)[MT][NT], char* smem) {
;     ...
;   for (int kt = 0; kt < nk; ++kt) {
;     __syncthreads();
;     SSTORE((kt + 1) & 1);
;     { const int kn_ = (kt + 2 < nk) ? kt + 2 : nk - 1; GLOAD(kn_); }
;     const char* as = smem + (kt & 1) * BUF;
;     const char* bs = as + ASZ;
; #pragma unroll
;     for (int kk = 0; kk < 2; ++kk) {
;       bf16x8 xf[MT], wf[NT];
; #pragma unroll
;       for (int mi = 0; mi < MT; ++mi)
;         xf[mi] = *(const bf16x8*)(as + (wm * (MT * 16) + mi * 16 + fr) * 128 + (((kk * 4 + fq) ^ fsw) * 16));
; #pragma unroll
;       for (int ni = 0; ni < NT; ++ni)
;         wf[ni] = *(const bf16x8*)(bs + (wn * (NT * 16) + ni * 16 + fr) * 128 + (((kk * 4 + fq) ^ fsw) * 16));
;       __builtin_amdgcn_s_setprio(1);
; #pragma unroll
;       for (int mi = 0; mi < MT; ++mi)
; #pragma unroll
;         for (int ni = 0; ni < NT; ++ni) acc[mi][ni] = mfma16(wf[ni], xf[mi], acc[mi][ni]);
;       __builtin_amdgcn_s_setprio(0);
;     }
;   }
	v_add_u32_e32 v207, v186, v188
	v_add_u32_e32 v206, v186, v187
	ds_read_b128 v[190:193], v206
	ds_read_b128 v[208:211], v206 offset:2048
	ds_read_b128 v[212:215], v206 offset:4096
	ds_read_b128 v[216:219], v206 offset:6144
	ds_read_b128 v[220:223], v207 offset:32768
	ds_read_b128 v[224:227], v207 offset:34816
	ds_read_b128 v[228:231], v207 offset:36864
	ds_read_b128 v[232:235], v207 offset:38912
	ds_read_b128 v[236:239], v207 offset:40960
	ds_read_b128 v[240:243], v207 offset:43008
	ds_read_b128 v[244:247], v207 offset:45056
	ds_read_b128 v[248:251], v207 offset:47104
	s_waitcnt lgkmcnt(0)
.LBB0_768:
	s_add_i32 s8, s5, 0x10000
	s_and_b32 s9, s8, 0x10000
	s_add_i32 s7, s6, 1
	s_min_u32 s6, s6, 13
	s_lshl_b32 s54, s6, 7
	s_and_b32 s5, s5, 0x10000
	v_or_b32_e32 v206, s5, v189
	v_add_u32_e32 v207, v206, v188
	v_add_u32_e32 v206, v206, v187
	v_add3_u32 v170, s9, v0, v173
	s_waitcnt lgkmcnt(10)
	v_mfma_f32_16x16x32_bf16 v[158:161], v[220:223], v[190:193], v[158:161]
	s_waitcnt vmcnt(0)
	ds_write_b128 v170, v[110:113]
	s_waitcnt lgkmcnt(10)
	v_mfma_f32_16x16x32_bf16 v[94:97], v[220:223], v[208:211], v[94:97]
	v_lshl_add_u64 v[110:111], v[162:163], 0, s[54:55]
	global_load_dwordx4 v[110:113], v[110:111], off offset:256
	s_waitcnt lgkmcnt(8)
	v_mfma_f32_16x16x32_bf16 v[62:65], v[220:223], v[212:215], v[62:65]
	ds_write_b128 v170, v[118:121] offset:32768
	s_waitcnt lgkmcnt(3)
	v_mfma_f32_16x16x32_bf16 v[30:33], v[220:223], v[216:219], v[30:33]
	v_lshl_add_u64 v[118:119], v[164:165], 0, s[54:55]
	global_load_dwordx4 v[118:121], v[118:119], off offset:256
	ds_read_b128 v[194:197], v206
	v_mfma_f32_16x16x32_bf16 v[154:157], v[224:227], v[190:193], v[154:157]
	ds_read_b128 v[220:223], v207 offset:32768
	ds_write_b128 v170, v[114:117] offset:8192
	v_mfma_f32_16x16x32_bf16 v[90:93], v[224:227], v[208:211], v[90:93]
	v_lshl_add_u64 v[114:115], v[166:167], 0, s[54:55]
	global_load_dwordx4 v[114:117], v[114:115], off offset:256
	v_mfma_f32_16x16x32_bf16 v[58:61], v[224:227], v[212:215], v[58:61]
	ds_write_b128 v170, v[126:129] offset:40960
	v_mfma_f32_16x16x32_bf16 v[26:29], v[224:227], v[216:219], v[26:29]
	v_lshl_add_u64 v[126:127], v[168:169], 0, s[54:55]
	global_load_dwordx4 v[126:129], v[126:127], off offset:256
	ds_read_b128 v[198:201], v206 offset:2048
	v_mfma_f32_16x16x32_bf16 v[146:149], v[228:231], v[190:193], v[146:149]
	ds_read_b128 v[224:227], v207 offset:34816
	ds_write_b128 v170, v[122:125] offset:16384
	v_mfma_f32_16x16x32_bf16 v[86:89], v[228:231], v[208:211], v[86:89]
	v_lshl_add_u64 v[122:123], v[176:177], 0, s[54:55]
	global_load_dwordx4 v[122:125], v[122:123], off offset:256
	v_mfma_f32_16x16x32_bf16 v[54:57], v[228:231], v[212:215], v[54:57]
	ds_write_b128 v170, v[134:137] offset:49152
	v_mfma_f32_16x16x32_bf16 v[22:25], v[228:231], v[216:219], v[22:25]
	v_lshl_add_u64 v[134:135], v[178:179], 0, s[54:55]
	global_load_dwordx4 v[134:137], v[134:135], off offset:256
	ds_read_b128 v[202:205], v206 offset:4096
	v_mfma_f32_16x16x32_bf16 v[142:145], v[232:235], v[190:193], v[142:145]
	ds_read_b128 v[228:231], v207 offset:36864
	ds_write_b128 v170, v[130:133] offset:24576
	v_mfma_f32_16x16x32_bf16 v[82:85], v[232:235], v[208:211], v[82:85]
	v_lshl_add_u64 v[130:131], v[180:181], 0, s[54:55]
	global_load_dwordx4 v[130:133], v[130:131], off offset:256
	v_mfma_f32_16x16x32_bf16 v[50:53], v[232:235], v[212:215], v[50:53]
	ds_write_b128 v170, v[150:153] offset:57344
	v_mfma_f32_16x16x32_bf16 v[18:21], v[232:235], v[216:219], v[18:21]
	v_lshl_add_u64 v[150:151], v[182:183], 0, s[54:55]
	global_load_dwordx4 v[150:153], v[150:151], off offset:256
	v_mfma_f32_16x16x32_bf16 v[138:141], v[236:239], v[190:193], v[138:141]
	ds_read_b128 v[232:235], v207 offset:38912
	v_mfma_f32_16x16x32_bf16 v[78:81], v[236:239], v[208:211], v[78:81]
	v_mfma_f32_16x16x32_bf16 v[46:49], v[236:239], v[212:215], v[46:49]
	v_mfma_f32_16x16x32_bf16 v[14:17], v[236:239], v[216:219], v[14:17]
	v_mfma_f32_16x16x32_bf16 v[106:109], v[240:243], v[190:193], v[106:109]
	ds_read_b128 v[236:239], v207 offset:40960
	v_mfma_f32_16x16x32_bf16 v[74:77], v[240:243], v[208:211], v[74:77]
	v_mfma_f32_16x16x32_bf16 v[42:45], v[240:243], v[212:215], v[42:45]
	v_mfma_f32_16x16x32_bf16 v[10:13], v[240:243], v[216:219], v[10:13]
	v_mfma_f32_16x16x32_bf16 v[102:105], v[244:247], v[190:193], v[102:105]
	ds_read_b128 v[240:243], v207 offset:43008
	v_mfma_f32_16x16x32_bf16 v[70:73], v[244:247], v[208:211], v[70:73]
	v_mfma_f32_16x16x32_bf16 v[38:41], v[244:247], v[212:215], v[38:41]
	v_mfma_f32_16x16x32_bf16 v[6:9], v[244:247], v[216:219], v[6:9]
	s_waitcnt lgkmcnt(15)
	v_mfma_f32_16x16x32_bf16 v[2:5], v[248:251], v[216:219], v[2:5]
	ds_read_b128 v[244:247], v207 offset:45056
	ds_read_b128 v[216:219], v206 offset:6144
	v_mfma_f32_16x16x32_bf16 v[98:101], v[248:251], v[190:193], v[98:101]
	v_mfma_f32_16x16x32_bf16 v[66:69], v[248:251], v[208:211], v[66:69]
	v_mfma_f32_16x16x32_bf16 v[34:37], v[248:251], v[212:215], v[34:37]
	ds_read_b128 v[248:251], v207 offset:47104
	s_waitcnt lgkmcnt(6)
	s_barrier
;   __device__ __forceinline__ u16* P() const { return (u16*)(ws + O_P); }
; DI f32x4 mfma16(bf16x8 a, bf16x8 b, f32x4 c) { return __builtin_amdgcn_mfma_f32_16x16x32_bf16(a, b, c, 0, 0, 0); }
; #define GLOAD(kt) { GL1(0, kt) GL1(1, kt) GL1(2, kt) GL1(3, kt) }
; #define SSTORE(buf)                              \
;   {                                              \
;     char* as_ = smem + (buf) * BUF;              \
;     char* bs_ = as_ + ASZ;                       \
;     SS1(0) SS1(1) SS1(2) SS1(3)                  \
;   }
; template <int MT, int NT>
; DI void gemm_core(const u16* __restrict__ A, int lda, const u16* __restrict__ B, int ldb, int K,
;                   f32x4 (&acc)[MT][NT], char* smem) {
;     ...
;   for (int kt = 0; kt < nk; ++kt) {
;     __syncthreads();
;     SSTORE((kt + 1) & 1);
;     { const int kn_ = (kt + 2 < nk) ? kt + 2 : nk - 1; GLOAD(kn_); }
;     const char* as = smem + (kt & 1) * BUF;
;     const char* bs = as + ASZ;
; #pragma unroll
;     for (int kk = 0; kk < 2; ++kk) {
;       bf16x8 xf[MT], wf[NT];
; #pragma unroll
;       for (int mi = 0; mi < MT; ++mi)
;         xf[mi] = *(const bf16x8*)(as + (wm * (MT * 16) + mi * 16 + fr) * 128 + (((kk * 4 + fq) ^ fsw) * 16));
; #pragma unroll
;       for (int ni = 0; ni < NT; ++ni)
;         wf[ni] = *(const bf16x8*)(bs + (wn * (NT * 16) + ni * 16 + fr) * 128 + (((kk * 4 + fq) ^ fsw) * 16));
;       __builtin_amdgcn_s_setprio(1);
; #pragma unroll
;       for (int mi = 0; mi < MT; ++mi)
; #pragma unroll
;         for (int ni = 0; ni < NT; ++ni) acc[mi][ni] = mfma16(wf[ni], xf[mi], acc[mi][ni]);
;       __builtin_amdgcn_s_setprio(0);
;     }
;   }
; DI void phase_ff1(const Params& p, int l, char* smem) {
;     ...
;     EPI_LOOP(4, 8) {
;       const int row = r0 + wm_ * 64 + mi * 16 + fr_, col = c0 + wn_ * 128 + ni * 16 + fq_ * 4;
;       float a0 = fmaxf(acc[mi][ni][0], 0.f), a1 = fmaxf(acc[mi][ni][1], 0.f), a2 = fmaxf(acc[mi][ni][2], 0.f), a3 = fmaxf(acc[mi][ni][3], 0.f);
;       uint2 o;
;       o.x = pack2(a0 * a0, a1 * a1); o.y = pack2(a2 * a2, a3 * a3);
;       *(uint2*)(p.P() + (size_t)row * LDH + col) = o;
;     }
	v_or_b32_e32 v206, s9, v186
	v_add_u32_e32 v207, v206, v188
	v_add_u32_e32 v206, v206, v187
	v_mfma_f32_16x16x32_bf16 v[158:161], v[220:223], v[194:197], v[158:161]
	v_mfma_f32_16x16x32_bf16 v[94:97], v[220:223], v[198:201], v[94:97]
	v_mfma_f32_16x16x32_bf16 v[62:65], v[220:223], v[202:205], v[62:65]
	s_waitcnt lgkmcnt(1)
	v_mfma_f32_16x16x32_bf16 v[30:33], v[220:223], v[216:219], v[30:33]
	ds_read_b128 v[190:193], v206
	v_mfma_f32_16x16x32_bf16 v[154:157], v[224:227], v[194:197], v[154:157]
	ds_read_b128 v[220:223], v207 offset:32768
	v_mfma_f32_16x16x32_bf16 v[90:93], v[224:227], v[198:201], v[90:93]
	v_mfma_f32_16x16x32_bf16 v[58:61], v[224:227], v[202:205], v[58:61]
	v_mfma_f32_16x16x32_bf16 v[26:29], v[224:227], v[216:219], v[26:29]
	ds_read_b128 v[208:211], v206 offset:2048
	v_mfma_f32_16x16x32_bf16 v[146:149], v[228:231], v[194:197], v[146:149]
	ds_read_b128 v[224:227], v207 offset:34816
	v_mfma_f32_16x16x32_bf16 v[86:89], v[228:231], v[198:201], v[86:89]
	v_mfma_f32_16x16x32_bf16 v[54:57], v[228:231], v[202:205], v[54:57]
	v_mfma_f32_16x16x32_bf16 v[22:25], v[228:231], v[216:219], v[22:25]
	ds_read_b128 v[212:215], v206 offset:4096
	v_mfma_f32_16x16x32_bf16 v[142:145], v[232:235], v[194:197], v[142:145]
	ds_read_b128 v[228:231], v207 offset:36864
	v_mfma_f32_16x16x32_bf16 v[82:85], v[232:235], v[198:201], v[82:85]
	v_mfma_f32_16x16x32_bf16 v[50:53], v[232:235], v[202:205], v[50:53]
	v_mfma_f32_16x16x32_bf16 v[18:21], v[232:235], v[216:219], v[18:21]
	v_mfma_f32_16x16x32_bf16 v[138:141], v[236:239], v[194:197], v[138:141]
	ds_read_b128 v[232:235], v207 offset:38912
	v_mfma_f32_16x16x32_bf16 v[78:81], v[236:239], v[198:201], v[78:81]
	v_mfma_f32_16x16x32_bf16 v[46:49], v[236:239], v[202:205], v[46:49]
	v_mfma_f32_16x16x32_bf16 v[14:17], v[236:239], v[216:219], v[14:17]
	v_mfma_f32_16x16x32_bf16 v[106:109], v[240:243], v[194:197], v[106:109]
	ds_read_b128 v[236:239], v207 offset:40960
	v_mfma_f32_16x16x32_bf16 v[74:77], v[240:243], v[198:201], v[74:77]
	v_mfma_f32_16x16x32_bf16 v[42:45], v[240:243], v[202:205], v[42:45]
	v_mfma_f32_16x16x32_bf16 v[10:13], v[240:243], v[216:219], v[10:13]
	v_mfma_f32_16x16x32_bf16 v[102:105], v[244:247], v[194:197], v[102:105]
	ds_read_b128 v[240:243], v207 offset:43008
	v_mfma_f32_16x16x32_bf16 v[70:73], v[244:247], v[198:201], v[70:73]
	v_mfma_f32_16x16x32_bf16 v[38:41], v[244:247], v[202:205], v[38:41]
	v_mfma_f32_16x16x32_bf16 v[6:9], v[244:247], v[216:219], v[6:9]
	s_waitcnt lgkmcnt(9)
	v_mfma_f32_16x16x32_bf16 v[2:5], v[248:251], v[216:219], v[2:5]
	ds_read_b128 v[244:247], v207 offset:45056
	ds_read_b128 v[216:219], v206 offset:6144
	v_mfma_f32_16x16x32_bf16 v[98:101], v[248:251], v[194:197], v[98:101]
	v_mfma_f32_16x16x32_bf16 v[66:69], v[248:251], v[198:201], v[66:69]
	v_mfma_f32_16x16x32_bf16 v[34:37], v[248:251], v[202:205], v[34:37]
	ds_read_b128 v[248:251], v207 offset:47104
	s_cmp_lg_u32 s7, 16
	s_mov_b32 s5, s8
	s_mov_b32 s6, s7
	s_cbranch_scc1 .LBB0_768
	s_waitcnt vmcnt(0) lgkmcnt(0)
	v_mov_b32_e32 v170, 0x358637bd
	v_mov_b32_e32 v194, 0x25a08
	v_mbcnt_lo_u32_b32 v195, -1, 0
	v_mbcnt_hi_u32_b32 v196, -1, v195
	v_mov_b32_e32 v197, 0x24000
	v_mov_b32_e32 v198, 0x1fa0
	v_mov_b32_e32 v199, 0x41b17218
	v_mov_b32_e32 v200, 0x7e800
	v_mov_b32_e32 v201, 0xfd0
	v_mov_b32_e32 v202, 0x100
	v_mov_b32_e32 v203, 0x200
	v_mov_b32_e32 v204, 0x7f61b1e6
	v_mov_b32_e32 v205, 0xff800000
	v_mov_b32_e32 v206, 0x3f80
	v_mov_b32_e32 v207, 0x1d400
	v_mov_b32_e32 v0, v171
	s_waitcnt vmcnt(7)
	v_mov_b32_e32 v110, v171
	s_barrier
	v_max_f32_e32 v113, v159, v159
	v_ashrrev_i32_e32 v111, 1, v110
	v_and_b32_e32 v111, 0xffffffc0, v111
	v_add_u32_e32 v111, s1, v111
	s_waitcnt vmcnt(6)
	v_and_or_b32 v118, v0, 15, v111
	v_lshlrev_b32_e32 v110, 1, v110
	v_lshrrev_b32_e32 v0, 2, v0
	v_and_b32_e32 v110, 0x80, v110
	v_and_b32_e32 v0, 12, v0
	v_or3_b32 v112, v0, v110, s0
	v_max_f32_e32 v0, v158, v158
	v_max_f32_e32 v113, 0, v113
	s_waitcnt vmcnt(5)
	v_max_f32_e32 v116, v160, v160
	v_max_f32_e32 v117, v161, v161
	v_mov_b64_e32 v[110:111], s[78:79]
	v_max_f32_e32 v0, 0, v0
	v_max_f32_e32 v116, 0, v116
	v_max_f32_e32 v117, 0, v117
	v_mul_f32_e32 v119, v113, v113
	v_ashrrev_i32_e32 v113, 31, v112
	v_mad_i64_i32 v[114:115], s[0:1], v118, s10, v[110:111]
	v_mul_f32_e32 v0, v0, v0
	v_mul_f32_e32 v116, v116, v116
	v_mul_f32_e32 v117, v117, v117
	v_lshlrev_b64 v[112:113], 1, v[112:113]
	v_lshl_add_u64 v[114:115], v[114:115], 0, v[112:113]
	v_cvt_pk_bf16_f32 v117, v116, v117
	v_cvt_pk_bf16_f32 v116, v0, v119
	global_store_dwordx2 v[114:115], v[116:117], off
	v_max_f32_e32 v0, v154, v154
	v_max_f32_e32 v116, v155, v155
	v_max_f32_e32 v117, v156, v156
	v_max_f32_e32 v119, v157, v157
	v_max_f32_e32 v0, 0, v0
	v_max_f32_e32 v116, 0, v116
	v_max_f32_e32 v117, 0, v117
	v_max_f32_e32 v119, 0, v119
	v_mul_f32_e32 v0, v0, v0
	v_mul_f32_e32 v116, v116, v116
	v_mul_f32_e32 v117, v117, v117
	v_mul_f32_e32 v119, v119, v119
	v_cvt_pk_bf16_f32 v117, v117, v119
	v_cvt_pk_bf16_f32 v116, v0, v116
	global_store_dwordx2 v[114:115], v[116:117], off offset:32
	v_max_f32_e32 v0, v146, v146
	v_max_f32_e32 v116, v147, v147
	v_max_f32_e32 v117, v148, v148
	v_max_f32_e32 v119, v149, v149
	v_max_f32_e32 v0, 0, v0
	v_max_f32_e32 v116, 0, v116
	v_max_f32_e32 v117, 0, v117
	v_max_f32_e32 v119, 0, v119
	v_mul_f32_e32 v0, v0, v0
	v_mul_f32_e32 v116, v116, v116
	v_mul_f32_e32 v117, v117, v117
	v_mul_f32_e32 v119, v119, v119
	v_cvt_pk_bf16_f32 v117, v117, v119
	v_cvt_pk_bf16_f32 v116, v0, v116
	global_store_dwordx2 v[114:115], v[116:117], off offset:64
	v_max_f32_e32 v0, v142, v142
	v_max_f32_e32 v116, v143, v143
	v_max_f32_e32 v117, v144, v144
	v_max_f32_e32 v119, v145, v145
;   __device__ __forceinline__ u16* P() const { return (u16*)(ws + O_P); }
; #define EPI_LOOP(MT_, NT_)                                                \
;   const int l_ = ltid() & 63, w_ = ltid() >> 6;                           \
;   const int wm_ = w_ >> 1, wn_ = w_ & 1, fr_ = l_ & 15, fq_ = l_ >> 4;    \
;   _Pragma("unroll") for (int mi = 0; mi < MT_; ++mi)                      \
;   _Pragma("unroll") for (int ni = 0; ni < NT_; ++ni)
; DI void phase_ff1(const Params& p, int l, char* smem) {
;     ...
;     EPI_LOOP(4, 8) {
;       const int row = r0 + wm_ * 64 + mi * 16 + fr_, col = c0 + wn_ * 128 + ni * 16 + fq_ * 4;
;       float a0 = fmaxf(acc[mi][ni][0], 0.f), a1 = fmaxf(acc[mi][ni][1], 0.f), a2 = fmaxf(acc[mi][ni][2], 0.f), a3 = fmaxf(acc[mi][ni][3], 0.f);
;       uint2 o;
;       o.x = pack2(a0 * a0, a1 * a1); o.y = pack2(a2 * a2, a3 * a3);
;       *(uint2*)(p.P() + (size_t)row * LDH + col) = o;
;     }
	v_max_f32_e32 v0, 0, v0
	v_max_f32_e32 v116, 0, v116
	v_max_f32_e32 v117, 0, v117
	v_max_f32_e32 v119, 0, v119
	v_mul_f32_e32 v0, v0, v0
	v_mul_f32_e32 v116, v116, v116
	v_mul_f32_e32 v117, v117, v117
	v_mul_f32_e32 v119, v119, v119
	v_cvt_pk_bf16_f32 v117, v117, v119
	v_cvt_pk_bf16_f32 v116, v0, v116
	global_store_dwordx2 v[114:115], v[116:117], off offset:96
	v_max_f32_e32 v0, v138, v138
	v_max_f32_e32 v116, v139, v139
	v_max_f32_e32 v0, 0, v0
	v_max_f32_e32 v116, 0, v116
	v_mul_f32_e32 v0, v0, v0
	v_mul_f32_e32 v116, v116, v116
	v_cvt_pk_bf16_f32 v116, v0, v116
	v_max_f32_e32 v0, v106, v106
	v_max_f32_e32 v106, v107, v107
	v_max_f32_e32 v0, 0, v0
	v_max_f32_e32 v106, 0, v106
	v_mul_f32_e32 v0, v0, v0
	v_mul_f32_e32 v106, v106, v106
	v_cvt_pk_bf16_f32 v106, v0, v106
	v_max_f32_e32 v0, v102, v102
	v_max_f32_e32 v102, v103, v103
	v_max_f32_e32 v0, 0, v0
	v_max_f32_e32 v102, 0, v102
	v_mul_f32_e32 v0, v0, v0
	v_mul_f32_e32 v102, v102, v102
	v_cvt_pk_bf16_f32 v102, v0, v102
	v_max_f32_e32 v0, v98, v98
	v_max_f32_e32 v98, v99, v99
	v_max_f32_e32 v99, v100, v100
	v_max_f32_e32 v100, v101, v101
	v_max_f32_e32 v0, 0, v0
	v_max_f32_e32 v98, 0, v98
	v_max_f32_e32 v99, 0, v99
	v_max_f32_e32 v100, 0, v100
	v_mul_f32_e32 v0, v0, v0
	v_mul_f32_e32 v98, v98, v98
	v_mul_f32_e32 v99, v99, v99
	v_mul_f32_e32 v100, v100, v100
	v_cvt_pk_bf16_f32 v99, v99, v100
	v_cvt_pk_bf16_f32 v98, v0, v98
	v_or_b32_e32 v0, 16, v118
	global_store_dwordx2 v[114:115], v[98:99], off offset:224
	v_mad_i64_i32 v[98:99], s[0:1], v0, s10, v[110:111]
	v_max_f32_e32 v0, v94, v94
	v_max_f32_e32 v94, v95, v95
	v_max_f32_e32 v95, v96, v96
	v_max_f32_e32 v96, v97, v97
	v_max_f32_e32 v0, 0, v0
	v_max_f32_e32 v94, 0, v94
	v_max_f32_e32 v95, 0, v95
	v_max_f32_e32 v96, 0, v96
	v_mul_f32_e32 v0, v0, v0
	v_mul_f32_e32 v100, v94, v94
	v_mul_f32_e32 v97, v95, v95
	v_mul_f32_e32 v96, v96, v96
	v_cvt_pk_bf16_f32 v97, v97, v96
	v_cvt_pk_bf16_f32 v96, v0, v100
	v_max_f32_e32 v0, v90, v90
	v_max_f32_e32 v90, v91, v91
	v_max_f32_e32 v0, 0, v0
	v_max_f32_e32 v90, 0, v90
	v_mul_f32_e32 v0, v0, v0
	v_mul_f32_e32 v90, v90, v90
	v_cvt_pk_bf16_f32 v90, v0, v90
	v_max_f32_e32 v0, v86, v86
	v_max_f32_e32 v86, v87, v87
	v_max_f32_e32 v0, 0, v0
	v_max_f32_e32 v86, 0, v86
	v_mul_f32_e32 v0, v0, v0
	v_mul_f32_e32 v86, v86, v86
	v_cvt_pk_bf16_f32 v86, v0, v86
	v_max_f32_e32 v0, v82, v82
	v_max_f32_e32 v82, v83, v83
	v_max_f32_e32 v0, 0, v0
	v_max_f32_e32 v82, 0, v82
	v_mul_f32_e32 v0, v0, v0
	v_mul_f32_e32 v82, v82, v82
	v_cvt_pk_bf16_f32 v82, v0, v82
	v_max_f32_e32 v0, v78, v78
	v_max_f32_e32 v78, v79, v79
	v_max_f32_e32 v0, 0, v0
	v_max_f32_e32 v78, 0, v78
	v_mul_f32_e32 v0, v0, v0
	v_mul_f32_e32 v78, v78, v78
	v_cvt_pk_bf16_f32 v78, v0, v78
	v_max_f32_e32 v0, v74, v74
	v_max_f32_e32 v74, v75, v75
	v_max_f32_e32 v0, 0, v0
	v_max_f32_e32 v74, 0, v74
	v_mul_f32_e32 v0, v0, v0
	v_mul_f32_e32 v74, v74, v74
	v_cvt_pk_bf16_f32 v74, v0, v74
	v_max_f32_e32 v0, v70, v70
	v_max_f32_e32 v70, v71, v71
	v_max_f32_e32 v0, 0, v0
	v_max_f32_e32 v70, 0, v70
	v_mul_f32_e32 v0, v0, v0
	v_mul_f32_e32 v70, v70, v70
	v_cvt_pk_bf16_f32 v70, v0, v70
	v_max_f32_e32 v0, v66, v66
	v_max_f32_e32 v66, v67, v67
	v_max_f32_e32 v67, v68, v68
	v_max_f32_e32 v68, v69, v69
	v_max_f32_e32 v0, 0, v0
	v_max_f32_e32 v66, 0, v66
	v_max_f32_e32 v67, 0, v67
	v_max_f32_e32 v68, 0, v68
	v_mul_f32_e32 v0, v0, v0
	v_mul_f32_e32 v66, v66, v66
	v_mul_f32_e32 v67, v67, v67
	v_mul_f32_e32 v68, v68, v68
	v_lshl_add_u64 v[94:95], v[98:99], 0, v[112:113]
	v_cvt_pk_bf16_f32 v67, v67, v68
	v_cvt_pk_bf16_f32 v66, v0, v66
	v_or_b32_e32 v0, 32, v118
	global_store_dwordx2 v[94:95], v[66:67], off offset:224
	v_mad_i64_i32 v[66:67], s[0:1], v0, s10, v[110:111]
	v_max_f32_e32 v0, v62, v62
	v_max_f32_e32 v62, v63, v63
	v_max_f32_e32 v63, v64, v64
	v_max_f32_e32 v64, v65, v65
	v_max_f32_e32 v0, 0, v0
	v_max_f32_e32 v62, 0, v62
	v_max_f32_e32 v63, 0, v63
	v_max_f32_e32 v64, 0, v64
	v_mul_f32_e32 v0, v0, v0
	v_mul_f32_e32 v68, v62, v62
	v_mul_f32_e32 v65, v63, v63
	v_mul_f32_e32 v64, v64, v64
	v_cvt_pk_bf16_f32 v65, v65, v64
	v_cvt_pk_bf16_f32 v64, v0, v68
	v_max_f32_e32 v0, v58, v58
	v_max_f32_e32 v58, v59, v59
	v_max_f32_e32 v0, 0, v0
	v_max_f32_e32 v58, 0, v58
	v_mul_f32_e32 v0, v0, v0
	v_mul_f32_e32 v58, v58, v58
	v_cvt_pk_bf16_f32 v58, v0, v58
	v_max_f32_e32 v0, v54, v54
	v_max_f32_e32 v54, v55, v55
	v_max_f32_e32 v0, 0, v0
	v_max_f32_e32 v54, 0, v54
	v_mul_f32_e32 v0, v0, v0
	v_mul_f32_e32 v54, v54, v54
	v_cvt_pk_bf16_f32 v54, v0, v54
	v_max_f32_e32 v0, v50, v50
	v_max_f32_e32 v50, v51, v51
	v_max_f32_e32 v0, 0, v0
	v_max_f32_e32 v50, 0, v50
	v_mul_f32_e32 v0, v0, v0
	v_mul_f32_e32 v50, v50, v50
	v_cvt_pk_bf16_f32 v50, v0, v50
	v_max_f32_e32 v0, v46, v46
	v_max_f32_e32 v46, v47, v47
	v_max_f32_e32 v0, 0, v0
	v_max_f32_e32 v46, 0, v46
	v_mul_f32_e32 v0, v0, v0
	v_mul_f32_e32 v46, v46, v46
	v_cvt_pk_bf16_f32 v46, v0, v46
	v_max_f32_e32 v0, v42, v42
	v_max_f32_e32 v42, v43, v43
	v_max_f32_e32 v0, 0, v0
	v_max_f32_e32 v42, 0, v42
	v_mul_f32_e32 v0, v0, v0
	v_mul_f32_e32 v42, v42, v42
	v_cvt_pk_bf16_f32 v42, v0, v42
	v_max_f32_e32 v0, v38, v38
	v_max_f32_e32 v38, v39, v39
	v_max_f32_e32 v0, 0, v0
	v_max_f32_e32 v38, 0, v38
	v_mul_f32_e32 v0, v0, v0
	v_mul_f32_e32 v38, v38, v38
	v_cvt_pk_bf16_f32 v38, v0, v38
	v_max_f32_e32 v0, v34, v34
	v_max_f32_e32 v34, v35, v35
	v_max_f32_e32 v35, v36, v36
	v_max_f32_e32 v36, v37, v37
	v_max_f32_e32 v0, 0, v0
	v_max_f32_e32 v34, 0, v34
	v_max_f32_e32 v35, 0, v35
	v_max_f32_e32 v36, 0, v36
	v_mul_f32_e32 v0, v0, v0
	v_mul_f32_e32 v34, v34, v34
	v_mul_f32_e32 v35, v35, v35
	v_mul_f32_e32 v36, v36, v36
	v_lshl_add_u64 v[62:63], v[66:67], 0, v[112:113]
;   __device__ __forceinline__ u16* P() const { return (u16*)(ws + O_P); }
; #define EPI_LOOP(MT_, NT_)                                                \
;   const int l_ = ltid() & 63, w_ = ltid() >> 6;                           \
;   const int wm_ = w_ >> 1, wn_ = w_ & 1, fr_ = l_ & 15, fq_ = l_ >> 4;    \
;   _Pragma("unroll") for (int mi = 0; mi < MT_; ++mi)                      \
;   _Pragma("unroll") for (int ni = 0; ni < NT_; ++ni)
; DI void phase_ff1(const Params& p, int l, char* smem) {
;     ...
;     EPI_LOOP(4, 8) {
;       const int row = r0 + wm_ * 64 + mi * 16 + fr_, col = c0 + wn_ * 128 + ni * 16 + fq_ * 4;
;       float a0 = fmaxf(acc[mi][ni][0], 0.f), a1 = fmaxf(acc[mi][ni][1], 0.f), a2 = fmaxf(acc[mi][ni][2], 0.f), a3 = fmaxf(acc[mi][ni][3], 0.f);
;       uint2 o;
;       o.x = pack2(a0 * a0, a1 * a1); o.y = pack2(a2 * a2, a3 * a3);
;       *(uint2*)(p.P() + (size_t)row * LDH + col) = o;
;     }
	v_cvt_pk_bf16_f32 v35, v35, v36
	v_cvt_pk_bf16_f32 v34, v0, v34
	v_or_b32_e32 v0, 48, v118
	global_store_dwordx2 v[62:63], v[34:35], off offset:224
	v_mad_i64_i32 v[34:35], s[0:1], v0, s10, v[110:111]
	v_max_f32_e32 v0, v30, v30
	v_max_f32_e32 v30, v31, v31
	v_max_f32_e32 v31, v32, v32
	v_max_f32_e32 v32, v33, v33
	v_max_f32_e32 v0, 0, v0
	v_max_f32_e32 v30, 0, v30
	v_max_f32_e32 v31, 0, v31
	v_max_f32_e32 v32, 0, v32
	v_mul_f32_e32 v0, v0, v0
	v_mul_f32_e32 v36, v30, v30
	v_mul_f32_e32 v33, v31, v31
	v_mul_f32_e32 v32, v32, v32
	v_cvt_pk_bf16_f32 v33, v33, v32
	v_cvt_pk_bf16_f32 v32, v0, v36
	v_max_f32_e32 v0, v26, v26
	v_max_f32_e32 v26, v27, v27
	v_max_f32_e32 v0, 0, v0
	v_max_f32_e32 v26, 0, v26
	v_mul_f32_e32 v0, v0, v0
	v_mul_f32_e32 v26, v26, v26
	v_cvt_pk_bf16_f32 v26, v0, v26
	v_max_f32_e32 v0, v22, v22
	v_max_f32_e32 v22, v23, v23
	v_max_f32_e32 v0, 0, v0
	v_max_f32_e32 v22, 0, v22
	v_mul_f32_e32 v0, v0, v0
	v_mul_f32_e32 v22, v22, v22
	v_cvt_pk_bf16_f32 v22, v0, v22
	v_max_f32_e32 v0, v18, v18
	v_max_f32_e32 v18, v19, v19
	v_max_f32_e32 v0, 0, v0
	v_max_f32_e32 v18, 0, v18
	v_mul_f32_e32 v0, v0, v0
	v_mul_f32_e32 v18, v18, v18
	v_cvt_pk_bf16_f32 v18, v0, v18
	v_max_f32_e32 v0, v14, v14
	v_max_f32_e32 v14, v15, v15
	v_max_f32_e32 v0, 0, v0
	v_max_f32_e32 v14, 0, v14
	v_mul_f32_e32 v0, v0, v0
	v_mul_f32_e32 v14, v14, v14
	v_cvt_pk_bf16_f32 v14, v0, v14
	v_max_f32_e32 v0, v10, v10
	v_max_f32_e32 v10, v11, v11
	v_max_f32_e32 v0, 0, v0
	v_max_f32_e32 v10, 0, v10
	v_mul_f32_e32 v0, v0, v0
	v_mul_f32_e32 v10, v10, v10
	v_cvt_pk_bf16_f32 v10, v0, v10
	v_max_f32_e32 v0, v6, v6
	v_max_f32_e32 v6, v7, v7
	v_max_f32_e32 v0, 0, v0
	v_max_f32_e32 v6, 0, v6
	v_mul_f32_e32 v0, v0, v0
	v_mul_f32_e32 v6, v6, v6
	v_max_f32_e32 v117, v140, v140
	v_max_f32_e32 v119, v141, v141
	v_max_f32_e32 v107, v108, v108
	v_max_f32_e32 v108, v109, v109
	v_max_f32_e32 v103, v104, v104
	v_max_f32_e32 v104, v105, v105
	v_max_f32_e32 v91, v92, v92
	v_max_f32_e32 v92, v93, v93
	v_max_f32_e32 v87, v88, v88
	v_max_f32_e32 v88, v89, v89
	v_max_f32_e32 v83, v84, v84
	v_max_f32_e32 v84, v85, v85
	v_max_f32_e32 v79, v80, v80
	v_max_f32_e32 v80, v81, v81
	v_max_f32_e32 v75, v76, v76
	v_max_f32_e32 v76, v77, v77
	v_max_f32_e32 v71, v72, v72
	v_max_f32_e32 v72, v73, v73
	v_max_f32_e32 v59, v60, v60
	v_max_f32_e32 v60, v61, v61
	v_max_f32_e32 v55, v56, v56
	v_max_f32_e32 v56, v57, v57
	v_max_f32_e32 v51, v52, v52
	v_max_f32_e32 v52, v53, v53
	v_max_f32_e32 v47, v48, v48
	v_max_f32_e32 v48, v49, v49
	v_max_f32_e32 v43, v44, v44
	v_max_f32_e32 v44, v45, v45
	v_max_f32_e32 v39, v40, v40
	v_max_f32_e32 v40, v41, v41
	v_max_f32_e32 v27, v28, v28
	v_max_f32_e32 v28, v29, v29
	v_max_f32_e32 v23, v24, v24
	v_max_f32_e32 v24, v25, v25
	v_max_f32_e32 v19, v20, v20
	v_max_f32_e32 v20, v21, v21
	v_max_f32_e32 v15, v16, v16
	v_max_f32_e32 v16, v17, v17
	v_max_f32_e32 v11, v12, v12
	v_max_f32_e32 v12, v13, v13
	v_max_f32_e32 v7, v8, v8
	v_max_f32_e32 v8, v9, v9
	v_cvt_pk_bf16_f32 v6, v0, v6
	v_max_f32_e32 v0, v2, v2
	v_max_f32_e32 v2, v3, v3
	v_max_f32_e32 v3, v4, v4
	v_max_f32_e32 v4, v5, v5
	v_max_f32_e32 v117, 0, v117
	v_max_f32_e32 v119, 0, v119
	v_max_f32_e32 v107, 0, v107
	v_max_f32_e32 v108, 0, v108
	v_max_f32_e32 v103, 0, v103
	v_max_f32_e32 v104, 0, v104
	v_max_f32_e32 v91, 0, v91
	v_max_f32_e32 v92, 0, v92
	v_max_f32_e32 v87, 0, v87
	v_max_f32_e32 v88, 0, v88
	v_max_f32_e32 v83, 0, v83
	v_max_f32_e32 v84, 0, v84
	v_max_f32_e32 v79, 0, v79
	v_max_f32_e32 v80, 0, v80
	v_max_f32_e32 v75, 0, v75
	v_max_f32_e32 v76, 0, v76
	v_max_f32_e32 v71, 0, v71
	v_max_f32_e32 v72, 0, v72
	v_max_f32_e32 v59, 0, v59
	v_max_f32_e32 v60, 0, v60
	v_max_f32_e32 v55, 0, v55
	v_max_f32_e32 v56, 0, v56
	v_max_f32_e32 v51, 0, v51
	v_max_f32_e32 v52, 0, v52
	v_max_f32_e32 v47, 0, v47
	v_max_f32_e32 v48, 0, v48
	v_max_f32_e32 v43, 0, v43
	v_max_f32_e32 v44, 0, v44
	v_max_f32_e32 v39, 0, v39
	v_max_f32_e32 v40, 0, v40
	v_max_f32_e32 v27, 0, v27
	v_max_f32_e32 v28, 0, v28
;   __device__ __forceinline__ u16* wf1(int l) const { return (u16*)(ws + l * LAYER_W + O_WF1); }
;   __device__ __forceinline__ u16* P() const { return (u16*)(ws + O_P); }
;   __device__ __forceinline__ u16* XB() const { return (u16*)(ws + O_XB); }
; #define EPI_LOOP(MT_, NT_)                                                \
;   const int l_ = ltid() & 63, w_ = ltid() >> 6;                           \
;   const int wm_ = w_ >> 1, wn_ = w_ & 1, fr_ = l_ & 15, fq_ = l_ >> 4;    \
;   _Pragma("unroll") for (int mi = 0; mi < MT_; ++mi)                      \
;   _Pragma("unroll") for (int ni = 0; ni < NT_; ++ni)
; DI void phase_ff1(const Params& p, int l, char* smem) {
;     ...
;   for (int it = 0; next_tile(it, 128, 16, 8, 8, rt, ct); ++it) {
;     const int r0 = rt * 256, c0 = ct * 256;
;     f32x4 acc[4][8];
;     zero_acc<4, 8>(acc);
;     gemm_core<4, 8>(p.XB() + (size_t)r0 * LDX, LDX, p.wf1(l) + (size_t)c0 * KP1024, KP1024, 1024, acc, smem);
;     EPI_LOOP(4, 8) {
;       const int row = r0 + wm_ * 64 + mi * 16 + fr_, col = c0 + wn_ * 128 + ni * 16 + fq_ * 4;
;       float a0 = fmaxf(acc[mi][ni][0], 0.f), a1 = fmaxf(acc[mi][ni][1], 0.f), a2 = fmaxf(acc[mi][ni][2], 0.f), a3 = fmaxf(acc[mi][ni][3], 0.f);
;       uint2 o;
;       o.x = pack2(a0 * a0, a1 * a1); o.y = pack2(a2 * a2, a3 * a3);
;       *(uint2*)(p.P() + (size_t)row * LDH + col) = o;
;     }
	v_max_f32_e32 v23, 0, v23
	v_max_f32_e32 v24, 0, v24
	v_max_f32_e32 v19, 0, v19
	v_max_f32_e32 v20, 0, v20
	v_max_f32_e32 v15, 0, v15
	v_max_f32_e32 v16, 0, v16
	v_max_f32_e32 v11, 0, v11
	v_max_f32_e32 v12, 0, v12
	v_max_f32_e32 v7, 0, v7
	v_max_f32_e32 v8, 0, v8
	v_max_f32_e32 v0, 0, v0
	v_max_f32_e32 v2, 0, v2
	v_max_f32_e32 v3, 0, v3
	v_max_f32_e32 v4, 0, v4
	v_mul_f32_e32 v117, v117, v117
	v_mul_f32_e32 v119, v119, v119
	v_mul_f32_e32 v107, v107, v107
	v_mul_f32_e32 v108, v108, v108
	v_mul_f32_e32 v103, v103, v103
	v_mul_f32_e32 v104, v104, v104
	v_mul_f32_e32 v91, v91, v91
	v_mul_f32_e32 v92, v92, v92
	v_mul_f32_e32 v87, v87, v87
	v_mul_f32_e32 v88, v88, v88
	v_mul_f32_e32 v83, v83, v83
	v_mul_f32_e32 v84, v84, v84
	v_mul_f32_e32 v79, v79, v79
	v_mul_f32_e32 v80, v80, v80
	v_mul_f32_e32 v75, v75, v75
	v_mul_f32_e32 v76, v76, v76
	v_mul_f32_e32 v71, v71, v71
	v_mul_f32_e32 v72, v72, v72
	v_mul_f32_e32 v59, v59, v59
	v_mul_f32_e32 v60, v60, v60
	v_mul_f32_e32 v55, v55, v55
	v_mul_f32_e32 v56, v56, v56
	v_mul_f32_e32 v51, v51, v51
	v_mul_f32_e32 v52, v52, v52
	v_mul_f32_e32 v47, v47, v47
	v_mul_f32_e32 v48, v48, v48
	v_mul_f32_e32 v43, v43, v43
	v_mul_f32_e32 v44, v44, v44
	v_mul_f32_e32 v39, v39, v39
	v_mul_f32_e32 v40, v40, v40
	v_mul_f32_e32 v27, v27, v27
	v_mul_f32_e32 v28, v28, v28
	v_mul_f32_e32 v23, v23, v23
	v_mul_f32_e32 v24, v24, v24
	v_mul_f32_e32 v19, v19, v19
	v_mul_f32_e32 v20, v20, v20
	v_mul_f32_e32 v15, v15, v15
	v_mul_f32_e32 v16, v16, v16
	v_mul_f32_e32 v11, v11, v11
	v_mul_f32_e32 v12, v12, v12
	v_mul_f32_e32 v7, v7, v7
	v_mul_f32_e32 v8, v8, v8
	v_mul_f32_e32 v0, v0, v0
	v_mul_f32_e32 v2, v2, v2
	v_mul_f32_e32 v3, v3, v3
	v_mul_f32_e32 v4, v4, v4
	v_cvt_pk_bf16_f32 v117, v117, v119
	v_cvt_pk_bf16_f32 v107, v107, v108
	v_cvt_pk_bf16_f32 v103, v103, v104
	v_cvt_pk_bf16_f32 v91, v91, v92
	v_cvt_pk_bf16_f32 v87, v87, v88
	v_cvt_pk_bf16_f32 v83, v83, v84
	v_cvt_pk_bf16_f32 v79, v79, v80
	v_cvt_pk_bf16_f32 v75, v75, v76
	v_cvt_pk_bf16_f32 v71, v71, v72
	v_cvt_pk_bf16_f32 v59, v59, v60
	v_cvt_pk_bf16_f32 v55, v55, v56
	v_cvt_pk_bf16_f32 v51, v51, v52
	v_cvt_pk_bf16_f32 v47, v47, v48
	v_cvt_pk_bf16_f32 v43, v43, v44
	v_cvt_pk_bf16_f32 v39, v39, v40
	v_lshl_add_u64 v[30:31], v[34:35], 0, v[112:113]
	v_cvt_pk_bf16_f32 v27, v27, v28
	v_cvt_pk_bf16_f32 v23, v23, v24
	v_cvt_pk_bf16_f32 v19, v19, v20
	v_cvt_pk_bf16_f32 v15, v15, v16
	v_cvt_pk_bf16_f32 v11, v11, v12
	v_cvt_pk_bf16_f32 v7, v7, v8
	v_cvt_pk_bf16_f32 v3, v3, v4
	v_cvt_pk_bf16_f32 v2, v0, v2
	s_add_i32 s4, s4, 1
	s_mov_b64 s[0:1], 0
	global_store_dwordx2 v[114:115], v[116:117], off offset:128
	global_store_dwordx2 v[114:115], v[106:107], off offset:160
	global_store_dwordx2 v[114:115], v[102:103], off offset:192
	global_store_dwordx2 v[94:95], v[96:97], off
	global_store_dwordx2 v[94:95], v[90:91], off offset:32
	global_store_dwordx2 v[94:95], v[86:87], off offset:64
	global_store_dwordx2 v[94:95], v[82:83], off offset:96
	global_store_dwordx2 v[94:95], v[78:79], off offset:128
	global_store_dwordx2 v[94:95], v[74:75], off offset:160
	global_store_dwordx2 v[94:95], v[70:71], off offset:192
	global_store_dwordx2 v[62:63], v[64:65], off
	global_store_dwordx2 v[62:63], v[58:59], off offset:32
	global_store_dwordx2 v[62:63], v[54:55], off offset:64
	global_store_dwordx2 v[62:63], v[50:51], off offset:96
	global_store_dwordx2 v[62:63], v[46:47], off offset:128
	global_store_dwordx2 v[62:63], v[42:43], off offset:160
	global_store_dwordx2 v[62:63], v[38:39], off offset:192
	global_store_dwordx2 v[30:31], v[32:33], off
	global_store_dwordx2 v[30:31], v[26:27], off offset:32
	global_store_dwordx2 v[30:31], v[22:23], off offset:64
	global_store_dwordx2 v[30:31], v[18:19], off offset:96
	global_store_dwordx2 v[30:31], v[14:15], off offset:128
	global_store_dwordx2 v[30:31], v[10:11], off offset:160
	global_store_dwordx2 v[30:31], v[6:7], off offset:192
	global_store_dwordx2 v[30:31], v[2:3], off offset:224
	s_branch .LBB0_765

; DI int ltid() { int t = threadIdx.x; asm volatile("" : "+v"(t)); return t; }
; #define GLOAD(kt) { GL1(0, kt) GL1(1, kt) GL1(2, kt) GL1(3, kt) }
; #define SSTORE(buf)                              \
;   {                                              \
;     char* as_ = smem + (buf) * BUF;              \
;     char* bs_ = as_ + ASZ;                       \
;     SS1(0) SS1(1) SS1(2) SS1(3)                  \
;   }
; template <int MT, int NT>
; DI void gemm_core(const u16* __restrict__ A, int lda, const u16* __restrict__ B, int ldb, int K,
;                   f32x4 (&acc)[MT][NT], char* smem) {
;     ...
;   const int tid = ltid(), l = tid & 63, w = tid >> 6, wm = w >> 1, wn = w & 1;
;   const int fr = l & 15, fq = l >> 4;
;   uint4 ra0, ra1, ra2, ra3, rb0, rb1, rb2, rb3;
;   const int nk = K >> 6;
;   const int srow = tid >> 3, sch = tid & 7;
;   const int ssw = sch ^ ((srow >> 1) & 7);
;   const int fsw = (fr >> 1) & 7;
;     ...
;   GLOAD(0);
;   SSTORE(0);
;   GLOAD(((1 < nk) ? 1 : 0));
; DI void phase_resgemm(const Params& p, const u16* A, int lda, const u16* W, int ldw, int K, char* smem) {
;   int rt, ct;
;   for (int it = 0; next_tile(it, 128, 4, 16, 4, rt, ct); ++it) {
;     const int r0 = rt * 256, c0 = ct * 256;
;     f32x4 acc[4][8];
;     zero_acc<4, 8>(acc);
;     gemm_core<4, 8>(A + (size_t)r0 * lda, lda, W + (size_t)c0 * ldw, ldw, K, acc, smem);
.LBB0_795:
	s_mov_b32 s0, s56
	s_mov_b32 s5, s14
	s_ashr_i32 s5, s5, 3
	s_and_b32 s1, s0, 7
	s_ashr_i32 s0, s0, 3
	s_mul_i32 s5, s5, s4
	s_add_i32 s5, s5, s0
	s_ashr_i32 s0, s5, 3
	s_and_b32 s0, s0, -8
	s_or_b32 s6, s0, s1
	s_cmp_gt_i32 s6, 7
	s_mov_b64 s[0:1], -1
	s_cbranch_scc1 .LBB0_794
	s_lshl_b32 s1, s5, 6
	s_lshl_b32 s0, s6, 12
	s_and_b32 s1, s1, 0xf00
	s_or_b32 s1, s0, s1
	s_lshl_b32 s0, s5, 8
	s_and_b32 s0, s0, 0x300
	s_mul_i32 s6, s1, 0x2080
	s_mul_hi_i32 s5, s1, 0x2080
	s_add_u32 s6, s78, s6
	s_addc_u32 s7, s79, s5
	s_mul_i32 s5, s0, 0x2080
	s_add_u32 s8, s2, s5
	v_mov_b32_e32 v34, v171
	s_addc_u32 s9, s3, 0
	v_mov_b64_e32 v[26:27], s[6:7]
	v_ashrrev_i32_e32 v35, 3, v34
	v_lshlrev_b32_e32 v36, 4, v34
	v_mov_b64_e32 v[30:31], s[8:9]
	v_add_u32_e32 v37, 64, v35
	v_add_u32_e32 v38, 0x80, v35
	v_add_u32_e32 v39, 0xc0, v35
	v_mad_i64_i32 v[2:3], s[6:7], v35, s10, v[26:27]
	v_and_b32_e32 v0, 0x70, v36
	v_mad_i64_i32 v[6:7], s[6:7], v35, s10, v[30:31]
	v_mad_i64_i32 v[10:11], s[6:7], v37, s10, v[26:27]
	v_mad_i64_i32 v[14:15], s[6:7], v37, s10, v[30:31]
	v_mad_i64_i32 v[18:19], s[6:7], v38, s10, v[26:27]
	v_mad_i64_i32 v[22:23], s[6:7], v38, s10, v[30:31]
	v_mad_i64_i32 v[26:27], s[6:7], v39, s10, v[26:27]
	v_mad_i64_i32 v[30:31], s[6:7], v39, s10, v[30:31]
	s_waitcnt vmcnt(16)
	v_lshl_add_u64 v[162:163], v[2:3], 0, v[0:1]
	v_lshl_add_u64 v[164:165], v[6:7], 0, v[0:1]
	v_lshl_add_u64 v[166:167], v[10:11], 0, v[0:1]
	v_lshl_add_u64 v[168:169], v[14:15], 0, v[0:1]
	v_lshl_add_u64 v[176:177], v[18:19], 0, v[0:1]
	v_lshl_add_u64 v[178:179], v[22:23], 0, v[0:1]
	v_lshl_add_u64 v[180:181], v[26:27], 0, v[0:1]
	s_waitcnt vmcnt(0)
	v_lshl_add_u64 v[182:183], v[30:31], 0, v[0:1]
	global_load_dwordx4 v[2:5], v[162:163], off
	global_load_dwordx4 v[6:9], v[164:165], off
	global_load_dwordx4 v[10:13], v[166:167], off
	global_load_dwordx4 v[14:17], v[168:169], off
	global_load_dwordx4 v[18:21], v[176:177], off
	global_load_dwordx4 v[22:25], v[178:179], off
	global_load_dwordx4 v[26:29], v[180:181], off
	global_load_dwordx4 v[30:33], v[182:183], off
	global_load_dwordx4 v[138:141], v[180:181], off offset:128
	global_load_dwordx4 v[130:133], v[176:177], off offset:128
	global_load_dwordx4 v[118:121], v[166:167], off offset:128
	global_load_dwordx4 v[114:117], v[162:163], off offset:128
	global_load_dwordx4 v[154:157], v[182:183], off offset:128
	global_load_dwordx4 v[142:145], v[178:179], off offset:128
	global_load_dwordx4 v[134:137], v[168:169], off offset:128
	global_load_dwordx4 v[122:125], v[164:165], off offset:128
	v_lshrrev_b32_e32 v40, 4, v34
	v_lshrrev_b32_e32 v42, 1, v34
	v_bfe_u32 v43, v34, 1, 3
	v_and_b32_e32 v44, 15, v34
	v_lshlrev_b32_e32 v45, 1, v34
	v_lshlrev_b32_e32 v0, 7, v35
	v_bitop3_b32 v173, v36, s75, v34 bitop3:0x48
	v_bfe_u32 v41, v34, 4, 2
	v_and_or_b32 v34, v42, s90, v44
	v_and_or_b32 v35, v45, s57, v44
	v_bitop3_b32 v36, v40, v43, 3 bitop3:0x6c
	v_or_b32_e32 v40, v0, v173
	v_lshlrev_b32_e32 v175, 7, v37
	v_lshlrev_b32_e32 v184, 7, v38
	v_lshlrev_b32_e32 v185, 7, v39
	v_lshlrev_b32_e32 v186, 4, v36
	v_lshlrev_b32_e32 v187, 7, v34
	v_lshlrev_b32_e32 v188, 7, v35
	v_or_b32_e32 v34, v175, v173
	v_or_b32_e32 v35, v184, v173
	v_or_b32_e32 v36, v185, v173
	s_mov_b32 s5, 0
	s_mov_b32 s6, 0
	s_waitcnt vmcnt(15)
	ds_write_b128 v40, v[2:5]
	s_waitcnt vmcnt(13)
	ds_write_b128 v34, v[10:13]
	s_waitcnt vmcnt(11)
	ds_write_b128 v35, v[18:21]
	s_waitcnt vmcnt(9)
	ds_write_b128 v36, v[26:29]
	ds_write_b128 v40, v[6:9] offset:32768
	ds_write_b128 v34, v[14:17] offset:32768
	ds_write_b128 v35, v[22:25] offset:32768
	s_waitcnt vmcnt(8)
	ds_write_b128 v36, v[30:33] offset:32768
	v_bitop3_b32 v2, v41, v43, 4 bitop3:0x36
	v_lshlrev_b32_e32 v189, 4, v2
	v_mov_b32_e32 v2, 0
	v_mov_b32_e32 v3, v2
	v_mov_b32_e32 v4, v2
	v_mov_b32_e32 v5, v2
	v_mov_b32_e32 v6, v2
	v_mov_b32_e32 v7, v2
	v_mov_b32_e32 v8, v2
	v_mov_b32_e32 v9, v2
	v_mov_b32_e32 v10, v2
	v_mov_b32_e32 v11, v2
	v_mov_b32_e32 v12, v2
	v_mov_b32_e32 v13, v2
	v_mov_b32_e32 v14, v2
	v_mov_b32_e32 v15, v2
	v_mov_b32_e32 v16, v2
	v_mov_b32_e32 v17, v2
	v_mov_b32_e32 v18, v2
	v_mov_b32_e32 v19, v2
	v_mov_b32_e32 v20, v2
	v_mov_b32_e32 v21, v2
	v_mov_b32_e32 v22, v2
	v_mov_b32_e32 v23, v2
	v_mov_b32_e32 v24, v2
	v_mov_b32_e32 v25, v2
	v_mov_b32_e32 v26, v2
	v_mov_b32_e32 v27, v2
	v_mov_b32_e32 v28, v2
	v_mov_b32_e32 v29, v2
	v_mov_b32_e32 v30, v2
	v_mov_b32_e32 v31, v2
	v_mov_b32_e32 v32, v2
	v_mov_b32_e32 v33, v2
	v_mov_b32_e32 v34, v2
	v_mov_b32_e32 v35, v2
	v_mov_b32_e32 v36, v2
	v_mov_b32_e32 v37, v2
	v_mov_b32_e32 v38, v2
	v_mov_b32_e32 v39, v2
	v_mov_b32_e32 v40, v2
	v_mov_b32_e32 v41, v2
	v_mov_b32_e32 v42, v2
	v_mov_b32_e32 v43, v2
	v_mov_b32_e32 v44, v2
	v_mov_b32_e32 v45, v2
	v_mov_b32_e32 v46, v2
	v_mov_b32_e32 v47, v2
	v_mov_b32_e32 v48, v2
	v_mov_b32_e32 v49, v2
	v_mov_b32_e32 v50, v2
	v_mov_b32_e32 v51, v2
	v_mov_b32_e32 v52, v2
	v_mov_b32_e32 v53, v2
	v_mov_b32_e32 v54, v2
	v_mov_b32_e32 v55, v2
	v_mov_b32_e32 v56, v2
	v_mov_b32_e32 v57, v2
	v_mov_b32_e32 v58, v2
	v_mov_b32_e32 v59, v2
	v_mov_b32_e32 v60, v2
	v_mov_b32_e32 v61, v2
	v_mov_b32_e32 v62, v2
	v_mov_b32_e32 v63, v2
	v_mov_b32_e32 v64, v2
	v_mov_b32_e32 v65, v2
	v_mov_b32_e32 v66, v2
	v_mov_b32_e32 v67, v2
	v_mov_b32_e32 v68, v2
	v_mov_b32_e32 v69, v2
	v_mov_b32_e32 v70, v2
	v_mov_b32_e32 v71, v2
	v_mov_b32_e32 v72, v2
	v_mov_b32_e32 v73, v2
	v_mov_b32_e32 v74, v2
	v_mov_b32_e32 v75, v2
	v_mov_b32_e32 v76, v2
	v_mov_b32_e32 v77, v2
	v_mov_b32_e32 v78, v2
	v_mov_b32_e32 v79, v2
	v_mov_b32_e32 v80, v2
	v_mov_b32_e32 v81, v2
	v_mov_b32_e32 v82, v2
	v_mov_b32_e32 v83, v2
	v_mov_b32_e32 v84, v2
	v_mov_b32_e32 v85, v2
	v_mov_b32_e32 v86, v2
	v_mov_b32_e32 v87, v2
	v_mov_b32_e32 v88, v2
	v_mov_b32_e32 v89, v2
	v_mov_b32_e32 v90, v2
	v_mov_b32_e32 v91, v2
	v_mov_b32_e32 v92, v2
	v_mov_b32_e32 v93, v2
	v_mov_b32_e32 v94, v2
	v_mov_b32_e32 v95, v2
	v_mov_b32_e32 v96, v2
	v_mov_b32_e32 v97, v2
	v_mov_b32_e32 v98, v2
	v_mov_b32_e32 v99, v2
	v_mov_b32_e32 v100, v2
	v_mov_b32_e32 v101, v2
	v_mov_b32_e32 v102, v2
	v_mov_b32_e32 v103, v2
	v_mov_b32_e32 v104, v2
	v_mov_b32_e32 v105, v2
	v_mov_b32_e32 v106, v2
	v_mov_b32_e32 v107, v2
	v_mov_b32_e32 v108, v2
	v_mov_b32_e32 v109, v2
	v_mov_b32_e32 v110, v2
	v_mov_b32_e32 v111, v2
	v_mov_b32_e32 v112, v2
	v_mov_b32_e32 v113, v2
	v_mov_b32_e32 v126, v2
	v_mov_b32_e32 v127, v2
	v_mov_b32_e32 v128, v2
	v_mov_b32_e32 v129, v2
	v_mov_b32_e32 v146, v2
	v_mov_b32_e32 v147, v2
	v_mov_b32_e32 v148, v2
	v_mov_b32_e32 v149, v2
	v_mov_b32_e32 v150, v2
	v_mov_b32_e32 v151, v2
	v_mov_b32_e32 v152, v2
	v_mov_b32_e32 v153, v2
	v_mov_b32_e32 v158, v2
	v_mov_b32_e32 v159, v2
	v_mov_b32_e32 v160, v2
	v_mov_b32_e32 v161, v2
	s_waitcnt lgkmcnt(0)
	s_barrier
; DI f32x4 mfma16(bf16x8 a, bf16x8 b, f32x4 c) { return __builtin_amdgcn_mfma_f32_16x16x32_bf16(a, b, c, 0, 0, 0); }
; #define GLOAD(kt) { GL1(0, kt) GL1(1, kt) GL1(2, kt) GL1(3, kt) }
; #define SSTORE(buf)                              \
;   {                                              \
;     char* as_ = smem + (buf) * BUF;              \
;     char* bs_ = as_ + ASZ;                       \
;     SS1(0) SS1(1) SS1(2) SS1(3)                  \
;   }
; template <int MT, int NT>
; DI void gemm_core(const u16* __restrict__ A, int lda, const u16* __restrict__ B, int ldb, int K,
;                   f32x4 (&acc)[MT][NT], char* smem) {
;     ...
;   GLOAD(0);
;   SSTORE(0);
;   GLOAD(((1 < nk) ? 1 : 0));
; #pragma unroll 1
;   for (int kt = 0; kt < nk; ++kt) {
;     __syncthreads();
;     SSTORE((kt + 1) & 1);
;     { const int kn_ = (kt + 2 < nk) ? kt + 2 : nk - 1; GLOAD(kn_); }
;     const char* as = smem + (kt & 1) * BUF;
;     const char* bs = as + ASZ;
; #pragma unroll
;     for (int kk = 0; kk < 2; ++kk) {
;       bf16x8 xf[MT], wf[NT];
; #pragma unroll
;       for (int mi = 0; mi < MT; ++mi)
;         xf[mi] = *(const bf16x8*)(as + (wm * (MT * 16) + mi * 16 + fr) * 128 + (((kk * 4 + fq) ^ fsw) * 16));
; #pragma unroll
;       for (int ni = 0; ni < NT; ++ni)
;         wf[ni] = *(const bf16x8*)(bs + (wn * (NT * 16) + ni * 16 + fr) * 128 + (((kk * 4 + fq) ^ fsw) * 16));
;       __builtin_amdgcn_s_setprio(1);
; #pragma unroll
;       for (int mi = 0; mi < MT; ++mi)
; #pragma unroll
;         for (int ni = 0; ni < NT; ++ni) acc[mi][ni] = mfma16(wf[ni], xf[mi], acc[mi][ni]);
;       __builtin_amdgcn_s_setprio(0);
;     }
;   }
	v_add_u32_e32 v207, v186, v188
	v_add_u32_e32 v206, v186, v187
	ds_read_b128 v[190:193], v206
	ds_read_b128 v[208:211], v206 offset:2048
	ds_read_b128 v[212:215], v206 offset:4096
	ds_read_b128 v[216:219], v206 offset:6144
	ds_read_b128 v[220:223], v207 offset:32768
	ds_read_b128 v[224:227], v207 offset:34816
	ds_read_b128 v[228:231], v207 offset:36864
	ds_read_b128 v[232:235], v207 offset:38912
	ds_read_b128 v[236:239], v207 offset:40960
	ds_read_b128 v[240:243], v207 offset:43008
	ds_read_b128 v[244:247], v207 offset:45056
	ds_read_b128 v[248:251], v207 offset:47104
	s_waitcnt lgkmcnt(0)
.LBB0_797:
	s_add_i32 s8, s5, 0x10000
	s_and_b32 s9, s8, 0x10000
	s_add_i32 s7, s6, 1
	s_min_u32 s6, s6, 61
	s_lshl_b32 s54, s6, 7
	s_and_b32 s5, s5, 0x10000
	v_or_b32_e32 v206, s5, v189
	v_add_u32_e32 v207, v206, v188
	v_add_u32_e32 v206, v206, v187
	v_add3_u32 v170, s9, v0, v173
	s_waitcnt lgkmcnt(10)
	v_mfma_f32_16x16x32_bf16 v[158:161], v[220:223], v[190:193], v[158:161]
	s_waitcnt vmcnt(0)
	ds_write_b128 v170, v[114:117]
	s_waitcnt lgkmcnt(10)
	v_mfma_f32_16x16x32_bf16 v[94:97], v[220:223], v[208:211], v[94:97]
	v_lshl_add_u64 v[114:115], v[162:163], 0, s[54:55]
	global_load_dwordx4 v[114:117], v[114:115], off offset:256
	s_waitcnt lgkmcnt(8)
	v_mfma_f32_16x16x32_bf16 v[62:65], v[220:223], v[212:215], v[62:65]
	ds_write_b128 v170, v[122:125] offset:32768
	s_waitcnt lgkmcnt(3)
	v_mfma_f32_16x16x32_bf16 v[30:33], v[220:223], v[216:219], v[30:33]
	v_lshl_add_u64 v[122:123], v[164:165], 0, s[54:55]
	global_load_dwordx4 v[122:125], v[122:123], off offset:256
	ds_read_b128 v[194:197], v206
	v_mfma_f32_16x16x32_bf16 v[150:153], v[224:227], v[190:193], v[150:153]
	ds_read_b128 v[220:223], v207 offset:32768
	ds_write_b128 v170, v[118:121] offset:8192
	v_mfma_f32_16x16x32_bf16 v[90:93], v[224:227], v[208:211], v[90:93]
	v_lshl_add_u64 v[118:119], v[166:167], 0, s[54:55]
	global_load_dwordx4 v[118:121], v[118:119], off offset:256
	v_mfma_f32_16x16x32_bf16 v[58:61], v[224:227], v[212:215], v[58:61]
	ds_write_b128 v170, v[134:137] offset:40960
	v_mfma_f32_16x16x32_bf16 v[26:29], v[224:227], v[216:219], v[26:29]
	v_lshl_add_u64 v[134:135], v[168:169], 0, s[54:55]
	global_load_dwordx4 v[134:137], v[134:135], off offset:256
	ds_read_b128 v[198:201], v206 offset:2048
	v_mfma_f32_16x16x32_bf16 v[146:149], v[228:231], v[190:193], v[146:149]
	ds_read_b128 v[224:227], v207 offset:34816
	ds_write_b128 v170, v[130:133] offset:16384
	v_mfma_f32_16x16x32_bf16 v[86:89], v[228:231], v[208:211], v[86:89]
	v_lshl_add_u64 v[130:131], v[176:177], 0, s[54:55]
	global_load_dwordx4 v[130:133], v[130:131], off offset:256
	v_mfma_f32_16x16x32_bf16 v[54:57], v[228:231], v[212:215], v[54:57]
	ds_write_b128 v170, v[142:145] offset:49152
	v_mfma_f32_16x16x32_bf16 v[22:25], v[228:231], v[216:219], v[22:25]
	v_lshl_add_u64 v[142:143], v[178:179], 0, s[54:55]
	global_load_dwordx4 v[142:145], v[142:143], off offset:256
	ds_read_b128 v[202:205], v206 offset:4096
	v_mfma_f32_16x16x32_bf16 v[126:129], v[232:235], v[190:193], v[126:129]
	ds_read_b128 v[228:231], v207 offset:36864
	ds_write_b128 v170, v[138:141] offset:24576
	v_mfma_f32_16x16x32_bf16 v[82:85], v[232:235], v[208:211], v[82:85]
	v_lshl_add_u64 v[138:139], v[180:181], 0, s[54:55]
	global_load_dwordx4 v[138:141], v[138:139], off offset:256
	v_mfma_f32_16x16x32_bf16 v[50:53], v[232:235], v[212:215], v[50:53]
	ds_write_b128 v170, v[154:157] offset:57344
	v_mfma_f32_16x16x32_bf16 v[18:21], v[232:235], v[216:219], v[18:21]
	v_lshl_add_u64 v[154:155], v[182:183], 0, s[54:55]
	global_load_dwordx4 v[154:157], v[154:155], off offset:256
	v_mfma_f32_16x16x32_bf16 v[110:113], v[236:239], v[190:193], v[110:113]
	ds_read_b128 v[232:235], v207 offset:38912
	v_mfma_f32_16x16x32_bf16 v[78:81], v[236:239], v[208:211], v[78:81]
	v_mfma_f32_16x16x32_bf16 v[46:49], v[236:239], v[212:215], v[46:49]
	v_mfma_f32_16x16x32_bf16 v[14:17], v[236:239], v[216:219], v[14:17]
	v_mfma_f32_16x16x32_bf16 v[106:109], v[240:243], v[190:193], v[106:109]
	ds_read_b128 v[236:239], v207 offset:40960
	v_mfma_f32_16x16x32_bf16 v[74:77], v[240:243], v[208:211], v[74:77]
	v_mfma_f32_16x16x32_bf16 v[42:45], v[240:243], v[212:215], v[42:45]
	v_mfma_f32_16x16x32_bf16 v[10:13], v[240:243], v[216:219], v[10:13]
	v_mfma_f32_16x16x32_bf16 v[102:105], v[244:247], v[190:193], v[102:105]
	ds_read_b128 v[240:243], v207 offset:43008
	v_mfma_f32_16x16x32_bf16 v[70:73], v[244:247], v[208:211], v[70:73]
	v_mfma_f32_16x16x32_bf16 v[38:41], v[244:247], v[212:215], v[38:41]
	v_mfma_f32_16x16x32_bf16 v[6:9], v[244:247], v[216:219], v[6:9]
	s_waitcnt lgkmcnt(15)
	v_mfma_f32_16x16x32_bf16 v[2:5], v[248:251], v[216:219], v[2:5]
	ds_read_b128 v[244:247], v207 offset:45056
	ds_read_b128 v[216:219], v206 offset:6144
	v_mfma_f32_16x16x32_bf16 v[98:101], v[248:251], v[190:193], v[98:101]
	v_mfma_f32_16x16x32_bf16 v[66:69], v[248:251], v[208:211], v[66:69]
	v_mfma_f32_16x16x32_bf16 v[34:37], v[248:251], v[212:215], v[34:37]
	ds_read_b128 v[248:251], v207 offset:47104
	s_waitcnt lgkmcnt(6)
	s_barrier
;   __device__ __forceinline__ u16* XB() const { return (u16*)(ws + O_XB); }
; DI float bflo(u32 v) { return __uint_as_float(v << 16); }
; DI float bfhi(u32 v) { return __uint_as_float(v & 0xffff0000u); }
; DI f32x4 mfma16(bf16x8 a, bf16x8 b, f32x4 c) { return __builtin_amdgcn_mfma_f32_16x16x32_bf16(a, b, c, 0, 0, 0); }
; #define GLOAD(kt) { GL1(0, kt) GL1(1, kt) GL1(2, kt) GL1(3, kt) }
; #define SSTORE(buf)                              \
;   {                                              \
;     char* as_ = smem + (buf) * BUF;              \
;     char* bs_ = as_ + ASZ;                       \
;     SS1(0) SS1(1) SS1(2) SS1(3)                  \
;   }
; template <int MT, int NT>
; DI void gemm_core(const u16* __restrict__ A, int lda, const u16* __restrict__ B, int ldb, int K,
;                   f32x4 (&acc)[MT][NT], char* smem) {
;     ...
;   for (int kt = 0; kt < nk; ++kt) {
;     __syncthreads();
;     SSTORE((kt + 1) & 1);
;     { const int kn_ = (kt + 2 < nk) ? kt + 2 : nk - 1; GLOAD(kn_); }
;     const char* as = smem + (kt & 1) * BUF;
;     const char* bs = as + ASZ;
; #pragma unroll
;     for (int kk = 0; kk < 2; ++kk) {
;       bf16x8 xf[MT], wf[NT];
; #pragma unroll
;       for (int mi = 0; mi < MT; ++mi)
;         xf[mi] = *(const bf16x8*)(as + (wm * (MT * 16) + mi * 16 + fr) * 128 + (((kk * 4 + fq) ^ fsw) * 16));
; #pragma unroll
;       for (int ni = 0; ni < NT; ++ni)
;         wf[ni] = *(const bf16x8*)(bs + (wn * (NT * 16) + ni * 16 + fr) * 128 + (((kk * 4 + fq) ^ fsw) * 16));
;       __builtin_amdgcn_s_setprio(1);
; #pragma unroll
;       for (int mi = 0; mi < MT; ++mi)
; #pragma unroll
;         for (int ni = 0; ni < NT; ++ni) acc[mi][ni] = mfma16(wf[ni], xf[mi], acc[mi][ni]);
;       __builtin_amdgcn_s_setprio(0);
;     }
;   }
;   __syncthreads();
; DI void phase_resgemm(const Params& p, const u16* A, int lda, const u16* W, int ldw, int K, char* smem) {
;     ...
;     EPI_LOOP(4, 8) {
;       const int row = r0 + wm_ * 64 + mi * 16 + fr_, col = c0 + wn_ * 128 + ni * 16 + fq_ * 4;
;       const uint2 xb = *(const uint2*)(p.XB() + (size_t)row * LDX + col);
;       float4 o;
;       o.x = DN_ALPHA * bflo(xb.x) + acc[mi][ni][0]; o.y = DN_ALPHA * bfhi(xb.x) + acc[mi][ni][1];
;       o.z = DN_ALPHA * bflo(xb.y) + acc[mi][ni][2]; o.w = DN_ALPHA * bfhi(xb.y) + acc[mi][ni][3];
;       *(float4*)(p.out + (size_t)row * 1024 + col) = o;
;     }
	v_or_b32_e32 v206, s9, v186
	v_add_u32_e32 v207, v206, v188
	v_add_u32_e32 v206, v206, v187
	v_mfma_f32_16x16x32_bf16 v[158:161], v[220:223], v[194:197], v[158:161]
	v_mfma_f32_16x16x32_bf16 v[94:97], v[220:223], v[198:201], v[94:97]
	v_mfma_f32_16x16x32_bf16 v[62:65], v[220:223], v[202:205], v[62:65]
	s_waitcnt lgkmcnt(1)
	v_mfma_f32_16x16x32_bf16 v[30:33], v[220:223], v[216:219], v[30:33]
	ds_read_b128 v[190:193], v206
	v_mfma_f32_16x16x32_bf16 v[150:153], v[224:227], v[194:197], v[150:153]
	ds_read_b128 v[220:223], v207 offset:32768
	v_mfma_f32_16x16x32_bf16 v[90:93], v[224:227], v[198:201], v[90:93]
	v_mfma_f32_16x16x32_bf16 v[58:61], v[224:227], v[202:205], v[58:61]
	v_mfma_f32_16x16x32_bf16 v[26:29], v[224:227], v[216:219], v[26:29]
	ds_read_b128 v[208:211], v206 offset:2048
	v_mfma_f32_16x16x32_bf16 v[146:149], v[228:231], v[194:197], v[146:149]
	ds_read_b128 v[224:227], v207 offset:34816
	v_mfma_f32_16x16x32_bf16 v[86:89], v[228:231], v[198:201], v[86:89]
	v_mfma_f32_16x16x32_bf16 v[54:57], v[228:231], v[202:205], v[54:57]
	v_mfma_f32_16x16x32_bf16 v[22:25], v[228:231], v[216:219], v[22:25]
	ds_read_b128 v[212:215], v206 offset:4096
	v_mfma_f32_16x16x32_bf16 v[126:129], v[232:235], v[194:197], v[126:129]
	ds_read_b128 v[228:231], v207 offset:36864
	v_mfma_f32_16x16x32_bf16 v[82:85], v[232:235], v[198:201], v[82:85]
	v_mfma_f32_16x16x32_bf16 v[50:53], v[232:235], v[202:205], v[50:53]
	v_mfma_f32_16x16x32_bf16 v[18:21], v[232:235], v[216:219], v[18:21]
	v_mfma_f32_16x16x32_bf16 v[110:113], v[236:239], v[194:197], v[110:113]
	ds_read_b128 v[232:235], v207 offset:38912
	v_mfma_f32_16x16x32_bf16 v[78:81], v[236:239], v[198:201], v[78:81]
	v_mfma_f32_16x16x32_bf16 v[46:49], v[236:239], v[202:205], v[46:49]
	v_mfma_f32_16x16x32_bf16 v[14:17], v[236:239], v[216:219], v[14:17]
	v_mfma_f32_16x16x32_bf16 v[106:109], v[240:243], v[194:197], v[106:109]
	ds_read_b128 v[236:239], v207 offset:40960
	v_mfma_f32_16x16x32_bf16 v[74:77], v[240:243], v[198:201], v[74:77]
	v_mfma_f32_16x16x32_bf16 v[42:45], v[240:243], v[202:205], v[42:45]
	v_mfma_f32_16x16x32_bf16 v[10:13], v[240:243], v[216:219], v[10:13]
	v_mfma_f32_16x16x32_bf16 v[102:105], v[244:247], v[194:197], v[102:105]
	ds_read_b128 v[240:243], v207 offset:43008
	v_mfma_f32_16x16x32_bf16 v[70:73], v[244:247], v[198:201], v[70:73]
	v_mfma_f32_16x16x32_bf16 v[38:41], v[244:247], v[202:205], v[38:41]
	v_mfma_f32_16x16x32_bf16 v[6:9], v[244:247], v[216:219], v[6:9]
	s_waitcnt lgkmcnt(9)
	v_mfma_f32_16x16x32_bf16 v[2:5], v[248:251], v[216:219], v[2:5]
	ds_read_b128 v[244:247], v207 offset:45056
	ds_read_b128 v[216:219], v206 offset:6144
	v_mfma_f32_16x16x32_bf16 v[98:101], v[248:251], v[194:197], v[98:101]
	v_mfma_f32_16x16x32_bf16 v[66:69], v[248:251], v[198:201], v[66:69]
	v_mfma_f32_16x16x32_bf16 v[34:37], v[248:251], v[202:205], v[34:37]
	ds_read_b128 v[248:251], v207 offset:47104
	s_cmp_lg_u32 s7, 64
	s_mov_b32 s5, s8
	s_mov_b32 s6, s7
	s_cbranch_scc1 .LBB0_797
	s_waitcnt vmcnt(0) lgkmcnt(0)
	v_mov_b32_e32 v170, 0x358637bd
	v_mov_b32_e32 v194, 0x25a08
	v_mbcnt_lo_u32_b32 v195, -1, 0
	v_mbcnt_hi_u32_b32 v196, -1, v195
	v_mov_b32_e32 v197, 0x24000
	v_mov_b32_e32 v198, 0x1fa0
	v_mov_b32_e32 v199, 0x41b17218
	v_mov_b32_e32 v200, 0x7e800
	v_mov_b32_e32 v201, 0xfd0
	v_mov_b32_e32 v202, 0x100
	v_mov_b32_e32 v203, 0x200
	v_mov_b32_e32 v204, 0x7f61b1e6
	v_mov_b32_e32 v205, 0xff800000
	v_mov_b32_e32 v206, 0x3f80
	v_mov_b32_e32 v207, 0x1d400
	v_mov_b32_e32 v0, v171
	s_waitcnt vmcnt(7)
	v_mov_b32_e32 v115, v171
	s_barrier
	s_waitcnt vmcnt(5)
	v_mov_b64_e32 v[118:119], s[60:61]
	v_ashrrev_i32_e32 v114, 1, v115
	v_and_b32_e32 v114, 0xffffffc0, v114
	v_add_u32_e32 v114, s1, v114
	v_and_or_b32 v114, v0, 15, v114
	v_lshlrev_b32_e32 v115, 1, v115
	v_lshrrev_b32_e32 v0, 2, v0
	v_and_b32_e32 v115, 0x80, v115
	v_and_b32_e32 v0, 12, v0
	v_or3_b32 v115, v0, v115, s0
	v_mad_i64_i32 v[116:117], s[0:1], v114, s59, v[118:119]
	v_lshlrev_b32_e32 v0, 1, v115
	v_lshl_add_u64 v[124:125], v[116:117], 0, v[0:1]
	global_load_dwordx2 v[120:121], v[124:125], off
	v_lshlrev_b32_e32 v116, 2, v115
	v_ashrrev_i32_e32 v115, 31, v114
	v_lshlrev_b64 v[122:123], 12, v[114:115]
	v_mov_b32_e32 v117, v1
	v_lshl_add_u64 v[122:123], s[86:87], 0, v[122:123]
	s_waitcnt vmcnt(4)
	v_lshl_add_u64 v[130:131], v[122:123], 0, v[116:117]
	s_add_i32 s4, s4, 1
	s_waitcnt vmcnt(0)
	v_lshlrev_b32_e32 v122, 16, v120
	v_and_b32_e32 v123, 0xffff0000, v120
	v_lshlrev_b32_e32 v132, 16, v121
	v_and_b32_e32 v133, 0xffff0000, v121
	v_pk_fma_f32 v[120:121], v[122:123], s[74:75], v[158:159] op_sel_hi:[1,0,1]
	v_pk_fma_f32 v[122:123], v[132:133], s[74:75], v[160:161] op_sel_hi:[1,0,1]
	global_store_dwordx4 v[130:131], v[120:123], off
	global_load_dwordx2 v[120:121], v[124:125], off offset:32
	s_waitcnt vmcnt(0)
	v_lshlrev_b32_e32 v132, 16, v121
	v_lshlrev_b32_e32 v122, 16, v120
	v_and_b32_e32 v123, 0xffff0000, v120
	v_and_b32_e32 v133, 0xffff0000, v121
	v_pk_fma_f32 v[120:121], v[122:123], s[74:75], v[150:151] op_sel_hi:[1,0,1]
	v_pk_fma_f32 v[122:123], v[132:133], s[74:75], v[152:153] op_sel_hi:[1,0,1]
	global_store_dwordx4 v[130:131], v[120:123], off offset:64
	global_load_dwordx2 v[120:121], v[124:125], off offset:64
	s_waitcnt vmcnt(0)
	v_lshlrev_b32_e32 v132, 16, v121
	v_lshlrev_b32_e32 v122, 16, v120
	v_and_b32_e32 v123, 0xffff0000, v120
	v_and_b32_e32 v133, 0xffff0000, v121
	v_pk_fma_f32 v[120:121], v[122:123], s[74:75], v[146:147] op_sel_hi:[1,0,1]
	v_pk_fma_f32 v[122:123], v[132:133], s[74:75], v[148:149] op_sel_hi:[1,0,1]
	global_store_dwordx4 v[130:131], v[120:123], off offset:128
	global_load_dwordx2 v[120:121], v[124:125], off offset:96
	s_waitcnt vmcnt(0)
;   __device__ __forceinline__ u16* XB() const { return (u16*)(ws + O_XB); }
; DI float bflo(u32 v) { return __uint_as_float(v << 16); }
; DI float bfhi(u32 v) { return __uint_as_float(v & 0xffff0000u); }
; #define EPI_LOOP(MT_, NT_)                                                \
;   const int l_ = ltid() & 63, w_ = ltid() >> 6;                           \
;   const int wm_ = w_ >> 1, wn_ = w_ & 1, fr_ = l_ & 15, fq_ = l_ >> 4;    \
;   _Pragma("unroll") for (int mi = 0; mi < MT_; ++mi)                      \
;   _Pragma("unroll") for (int ni = 0; ni < NT_; ++ni)
; DI void phase_resgemm(const Params& p, const u16* A, int lda, const u16* W, int ldw, int K, char* smem) {
;     ...
;     EPI_LOOP(4, 8) {
;       const int row = r0 + wm_ * 64 + mi * 16 + fr_, col = c0 + wn_ * 128 + ni * 16 + fq_ * 4;
;       const uint2 xb = *(const uint2*)(p.XB() + (size_t)row * LDX + col);
;       float4 o;
;       o.x = DN_ALPHA * bflo(xb.x) + acc[mi][ni][0]; o.y = DN_ALPHA * bfhi(xb.x) + acc[mi][ni][1];
;       o.z = DN_ALPHA * bflo(xb.y) + acc[mi][ni][2]; o.w = DN_ALPHA * bfhi(xb.y) + acc[mi][ni][3];
;       *(float4*)(p.out + (size_t)row * 1024 + col) = o;
;     }
	v_lshlrev_b32_e32 v132, 16, v121
	v_lshlrev_b32_e32 v122, 16, v120
	v_and_b32_e32 v123, 0xffff0000, v120
	v_and_b32_e32 v133, 0xffff0000, v121
	v_pk_fma_f32 v[120:121], v[122:123], s[74:75], v[126:127] op_sel_hi:[1,0,1]
	v_pk_fma_f32 v[122:123], v[132:133], s[74:75], v[128:129] op_sel_hi:[1,0,1]
	global_store_dwordx4 v[130:131], v[120:123], off offset:192
	global_load_dwordx2 v[120:121], v[124:125], off offset:128
	s_waitcnt vmcnt(0)
	v_lshlrev_b32_e32 v122, 16, v120
	v_and_b32_e32 v123, 0xffff0000, v120
	v_lshlrev_b32_e32 v120, 16, v121
	v_and_b32_e32 v121, 0xffff0000, v121
	v_pk_fma_f32 v[110:111], v[122:123], s[74:75], v[110:111] op_sel_hi:[1,0,1]
	v_pk_fma_f32 v[112:113], v[120:121], s[74:75], v[112:113] op_sel_hi:[1,0,1]
	global_store_dwordx4 v[130:131], v[110:113], off offset:256
	global_load_dwordx2 v[110:111], v[124:125], off offset:160
	s_waitcnt vmcnt(0)
	v_lshlrev_b32_e32 v112, 16, v110
	v_and_b32_e32 v113, 0xffff0000, v110
	v_lshlrev_b32_e32 v110, 16, v111
	v_and_b32_e32 v111, 0xffff0000, v111
	v_pk_fma_f32 v[106:107], v[112:113], s[74:75], v[106:107] op_sel_hi:[1,0,1]
	v_pk_fma_f32 v[108:109], v[110:111], s[74:75], v[108:109] op_sel_hi:[1,0,1]
	global_store_dwordx4 v[130:131], v[106:109], off offset:320
	global_load_dwordx2 v[106:107], v[124:125], off offset:192
	s_waitcnt vmcnt(0)
	v_lshlrev_b32_e32 v108, 16, v106
	v_and_b32_e32 v109, 0xffff0000, v106
	v_lshlrev_b32_e32 v106, 16, v107
	v_and_b32_e32 v107, 0xffff0000, v107
	v_pk_fma_f32 v[102:103], v[108:109], s[74:75], v[102:103] op_sel_hi:[1,0,1]
	v_pk_fma_f32 v[104:105], v[106:107], s[74:75], v[104:105] op_sel_hi:[1,0,1]
	global_store_dwordx4 v[130:131], v[102:105], off offset:384
	global_load_dwordx2 v[102:103], v[124:125], off offset:224
	s_waitcnt vmcnt(0)
	v_lshlrev_b32_e32 v108, 16, v102
	v_or_b32_e32 v104, 16, v114
	v_and_b32_e32 v109, 0xffff0000, v102
	v_lshlrev_b32_e32 v102, 16, v103
	v_and_b32_e32 v103, 0xffff0000, v103
	v_mad_i64_i32 v[106:107], s[0:1], v104, s59, v[118:119]
	v_pk_fma_f32 v[98:99], v[108:109], s[74:75], v[98:99] op_sel_hi:[1,0,1]
	v_pk_fma_f32 v[100:101], v[102:103], s[74:75], v[100:101] op_sel_hi:[1,0,1]
	v_lshl_add_u64 v[106:107], v[106:107], 0, v[0:1]
	global_store_dwordx4 v[130:131], v[98:101], off offset:448
	global_load_dwordx2 v[98:99], v[106:107], off
	v_ashrrev_i32_e32 v105, 31, v104
	v_lshlrev_b64 v[100:101], 12, v[104:105]
	v_lshl_add_u64 v[100:101], s[86:87], 0, v[100:101]
	v_lshl_add_u64 v[100:101], v[100:101], 0, v[116:117]
	s_waitcnt vmcnt(0)
	v_lshlrev_b32_e32 v102, 16, v98
	v_and_b32_e32 v103, 0xffff0000, v98
	v_lshlrev_b32_e32 v98, 16, v99
	v_and_b32_e32 v99, 0xffff0000, v99
	v_pk_fma_f32 v[94:95], v[102:103], s[74:75], v[94:95] op_sel_hi:[1,0,1]
	v_pk_fma_f32 v[96:97], v[98:99], s[74:75], v[96:97] op_sel_hi:[1,0,1]
	global_store_dwordx4 v[100:101], v[94:97], off
	global_load_dwordx2 v[94:95], v[106:107], off offset:32
	s_waitcnt vmcnt(0)
	v_lshlrev_b32_e32 v96, 16, v94
	v_and_b32_e32 v97, 0xffff0000, v94
	v_lshlrev_b32_e32 v94, 16, v95
	v_and_b32_e32 v95, 0xffff0000, v95
	v_pk_fma_f32 v[90:91], v[96:97], s[74:75], v[90:91] op_sel_hi:[1,0,1]
	v_pk_fma_f32 v[92:93], v[94:95], s[74:75], v[92:93] op_sel_hi:[1,0,1]
	global_store_dwordx4 v[100:101], v[90:93], off offset:64
	global_load_dwordx2 v[90:91], v[106:107], off offset:64
	s_waitcnt vmcnt(0)
	v_lshlrev_b32_e32 v92, 16, v90
	v_and_b32_e32 v93, 0xffff0000, v90
	v_lshlrev_b32_e32 v90, 16, v91
	v_and_b32_e32 v91, 0xffff0000, v91
	v_pk_fma_f32 v[86:87], v[92:93], s[74:75], v[86:87] op_sel_hi:[1,0,1]
	v_pk_fma_f32 v[88:89], v[90:91], s[74:75], v[88:89] op_sel_hi:[1,0,1]
	global_store_dwordx4 v[100:101], v[86:89], off offset:128
	global_load_dwordx2 v[86:87], v[106:107], off offset:96
	s_waitcnt vmcnt(0)
	v_lshlrev_b32_e32 v88, 16, v86
	v_and_b32_e32 v89, 0xffff0000, v86
	v_lshlrev_b32_e32 v86, 16, v87
	v_and_b32_e32 v87, 0xffff0000, v87
	v_pk_fma_f32 v[82:83], v[88:89], s[74:75], v[82:83] op_sel_hi:[1,0,1]
	v_pk_fma_f32 v[84:85], v[86:87], s[74:75], v[84:85] op_sel_hi:[1,0,1]
	global_store_dwordx4 v[100:101], v[82:85], off offset:192
	global_load_dwordx2 v[82:83], v[106:107], off offset:128
	s_waitcnt vmcnt(0)
	v_lshlrev_b32_e32 v84, 16, v82
	v_and_b32_e32 v85, 0xffff0000, v82
	v_lshlrev_b32_e32 v82, 16, v83
	v_and_b32_e32 v83, 0xffff0000, v83
	v_pk_fma_f32 v[78:79], v[84:85], s[74:75], v[78:79] op_sel_hi:[1,0,1]
	v_pk_fma_f32 v[80:81], v[82:83], s[74:75], v[80:81] op_sel_hi:[1,0,1]
	global_store_dwordx4 v[100:101], v[78:81], off offset:256
	global_load_dwordx2 v[78:79], v[106:107], off offset:160
	s_waitcnt vmcnt(0)
	v_lshlrev_b32_e32 v80, 16, v78
	v_and_b32_e32 v81, 0xffff0000, v78
	v_lshlrev_b32_e32 v78, 16, v79
	v_and_b32_e32 v79, 0xffff0000, v79
	v_pk_fma_f32 v[74:75], v[80:81], s[74:75], v[74:75] op_sel_hi:[1,0,1]
	v_pk_fma_f32 v[76:77], v[78:79], s[74:75], v[76:77] op_sel_hi:[1,0,1]
	global_store_dwordx4 v[100:101], v[74:77], off offset:320
	global_load_dwordx2 v[74:75], v[106:107], off offset:192
	s_waitcnt vmcnt(0)
	v_lshlrev_b32_e32 v76, 16, v74
	v_and_b32_e32 v77, 0xffff0000, v74
	v_lshlrev_b32_e32 v74, 16, v75
	v_and_b32_e32 v75, 0xffff0000, v75
	v_pk_fma_f32 v[70:71], v[76:77], s[74:75], v[70:71] op_sel_hi:[1,0,1]
	v_pk_fma_f32 v[72:73], v[74:75], s[74:75], v[72:73] op_sel_hi:[1,0,1]
	global_store_dwordx4 v[100:101], v[70:73], off offset:384
	global_load_dwordx2 v[70:71], v[106:107], off offset:224
	s_waitcnt vmcnt(0)
;   __device__ __forceinline__ u16* XB() const { return (u16*)(ws + O_XB); }
; DI float bflo(u32 v) { return __uint_as_float(v << 16); }
; DI float bfhi(u32 v) { return __uint_as_float(v & 0xffff0000u); }
; #define EPI_LOOP(MT_, NT_)                                                \
;   const int l_ = ltid() & 63, w_ = ltid() >> 6;                           \
;   const int wm_ = w_ >> 1, wn_ = w_ & 1, fr_ = l_ & 15, fq_ = l_ >> 4;    \
;   _Pragma("unroll") for (int mi = 0; mi < MT_; ++mi)                      \
;   _Pragma("unroll") for (int ni = 0; ni < NT_; ++ni)
; DI void phase_resgemm(const Params& p, const u16* A, int lda, const u16* W, int ldw, int K, char* smem) {
;     ...
;     EPI_LOOP(4, 8) {
;       const int row = r0 + wm_ * 64 + mi * 16 + fr_, col = c0 + wn_ * 128 + ni * 16 + fq_ * 4;
;       const uint2 xb = *(const uint2*)(p.XB() + (size_t)row * LDX + col);
;       float4 o;
;       o.x = DN_ALPHA * bflo(xb.x) + acc[mi][ni][0]; o.y = DN_ALPHA * bfhi(xb.x) + acc[mi][ni][1];
;       o.z = DN_ALPHA * bflo(xb.y) + acc[mi][ni][2]; o.w = DN_ALPHA * bfhi(xb.y) + acc[mi][ni][3];
;       *(float4*)(p.out + (size_t)row * 1024 + col) = o;
;     }
	v_lshlrev_b32_e32 v76, 16, v70
	v_or_b32_e32 v72, 32, v114
	v_and_b32_e32 v77, 0xffff0000, v70
	v_lshlrev_b32_e32 v70, 16, v71
	v_and_b32_e32 v71, 0xffff0000, v71
	v_mad_i64_i32 v[74:75], s[0:1], v72, s59, v[118:119]
	v_pk_fma_f32 v[66:67], v[76:77], s[74:75], v[66:67] op_sel_hi:[1,0,1]
	v_pk_fma_f32 v[68:69], v[70:71], s[74:75], v[68:69] op_sel_hi:[1,0,1]
	v_lshl_add_u64 v[74:75], v[74:75], 0, v[0:1]
	global_store_dwordx4 v[100:101], v[66:69], off offset:448
	global_load_dwordx2 v[66:67], v[74:75], off
	v_ashrrev_i32_e32 v73, 31, v72
	v_lshlrev_b64 v[68:69], 12, v[72:73]
	v_lshl_add_u64 v[68:69], s[86:87], 0, v[68:69]
	v_lshl_add_u64 v[68:69], v[68:69], 0, v[116:117]
	s_waitcnt vmcnt(0)
	v_lshlrev_b32_e32 v70, 16, v66
	v_and_b32_e32 v71, 0xffff0000, v66
	v_lshlrev_b32_e32 v66, 16, v67
	v_and_b32_e32 v67, 0xffff0000, v67
	v_pk_fma_f32 v[62:63], v[70:71], s[74:75], v[62:63] op_sel_hi:[1,0,1]
	v_pk_fma_f32 v[64:65], v[66:67], s[74:75], v[64:65] op_sel_hi:[1,0,1]
	global_store_dwordx4 v[68:69], v[62:65], off
	global_load_dwordx2 v[62:63], v[74:75], off offset:32
	s_waitcnt vmcnt(0)
	v_lshlrev_b32_e32 v64, 16, v62
	v_and_b32_e32 v65, 0xffff0000, v62
	v_lshlrev_b32_e32 v62, 16, v63
	v_and_b32_e32 v63, 0xffff0000, v63
	v_pk_fma_f32 v[58:59], v[64:65], s[74:75], v[58:59] op_sel_hi:[1,0,1]
	v_pk_fma_f32 v[60:61], v[62:63], s[74:75], v[60:61] op_sel_hi:[1,0,1]
	global_store_dwordx4 v[68:69], v[58:61], off offset:64
	global_load_dwordx2 v[58:59], v[74:75], off offset:64
	s_waitcnt vmcnt(0)
	v_lshlrev_b32_e32 v60, 16, v58
	v_and_b32_e32 v61, 0xffff0000, v58
	v_lshlrev_b32_e32 v58, 16, v59
	v_and_b32_e32 v59, 0xffff0000, v59
	v_pk_fma_f32 v[54:55], v[60:61], s[74:75], v[54:55] op_sel_hi:[1,0,1]
	v_pk_fma_f32 v[56:57], v[58:59], s[74:75], v[56:57] op_sel_hi:[1,0,1]
	global_store_dwordx4 v[68:69], v[54:57], off offset:128
	global_load_dwordx2 v[54:55], v[74:75], off offset:96
	s_waitcnt vmcnt(0)
	v_lshlrev_b32_e32 v56, 16, v54
	v_and_b32_e32 v57, 0xffff0000, v54
	v_lshlrev_b32_e32 v54, 16, v55
	v_and_b32_e32 v55, 0xffff0000, v55
	v_pk_fma_f32 v[50:51], v[56:57], s[74:75], v[50:51] op_sel_hi:[1,0,1]
	v_pk_fma_f32 v[52:53], v[54:55], s[74:75], v[52:53] op_sel_hi:[1,0,1]
	global_store_dwordx4 v[68:69], v[50:53], off offset:192
	global_load_dwordx2 v[50:51], v[74:75], off offset:128
	s_waitcnt vmcnt(0)
	v_lshlrev_b32_e32 v52, 16, v50
	v_and_b32_e32 v53, 0xffff0000, v50
	v_lshlrev_b32_e32 v50, 16, v51
	v_and_b32_e32 v51, 0xffff0000, v51
	v_pk_fma_f32 v[46:47], v[52:53], s[74:75], v[46:47] op_sel_hi:[1,0,1]
	v_pk_fma_f32 v[48:49], v[50:51], s[74:75], v[48:49] op_sel_hi:[1,0,1]
	global_store_dwordx4 v[68:69], v[46:49], off offset:256
	global_load_dwordx2 v[46:47], v[74:75], off offset:160
	s_waitcnt vmcnt(0)
	v_lshlrev_b32_e32 v48, 16, v46
	v_and_b32_e32 v49, 0xffff0000, v46
	v_lshlrev_b32_e32 v46, 16, v47
	v_and_b32_e32 v47, 0xffff0000, v47
	v_pk_fma_f32 v[42:43], v[48:49], s[74:75], v[42:43] op_sel_hi:[1,0,1]
	v_pk_fma_f32 v[44:45], v[46:47], s[74:75], v[44:45] op_sel_hi:[1,0,1]
	global_store_dwordx4 v[68:69], v[42:45], off offset:320
	global_load_dwordx2 v[42:43], v[74:75], off offset:192
	s_waitcnt vmcnt(0)
	v_lshlrev_b32_e32 v44, 16, v42
	v_and_b32_e32 v45, 0xffff0000, v42
	v_lshlrev_b32_e32 v42, 16, v43
	v_and_b32_e32 v43, 0xffff0000, v43
	v_pk_fma_f32 v[38:39], v[44:45], s[74:75], v[38:39] op_sel_hi:[1,0,1]
	v_pk_fma_f32 v[40:41], v[42:43], s[74:75], v[40:41] op_sel_hi:[1,0,1]
	global_store_dwordx4 v[68:69], v[38:41], off offset:384
	global_load_dwordx2 v[38:39], v[74:75], off offset:224
	s_waitcnt vmcnt(0)
;   __device__ __forceinline__ u16* XB() const { return (u16*)(ws + O_XB); }
; DI float bflo(u32 v) { return __uint_as_float(v << 16); }
; DI float bfhi(u32 v) { return __uint_as_float(v & 0xffff0000u); }
; #define EPI_LOOP(MT_, NT_)                                                \
;   const int l_ = ltid() & 63, w_ = ltid() >> 6;                           \
;   const int wm_ = w_ >> 1, wn_ = w_ & 1, fr_ = l_ & 15, fq_ = l_ >> 4;    \
;   _Pragma("unroll") for (int mi = 0; mi < MT_; ++mi)                      \
;   _Pragma("unroll") for (int ni = 0; ni < NT_; ++ni)
; DI void phase_resgemm(const Params& p, const u16* A, int lda, const u16* W, int ldw, int K, char* smem) {
;     ...
;     EPI_LOOP(4, 8) {
;       const int row = r0 + wm_ * 64 + mi * 16 + fr_, col = c0 + wn_ * 128 + ni * 16 + fq_ * 4;
;       const uint2 xb = *(const uint2*)(p.XB() + (size_t)row * LDX + col);
;       float4 o;
;       o.x = DN_ALPHA * bflo(xb.x) + acc[mi][ni][0]; o.y = DN_ALPHA * bfhi(xb.x) + acc[mi][ni][1];
;       o.z = DN_ALPHA * bflo(xb.y) + acc[mi][ni][2]; o.w = DN_ALPHA * bfhi(xb.y) + acc[mi][ni][3];
;       *(float4*)(p.out + (size_t)row * 1024 + col) = o;
;     }
	v_lshlrev_b32_e32 v44, 16, v38
	v_or_b32_e32 v40, 48, v114
	v_and_b32_e32 v45, 0xffff0000, v38
	v_lshlrev_b32_e32 v38, 16, v39
	v_and_b32_e32 v39, 0xffff0000, v39
	v_mad_i64_i32 v[42:43], s[0:1], v40, s59, v[118:119]
	v_pk_fma_f32 v[34:35], v[44:45], s[74:75], v[34:35] op_sel_hi:[1,0,1]
	v_pk_fma_f32 v[36:37], v[38:39], s[74:75], v[36:37] op_sel_hi:[1,0,1]
	v_lshl_add_u64 v[42:43], v[42:43], 0, v[0:1]
	global_store_dwordx4 v[68:69], v[34:37], off offset:448
	global_load_dwordx2 v[34:35], v[42:43], off
	v_ashrrev_i32_e32 v41, 31, v40
	v_lshlrev_b64 v[36:37], 12, v[40:41]
	v_lshl_add_u64 v[36:37], s[86:87], 0, v[36:37]
	v_lshl_add_u64 v[36:37], v[36:37], 0, v[116:117]
	s_mov_b64 s[0:1], 0
	s_waitcnt vmcnt(0)
	v_lshlrev_b32_e32 v38, 16, v34
	v_and_b32_e32 v39, 0xffff0000, v34
	v_lshlrev_b32_e32 v34, 16, v35
	v_and_b32_e32 v35, 0xffff0000, v35
	v_pk_fma_f32 v[30:31], v[38:39], s[74:75], v[30:31] op_sel_hi:[1,0,1]
	v_pk_fma_f32 v[32:33], v[34:35], s[74:75], v[32:33] op_sel_hi:[1,0,1]
	global_store_dwordx4 v[36:37], v[30:33], off
	global_load_dwordx2 v[30:31], v[42:43], off offset:32
	s_waitcnt vmcnt(0)
	v_lshlrev_b32_e32 v32, 16, v30
	v_and_b32_e32 v33, 0xffff0000, v30
	v_lshlrev_b32_e32 v30, 16, v31
	v_and_b32_e32 v31, 0xffff0000, v31
	v_pk_fma_f32 v[26:27], v[32:33], s[74:75], v[26:27] op_sel_hi:[1,0,1]
	v_pk_fma_f32 v[28:29], v[30:31], s[74:75], v[28:29] op_sel_hi:[1,0,1]
	global_store_dwordx4 v[36:37], v[26:29], off offset:64
	global_load_dwordx2 v[26:27], v[42:43], off offset:64
	s_waitcnt vmcnt(0)
	v_lshlrev_b32_e32 v28, 16, v26
	v_and_b32_e32 v29, 0xffff0000, v26
	v_lshlrev_b32_e32 v26, 16, v27
	v_and_b32_e32 v27, 0xffff0000, v27
	v_pk_fma_f32 v[22:23], v[28:29], s[74:75], v[22:23] op_sel_hi:[1,0,1]
	v_pk_fma_f32 v[24:25], v[26:27], s[74:75], v[24:25] op_sel_hi:[1,0,1]
	global_store_dwordx4 v[36:37], v[22:25], off offset:128
	global_load_dwordx2 v[22:23], v[42:43], off offset:96
	s_waitcnt vmcnt(0)
	v_lshlrev_b32_e32 v24, 16, v22
	v_and_b32_e32 v25, 0xffff0000, v22
	v_lshlrev_b32_e32 v22, 16, v23
	v_and_b32_e32 v23, 0xffff0000, v23
	v_pk_fma_f32 v[18:19], v[24:25], s[74:75], v[18:19] op_sel_hi:[1,0,1]
	v_pk_fma_f32 v[20:21], v[22:23], s[74:75], v[20:21] op_sel_hi:[1,0,1]
	global_store_dwordx4 v[36:37], v[18:21], off offset:192
	global_load_dwordx2 v[18:19], v[42:43], off offset:128
	s_waitcnt vmcnt(0)
	v_lshlrev_b32_e32 v20, 16, v18
	v_and_b32_e32 v21, 0xffff0000, v18
	v_lshlrev_b32_e32 v18, 16, v19
	v_and_b32_e32 v19, 0xffff0000, v19
	v_pk_fma_f32 v[14:15], v[20:21], s[74:75], v[14:15] op_sel_hi:[1,0,1]
	v_pk_fma_f32 v[16:17], v[18:19], s[74:75], v[16:17] op_sel_hi:[1,0,1]
	global_store_dwordx4 v[36:37], v[14:17], off offset:256
	global_load_dwordx2 v[14:15], v[42:43], off offset:160
	s_waitcnt vmcnt(0)
	v_lshlrev_b32_e32 v16, 16, v14
	v_and_b32_e32 v17, 0xffff0000, v14
	v_lshlrev_b32_e32 v14, 16, v15
	v_and_b32_e32 v15, 0xffff0000, v15
	v_pk_fma_f32 v[10:11], v[16:17], s[74:75], v[10:11] op_sel_hi:[1,0,1]
	v_pk_fma_f32 v[12:13], v[14:15], s[74:75], v[12:13] op_sel_hi:[1,0,1]
	global_store_dwordx4 v[36:37], v[10:13], off offset:320
	global_load_dwordx2 v[10:11], v[42:43], off offset:192
	s_waitcnt vmcnt(0)
	v_lshlrev_b32_e32 v12, 16, v10
	v_and_b32_e32 v13, 0xffff0000, v10
	v_lshlrev_b32_e32 v10, 16, v11
	v_and_b32_e32 v11, 0xffff0000, v11
	v_pk_fma_f32 v[6:7], v[12:13], s[74:75], v[6:7] op_sel_hi:[1,0,1]
	v_pk_fma_f32 v[8:9], v[10:11], s[74:75], v[8:9] op_sel_hi:[1,0,1]
	global_store_dwordx4 v[36:37], v[6:9], off offset:384
	global_load_dwordx2 v[6:7], v[42:43], off offset:224
	s_waitcnt vmcnt(0)
	v_lshlrev_b32_e32 v8, 16, v6
	v_and_b32_e32 v9, 0xffff0000, v6
	v_lshlrev_b32_e32 v6, 16, v7
	v_and_b32_e32 v7, 0xffff0000, v7
	v_pk_fma_f32 v[2:3], v[8:9], s[74:75], v[2:3] op_sel_hi:[1,0,1]
	v_pk_fma_f32 v[4:5], v[6:7], s[74:75], v[4:5] op_sel_hi:[1,0,1]
	global_store_dwordx4 v[36:37], v[2:5], off offset:448
	s_branch .LBB0_794
